# GEMM loops: MFMAs reordered so the two K-halves of each accumulator issue back to back (accumulate chain with SrcC forwarding), same accumulation order
# speedup vs baseline: 1.0350x; 1.0073x over previous
.LBB0_252:
	s_add_u32 s0, s0, 0x80
	s_addc_u32 s1, s1, 0
	s_add_u32 s47, s4, 0x100
	s_addc_u32 s48, s5, 0
	s_mov_b32 s4, 0
	s_waitcnt lgkmcnt(0)
	s_waitcnt vmcnt(0)
	s_add_i32 s49, s4, 2
	s_add_u32 s16, s0, 0x80
	s_addc_u32 s5, s1, 0
	s_add_i32 s65, 0, 0x10000
	ds_read_b128 v[148:151], v248
	ds_read_b128 v[152:155], v248 offset:1024
	ds_read_b128 v[156:159], v248 offset:2048
	ds_read_b128 v[160:163], v248 offset:3072
	s_cmp_eq_u32 s41, s4
	s_cselect_b32 s4, s10, s16
	s_cselect_b32 s5, s11, s5
	s_cselect_b32 s17, s13, s48
	s_cselect_b32 s16, s12, s47
	s_add_i32 m0, s26, 0xc000
	ds_read_b128 v[164:167], v146
	ds_read_b128 v[168:171], v146 offset:1024
	ds_read_b128 v[172:175], v146 offset:2048
	ds_read_b128 v[176:179], v146 offset:3072
	ds_read_b128 v[180:183], v146 offset:4096
	ds_read_b128 v[204:207], v146 offset:5120
	ds_read_b128 v[208:211], v146 offset:6144
	ds_read_b128 v[212:215], v146 offset:7168
	global_load_lds_dwordx4 v138, s[0:1]
	s_add_i32 m0, s26, 0xe000
	s_nop 0
	global_load_lds_dwordx4 v140, s[0:1]
	s_waitcnt lgkmcnt(8)
	s_barrier
	s_waitcnt lgkmcnt(0)
	v_mfma_f32_16x16x32_bf16 v[126:129], v[148:151], v[164:167], 0
	v_mfma_f32_16x16x32_bf16 v[126:129], v[152:155], v[168:171], v[126:129]
	v_mfma_f32_16x16x32_bf16 v[122:125], v[156:159], v[164:167], 0
	v_mfma_f32_16x16x32_bf16 v[122:125], v[160:163], v[168:171], v[122:125]
	v_mfma_f32_16x16x32_bf16 v[110:113], v[148:151], v[172:175], 0
	v_mfma_f32_16x16x32_bf16 v[110:113], v[152:155], v[176:179], v[110:113]
	v_mfma_f32_16x16x32_bf16 v[106:109], v[156:159], v[172:175], 0
	v_mfma_f32_16x16x32_bf16 v[106:109], v[160:163], v[176:179], v[106:109]
	v_mfma_f32_16x16x32_bf16 v[94:97], v[148:151], v[180:183], 0
	v_mfma_f32_16x16x32_bf16 v[94:97], v[152:155], v[204:207], v[94:97]
	v_mfma_f32_16x16x32_bf16 v[90:93], v[156:159], v[180:183], 0
	v_mfma_f32_16x16x32_bf16 v[90:93], v[160:163], v[204:207], v[90:93]
	v_mfma_f32_16x16x32_bf16 v[78:81], v[148:151], v[208:211], 0
	v_mfma_f32_16x16x32_bf16 v[78:81], v[152:155], v[212:215], v[78:81]
	v_mfma_f32_16x16x32_bf16 v[74:77], v[156:159], v[208:211], 0
	v_mfma_f32_16x16x32_bf16 v[74:77], v[160:163], v[212:215], v[74:77]
	s_barrier
	s_add_i32 s66, 0, 0x14000
	s_add_i32 s65, s65, s24
	ds_read_b128 v[216:219], v248 offset:16384
	ds_read_b128 v[220:223], v248 offset:17408
	ds_read_b128 v[224:227], v248 offset:18432
	ds_read_b128 v[228:231], v248 offset:19456
	s_add_u32 s70, s16, s6
	s_addc_u32 s71, s17, s7
	s_mov_b32 m0, s65
	s_nop 0
	global_load_lds_dwordx4 v132, s[16:17]
	s_add_i32 m0, s65, 0x2000
	s_nop 0
	global_load_lds_dwordx4 v136, s[16:17]
	s_barrier
	s_waitcnt lgkmcnt(0)
	v_mfma_f32_16x16x32_bf16 v[114:117], v[216:219], v[164:167], 0
	v_mfma_f32_16x16x32_bf16 v[114:117], v[220:223], v[168:171], v[114:117]
	v_mfma_f32_16x16x32_bf16 v[118:121], v[224:227], v[164:167], 0
	v_mfma_f32_16x16x32_bf16 v[118:121], v[228:231], v[168:171], v[118:121]
	v_mfma_f32_16x16x32_bf16 v[98:101], v[216:219], v[172:175], 0
	v_mfma_f32_16x16x32_bf16 v[98:101], v[220:223], v[176:179], v[98:101]
	v_mfma_f32_16x16x32_bf16 v[102:105], v[224:227], v[172:175], 0
	v_mfma_f32_16x16x32_bf16 v[102:105], v[228:231], v[176:179], v[102:105]
	v_mfma_f32_16x16x32_bf16 v[82:85], v[216:219], v[180:183], 0
	v_mfma_f32_16x16x32_bf16 v[82:85], v[220:223], v[204:207], v[82:85]
	v_mfma_f32_16x16x32_bf16 v[86:89], v[224:227], v[180:183], 0
	v_mfma_f32_16x16x32_bf16 v[86:89], v[228:231], v[204:207], v[86:89]
	v_mfma_f32_16x16x32_bf16 v[66:69], v[216:219], v[208:211], 0
	v_mfma_f32_16x16x32_bf16 v[66:69], v[220:223], v[212:215], v[66:69]
	v_mfma_f32_16x16x32_bf16 v[70:73], v[224:227], v[208:211], 0
	v_mfma_f32_16x16x32_bf16 v[70:73], v[228:231], v[212:215], v[70:73]
	s_barrier
	s_mov_b32 m0, s26
	s_add_u32 s72, s4, s6
	s_addc_u32 s73, s5, s7
	ds_read_b128 v[164:167], v146 offset:16384
	ds_read_b128 v[168:171], v146 offset:17408
	ds_read_b128 v[172:175], v146 offset:18432
	ds_read_b128 v[176:179], v146 offset:19456
	ds_read_b128 v[180:183], v146 offset:20480
	ds_read_b128 v[204:207], v146 offset:21504
	ds_read_b128 v[208:211], v146 offset:22528
	ds_read_b128 v[212:215], v146 offset:23552
	global_load_lds_dwordx4 v130, s[4:5]
	s_mov_b32 m0, s27
	s_nop 0
	global_load_lds_dwordx4 v134, s[4:5]
	s_barrier
	s_waitcnt lgkmcnt(0)
	v_mfma_f32_16x16x32_bf16 v[62:65], v[148:151], v[164:167], 0
	v_mfma_f32_16x16x32_bf16 v[62:65], v[152:155], v[168:171], v[62:65]
	v_mfma_f32_16x16x32_bf16 v[58:61], v[156:159], v[164:167], 0
	v_mfma_f32_16x16x32_bf16 v[58:61], v[160:163], v[168:171], v[58:61]
	v_mfma_f32_16x16x32_bf16 v[46:49], v[148:151], v[172:175], 0
	v_mfma_f32_16x16x32_bf16 v[46:49], v[152:155], v[176:179], v[46:49]
	v_mfma_f32_16x16x32_bf16 v[42:45], v[156:159], v[172:175], 0
	v_mfma_f32_16x16x32_bf16 v[42:45], v[160:163], v[176:179], v[42:45]
	v_mfma_f32_16x16x32_bf16 v[30:33], v[148:151], v[180:183], 0
	v_mfma_f32_16x16x32_bf16 v[30:33], v[152:155], v[204:207], v[30:33]
	v_mfma_f32_16x16x32_bf16 v[26:29], v[156:159], v[180:183], 0
	v_mfma_f32_16x16x32_bf16 v[26:29], v[160:163], v[204:207], v[26:29]
	v_mfma_f32_16x16x32_bf16 v[14:17], v[148:151], v[208:211], 0
	v_mfma_f32_16x16x32_bf16 v[14:17], v[152:155], v[212:215], v[14:17]
	v_mfma_f32_16x16x32_bf16 v[10:13], v[156:159], v[208:211], 0
	v_mfma_f32_16x16x32_bf16 v[10:13], v[160:163], v[212:215], v[10:13]
	s_barrier
	s_add_u32 s16, s16, s92
	s_addc_u32 s17, s17, 0
	s_add_i32 s65, s66, s24
	s_add_u32 s76, s16, s6
	s_addc_u32 s77, s17, s7
	s_mov_b32 m0, s65
	s_nop 0
	global_load_lds_dwordx4 v132, s[16:17]
	s_add_i32 m0, s65, 0x2000
	s_nop 0
	global_load_lds_dwordx4 v136, s[16:17]
	s_waitcnt vmcnt(6)
	s_barrier
	v_mfma_f32_16x16x32_bf16 v[50:53], v[216:219], v[164:167], 0
	v_mfma_f32_16x16x32_bf16 v[50:53], v[220:223], v[168:171], v[50:53]
	v_mfma_f32_16x16x32_bf16 v[54:57], v[224:227], v[164:167], 0
	v_mfma_f32_16x16x32_bf16 v[54:57], v[228:231], v[168:171], v[54:57]
	v_mfma_f32_16x16x32_bf16 v[34:37], v[216:219], v[172:175], 0
	v_mfma_f32_16x16x32_bf16 v[34:37], v[220:223], v[176:179], v[34:37]
	v_mfma_f32_16x16x32_bf16 v[38:41], v[224:227], v[172:175], 0
	v_mfma_f32_16x16x32_bf16 v[38:41], v[228:231], v[176:179], v[38:41]
	v_mfma_f32_16x16x32_bf16 v[18:21], v[216:219], v[180:183], 0
	v_mfma_f32_16x16x32_bf16 v[18:21], v[220:223], v[204:207], v[18:21]
	v_mfma_f32_16x16x32_bf16 v[22:25], v[224:227], v[180:183], 0
	v_mfma_f32_16x16x32_bf16 v[22:25], v[228:231], v[204:207], v[22:25]
	v_mfma_f32_16x16x32_bf16 v[6:9], v[216:219], v[208:211], 0
	v_mfma_f32_16x16x32_bf16 v[6:9], v[220:223], v[212:215], v[6:9]
	v_mfma_f32_16x16x32_bf16 v[2:5], v[224:227], v[208:211], 0
	v_mfma_f32_16x16x32_bf16 v[2:5], v[228:231], v[212:215], v[2:5]
	s_barrier
	s_add_i32 s16, 0, 0x18000
	ds_read_b128 v[148:151], v248 offset:32768
	ds_read_b128 v[152:155], v248 offset:33792
	ds_read_b128 v[156:159], v248 offset:34816
	ds_read_b128 v[160:163], v248 offset:35840
	s_add_u32 s4, s4, s92
	s_addc_u32 s5, s5, 0
	s_mov_b32 m0, s28
	ds_read_b128 v[164:167], v146 offset:32768
	ds_read_b128 v[168:171], v146 offset:33792
	ds_read_b128 v[172:175], v146 offset:34816
	ds_read_b128 v[176:179], v146 offset:35840
	ds_read_b128 v[180:183], v146 offset:36864
	ds_read_b128 v[204:207], v146 offset:37888
	ds_read_b128 v[208:211], v146 offset:38912
	ds_read_b128 v[212:215], v146 offset:39936
	global_load_lds_dwordx4 v130, s[4:5]
	s_mov_b32 m0, s29
	s_nop 0
	global_load_lds_dwordx4 v134, s[4:5]
	s_waitcnt lgkmcnt(8)
	s_barrier
	s_waitcnt lgkmcnt(0)
	v_mfma_f32_16x16x32_bf16 v[126:129], v[148:151], v[164:167], v[126:129]
	v_mfma_f32_16x16x32_bf16 v[126:129], v[152:155], v[168:171], v[126:129]
	v_mfma_f32_16x16x32_bf16 v[122:125], v[156:159], v[164:167], v[122:125]
	v_mfma_f32_16x16x32_bf16 v[122:125], v[160:163], v[168:171], v[122:125]
	v_mfma_f32_16x16x32_bf16 v[110:113], v[148:151], v[172:175], v[110:113]
	v_mfma_f32_16x16x32_bf16 v[110:113], v[152:155], v[176:179], v[110:113]
	v_mfma_f32_16x16x32_bf16 v[106:109], v[156:159], v[172:175], v[106:109]
	v_mfma_f32_16x16x32_bf16 v[106:109], v[160:163], v[176:179], v[106:109]
	v_mfma_f32_16x16x32_bf16 v[94:97], v[148:151], v[180:183], v[94:97]
	v_mfma_f32_16x16x32_bf16 v[94:97], v[152:155], v[204:207], v[94:97]
	v_mfma_f32_16x16x32_bf16 v[90:93], v[156:159], v[180:183], v[90:93]
	v_mfma_f32_16x16x32_bf16 v[90:93], v[160:163], v[204:207], v[90:93]
	v_mfma_f32_16x16x32_bf16 v[78:81], v[148:151], v[208:211], v[78:81]
	v_mfma_f32_16x16x32_bf16 v[78:81], v[152:155], v[212:215], v[78:81]
	v_mfma_f32_16x16x32_bf16 v[74:77], v[156:159], v[208:211], v[74:77]
	v_mfma_f32_16x16x32_bf16 v[74:77], v[160:163], v[212:215], v[74:77]
	s_barrier
	s_add_i32 s4, 0, 0x1c000
	s_add_i32 s5, s16, s24
	s_mov_b32 m0, s5
	ds_read_b128 v[216:219], v248 offset:49152
	ds_read_b128 v[220:223], v248 offset:50176
	ds_read_b128 v[224:227], v248 offset:51200
	ds_read_b128 v[228:231], v248 offset:52224
	global_load_lds_dwordx4 v132, s[70:71]
	s_add_i32 m0, s5, 0x2000
	s_nop 0
	global_load_lds_dwordx4 v136, s[70:71]
	s_barrier
	s_waitcnt lgkmcnt(0)
	v_mfma_f32_16x16x32_bf16 v[114:117], v[216:219], v[164:167], v[114:117]
	v_mfma_f32_16x16x32_bf16 v[114:117], v[220:223], v[168:171], v[114:117]
	v_mfma_f32_16x16x32_bf16 v[118:121], v[224:227], v[164:167], v[118:121]
	v_mfma_f32_16x16x32_bf16 v[118:121], v[228:231], v[168:171], v[118:121]
	v_mfma_f32_16x16x32_bf16 v[98:101], v[216:219], v[172:175], v[98:101]
	v_mfma_f32_16x16x32_bf16 v[98:101], v[220:223], v[176:179], v[98:101]
	v_mfma_f32_16x16x32_bf16 v[102:105], v[224:227], v[172:175], v[102:105]
	v_mfma_f32_16x16x32_bf16 v[102:105], v[228:231], v[176:179], v[102:105]
	v_mfma_f32_16x16x32_bf16 v[82:85], v[216:219], v[180:183], v[82:85]
	v_mfma_f32_16x16x32_bf16 v[82:85], v[220:223], v[204:207], v[82:85]
	v_mfma_f32_16x16x32_bf16 v[86:89], v[224:227], v[180:183], v[86:89]
	v_mfma_f32_16x16x32_bf16 v[86:89], v[228:231], v[204:207], v[86:89]
	v_mfma_f32_16x16x32_bf16 v[66:69], v[216:219], v[208:211], v[66:69]
	v_mfma_f32_16x16x32_bf16 v[66:69], v[220:223], v[212:215], v[66:69]
	v_mfma_f32_16x16x32_bf16 v[70:73], v[224:227], v[208:211], v[70:73]
	v_mfma_f32_16x16x32_bf16 v[70:73], v[228:231], v[212:215], v[70:73]
	s_barrier
	s_mov_b32 m0, s35
	ds_read_b128 v[164:167], v146 offset:49152
	ds_read_b128 v[168:171], v146 offset:50176
	ds_read_b128 v[172:175], v146 offset:51200
	ds_read_b128 v[176:179], v146 offset:52224
	ds_read_b128 v[180:183], v146 offset:53248
	ds_read_b128 v[204:207], v146 offset:54272
	ds_read_b128 v[208:211], v146 offset:55296
	ds_read_b128 v[212:215], v146 offset:56320
	global_load_lds_dwordx4 v130, s[72:73]
	s_mov_b32 m0, s40
	s_nop 0
	global_load_lds_dwordx4 v134, s[72:73]
	s_barrier
	s_waitcnt lgkmcnt(0)
	v_mfma_f32_16x16x32_bf16 v[62:65], v[148:151], v[164:167], v[62:65]
	v_mfma_f32_16x16x32_bf16 v[62:65], v[152:155], v[168:171], v[62:65]
	v_mfma_f32_16x16x32_bf16 v[58:61], v[156:159], v[164:167], v[58:61]
	v_mfma_f32_16x16x32_bf16 v[58:61], v[160:163], v[168:171], v[58:61]
	v_mfma_f32_16x16x32_bf16 v[46:49], v[148:151], v[172:175], v[46:49]
	v_mfma_f32_16x16x32_bf16 v[46:49], v[152:155], v[176:179], v[46:49]
	v_mfma_f32_16x16x32_bf16 v[42:45], v[156:159], v[172:175], v[42:45]
	v_mfma_f32_16x16x32_bf16 v[42:45], v[160:163], v[176:179], v[42:45]
	v_mfma_f32_16x16x32_bf16 v[30:33], v[148:151], v[180:183], v[30:33]
	v_mfma_f32_16x16x32_bf16 v[30:33], v[152:155], v[204:207], v[30:33]
	v_mfma_f32_16x16x32_bf16 v[26:29], v[156:159], v[180:183], v[26:29]
	v_mfma_f32_16x16x32_bf16 v[26:29], v[160:163], v[204:207], v[26:29]
	v_mfma_f32_16x16x32_bf16 v[14:17], v[148:151], v[208:211], v[14:17]
	v_mfma_f32_16x16x32_bf16 v[14:17], v[152:155], v[212:215], v[14:17]
	v_mfma_f32_16x16x32_bf16 v[10:13], v[156:159], v[208:211], v[10:13]
	v_mfma_f32_16x16x32_bf16 v[10:13], v[160:163], v[212:215], v[10:13]
	s_barrier
	s_add_i32 s4, s4, s24
	s_mov_b32 m0, s4
	s_nop 0
	global_load_lds_dwordx4 v132, s[76:77]
	s_add_i32 m0, s4, 0x2000
	s_nop 0
	global_load_lds_dwordx4 v136, s[76:77]
	s_add_u32 s0, s0, 0x100
	s_addc_u32 s1, s1, 0
	s_add_u32 s47, s47, 0x100
	s_addc_u32 s48, s48, 0
	s_cmp_ge_u32 s49, s30
	s_mov_b32 s4, s49
	s_waitcnt vmcnt(6)
	s_barrier
	v_mfma_f32_16x16x32_bf16 v[50:53], v[216:219], v[164:167], v[50:53]
	v_mfma_f32_16x16x32_bf16 v[50:53], v[220:223], v[168:171], v[50:53]
	v_mfma_f32_16x16x32_bf16 v[54:57], v[224:227], v[164:167], v[54:57]
	v_mfma_f32_16x16x32_bf16 v[54:57], v[228:231], v[168:171], v[54:57]
	v_mfma_f32_16x16x32_bf16 v[34:37], v[216:219], v[172:175], v[34:37]
	v_mfma_f32_16x16x32_bf16 v[34:37], v[220:223], v[176:179], v[34:37]
	v_mfma_f32_16x16x32_bf16 v[38:41], v[224:227], v[172:175], v[38:41]
	v_mfma_f32_16x16x32_bf16 v[38:41], v[228:231], v[176:179], v[38:41]
	v_mfma_f32_16x16x32_bf16 v[18:21], v[216:219], v[180:183], v[18:21]
	v_mfma_f32_16x16x32_bf16 v[18:21], v[220:223], v[204:207], v[18:21]
	v_mfma_f32_16x16x32_bf16 v[22:25], v[224:227], v[180:183], v[22:25]
	v_mfma_f32_16x16x32_bf16 v[22:25], v[228:231], v[204:207], v[22:25]
	v_mfma_f32_16x16x32_bf16 v[6:9], v[216:219], v[208:211], v[6:9]
	v_mfma_f32_16x16x32_bf16 v[6:9], v[220:223], v[212:215], v[6:9]
	v_mfma_f32_16x16x32_bf16 v[2:5], v[224:227], v[208:211], v[2:5]
	v_mfma_f32_16x16x32_bf16 v[2:5], v[228:231], v[212:215], v[2:5]
	s_barrier
	s_cbranch_scc1 .Lkexit_253
.LBB0_253:
	s_add_i32 s49, s4, 2
	s_add_u32 s16, s0, 0x80
	s_addc_u32 s5, s1, 0
	s_add_i32 s65, 0, 0x10000
	ds_read_b128 v[148:151], v248
	ds_read_b128 v[152:155], v248 offset:1024
	ds_read_b128 v[156:159], v248 offset:2048
	ds_read_b128 v[160:163], v248 offset:3072
	s_cmp_eq_u32 s41, s4
	s_cselect_b32 s4, s10, s16
	s_cselect_b32 s5, s11, s5
	s_cselect_b32 s17, s13, s48
	s_cselect_b32 s16, s12, s47
	s_add_i32 m0, s26, 0xc000
	ds_read_b128 v[164:167], v146
	ds_read_b128 v[168:171], v146 offset:1024
	ds_read_b128 v[172:175], v146 offset:2048
	ds_read_b128 v[176:179], v146 offset:3072
	ds_read_b128 v[180:183], v146 offset:4096
	ds_read_b128 v[204:207], v146 offset:5120
	ds_read_b128 v[208:211], v146 offset:6144
	ds_read_b128 v[212:215], v146 offset:7168
	global_load_lds_dwordx4 v138, s[0:1]
	s_add_i32 m0, s26, 0xe000
	s_nop 0
	global_load_lds_dwordx4 v140, s[0:1]
	s_waitcnt lgkmcnt(8)
	s_barrier
	s_waitcnt lgkmcnt(0)
	v_mfma_f32_16x16x32_bf16 v[126:129], v[148:151], v[164:167], v[126:129]
	v_mfma_f32_16x16x32_bf16 v[126:129], v[152:155], v[168:171], v[126:129]
	v_mfma_f32_16x16x32_bf16 v[122:125], v[156:159], v[164:167], v[122:125]
	v_mfma_f32_16x16x32_bf16 v[122:125], v[160:163], v[168:171], v[122:125]
	v_mfma_f32_16x16x32_bf16 v[110:113], v[148:151], v[172:175], v[110:113]
	v_mfma_f32_16x16x32_bf16 v[110:113], v[152:155], v[176:179], v[110:113]
	v_mfma_f32_16x16x32_bf16 v[106:109], v[156:159], v[172:175], v[106:109]
	v_mfma_f32_16x16x32_bf16 v[106:109], v[160:163], v[176:179], v[106:109]
	v_mfma_f32_16x16x32_bf16 v[94:97], v[148:151], v[180:183], v[94:97]
	v_mfma_f32_16x16x32_bf16 v[94:97], v[152:155], v[204:207], v[94:97]
	v_mfma_f32_16x16x32_bf16 v[90:93], v[156:159], v[180:183], v[90:93]
	v_mfma_f32_16x16x32_bf16 v[90:93], v[160:163], v[204:207], v[90:93]
	v_mfma_f32_16x16x32_bf16 v[78:81], v[148:151], v[208:211], v[78:81]
	v_mfma_f32_16x16x32_bf16 v[78:81], v[152:155], v[212:215], v[78:81]
	v_mfma_f32_16x16x32_bf16 v[74:77], v[156:159], v[208:211], v[74:77]
	v_mfma_f32_16x16x32_bf16 v[74:77], v[160:163], v[212:215], v[74:77]
	s_barrier
	s_add_i32 s66, 0, 0x14000
	s_add_i32 s65, s65, s24
	ds_read_b128 v[216:219], v248 offset:16384
	ds_read_b128 v[220:223], v248 offset:17408
	ds_read_b128 v[224:227], v248 offset:18432
	ds_read_b128 v[228:231], v248 offset:19456
	s_add_u32 s70, s16, s6
	s_addc_u32 s71, s17, s7
	s_mov_b32 m0, s65
	s_nop 0
	global_load_lds_dwordx4 v132, s[16:17]
	s_add_i32 m0, s65, 0x2000
	s_nop 0
	global_load_lds_dwordx4 v136, s[16:17]
	s_barrier
	s_waitcnt lgkmcnt(0)
	v_mfma_f32_16x16x32_bf16 v[114:117], v[216:219], v[164:167], v[114:117]
	v_mfma_f32_16x16x32_bf16 v[114:117], v[220:223], v[168:171], v[114:117]
	v_mfma_f32_16x16x32_bf16 v[118:121], v[224:227], v[164:167], v[118:121]
	v_mfma_f32_16x16x32_bf16 v[118:121], v[228:231], v[168:171], v[118:121]
	v_mfma_f32_16x16x32_bf16 v[98:101], v[216:219], v[172:175], v[98:101]
	v_mfma_f32_16x16x32_bf16 v[98:101], v[220:223], v[176:179], v[98:101]
	v_mfma_f32_16x16x32_bf16 v[102:105], v[224:227], v[172:175], v[102:105]
	v_mfma_f32_16x16x32_bf16 v[102:105], v[228:231], v[176:179], v[102:105]
	v_mfma_f32_16x16x32_bf16 v[82:85], v[216:219], v[180:183], v[82:85]
	v_mfma_f32_16x16x32_bf16 v[82:85], v[220:223], v[204:207], v[82:85]
	v_mfma_f32_16x16x32_bf16 v[86:89], v[224:227], v[180:183], v[86:89]
	v_mfma_f32_16x16x32_bf16 v[86:89], v[228:231], v[204:207], v[86:89]
	v_mfma_f32_16x16x32_bf16 v[66:69], v[216:219], v[208:211], v[66:69]
	v_mfma_f32_16x16x32_bf16 v[66:69], v[220:223], v[212:215], v[66:69]
	v_mfma_f32_16x16x32_bf16 v[70:73], v[224:227], v[208:211], v[70:73]
	v_mfma_f32_16x16x32_bf16 v[70:73], v[228:231], v[212:215], v[70:73]
	s_barrier
	s_mov_b32 m0, s26
	s_add_u32 s72, s4, s6
	s_addc_u32 s73, s5, s7
	ds_read_b128 v[164:167], v146 offset:16384
	ds_read_b128 v[168:171], v146 offset:17408
	ds_read_b128 v[172:175], v146 offset:18432
	ds_read_b128 v[176:179], v146 offset:19456
	ds_read_b128 v[180:183], v146 offset:20480
	ds_read_b128 v[204:207], v146 offset:21504
	ds_read_b128 v[208:211], v146 offset:22528
	ds_read_b128 v[212:215], v146 offset:23552
	global_load_lds_dwordx4 v130, s[4:5]
	s_mov_b32 m0, s27
	s_nop 0
	global_load_lds_dwordx4 v134, s[4:5]
	s_barrier
	s_waitcnt lgkmcnt(0)
	v_mfma_f32_16x16x32_bf16 v[62:65], v[148:151], v[164:167], v[62:65]
	v_mfma_f32_16x16x32_bf16 v[62:65], v[152:155], v[168:171], v[62:65]
	v_mfma_f32_16x16x32_bf16 v[58:61], v[156:159], v[164:167], v[58:61]
	v_mfma_f32_16x16x32_bf16 v[58:61], v[160:163], v[168:171], v[58:61]
	v_mfma_f32_16x16x32_bf16 v[46:49], v[148:151], v[172:175], v[46:49]
	v_mfma_f32_16x16x32_bf16 v[46:49], v[152:155], v[176:179], v[46:49]
	v_mfma_f32_16x16x32_bf16 v[42:45], v[156:159], v[172:175], v[42:45]
	v_mfma_f32_16x16x32_bf16 v[42:45], v[160:163], v[176:179], v[42:45]
	v_mfma_f32_16x16x32_bf16 v[30:33], v[148:151], v[180:183], v[30:33]
	v_mfma_f32_16x16x32_bf16 v[30:33], v[152:155], v[204:207], v[30:33]
	v_mfma_f32_16x16x32_bf16 v[26:29], v[156:159], v[180:183], v[26:29]
	v_mfma_f32_16x16x32_bf16 v[26:29], v[160:163], v[204:207], v[26:29]
	v_mfma_f32_16x16x32_bf16 v[14:17], v[148:151], v[208:211], v[14:17]
	v_mfma_f32_16x16x32_bf16 v[14:17], v[152:155], v[212:215], v[14:17]
	v_mfma_f32_16x16x32_bf16 v[10:13], v[156:159], v[208:211], v[10:13]
	v_mfma_f32_16x16x32_bf16 v[10:13], v[160:163], v[212:215], v[10:13]
	s_barrier
	s_add_u32 s16, s16, s92
	s_addc_u32 s17, s17, 0
	s_add_i32 s65, s66, s24
	s_add_u32 s76, s16, s6
	s_addc_u32 s77, s17, s7
	s_mov_b32 m0, s65
	s_nop 0
	global_load_lds_dwordx4 v132, s[16:17]
	s_add_i32 m0, s65, 0x2000
	s_nop 0
	global_load_lds_dwordx4 v136, s[16:17]
	s_waitcnt vmcnt(6)
	s_barrier
	v_mfma_f32_16x16x32_bf16 v[50:53], v[216:219], v[164:167], v[50:53]
	v_mfma_f32_16x16x32_bf16 v[50:53], v[220:223], v[168:171], v[50:53]
	v_mfma_f32_16x16x32_bf16 v[54:57], v[224:227], v[164:167], v[54:57]
	v_mfma_f32_16x16x32_bf16 v[54:57], v[228:231], v[168:171], v[54:57]
	v_mfma_f32_16x16x32_bf16 v[34:37], v[216:219], v[172:175], v[34:37]
	v_mfma_f32_16x16x32_bf16 v[34:37], v[220:223], v[176:179], v[34:37]
	v_mfma_f32_16x16x32_bf16 v[38:41], v[224:227], v[172:175], v[38:41]
	v_mfma_f32_16x16x32_bf16 v[38:41], v[228:231], v[176:179], v[38:41]
	v_mfma_f32_16x16x32_bf16 v[18:21], v[216:219], v[180:183], v[18:21]
	v_mfma_f32_16x16x32_bf16 v[18:21], v[220:223], v[204:207], v[18:21]
	v_mfma_f32_16x16x32_bf16 v[22:25], v[224:227], v[180:183], v[22:25]
	v_mfma_f32_16x16x32_bf16 v[22:25], v[228:231], v[204:207], v[22:25]
	v_mfma_f32_16x16x32_bf16 v[6:9], v[216:219], v[208:211], v[6:9]
	v_mfma_f32_16x16x32_bf16 v[6:9], v[220:223], v[212:215], v[6:9]
	v_mfma_f32_16x16x32_bf16 v[2:5], v[224:227], v[208:211], v[2:5]
	v_mfma_f32_16x16x32_bf16 v[2:5], v[228:231], v[212:215], v[2:5]
	s_barrier
	s_add_i32 s16, 0, 0x18000
	ds_read_b128 v[148:151], v248 offset:32768
	ds_read_b128 v[152:155], v248 offset:33792
	ds_read_b128 v[156:159], v248 offset:34816
	ds_read_b128 v[160:163], v248 offset:35840
	s_add_u32 s4, s4, s92
	s_addc_u32 s5, s5, 0
	s_mov_b32 m0, s28
	ds_read_b128 v[164:167], v146 offset:32768
	ds_read_b128 v[168:171], v146 offset:33792
	ds_read_b128 v[172:175], v146 offset:34816
	ds_read_b128 v[176:179], v146 offset:35840
	ds_read_b128 v[180:183], v146 offset:36864
	ds_read_b128 v[204:207], v146 offset:37888
	ds_read_b128 v[208:211], v146 offset:38912
	ds_read_b128 v[212:215], v146 offset:39936
	global_load_lds_dwordx4 v130, s[4:5]
	s_mov_b32 m0, s29
	s_nop 0
	global_load_lds_dwordx4 v134, s[4:5]
	s_waitcnt lgkmcnt(8)
	s_barrier
	s_waitcnt lgkmcnt(0)
	v_mfma_f32_16x16x32_bf16 v[126:129], v[148:151], v[164:167], v[126:129]
	v_mfma_f32_16x16x32_bf16 v[126:129], v[152:155], v[168:171], v[126:129]
	v_mfma_f32_16x16x32_bf16 v[122:125], v[156:159], v[164:167], v[122:125]
	v_mfma_f32_16x16x32_bf16 v[122:125], v[160:163], v[168:171], v[122:125]
	v_mfma_f32_16x16x32_bf16 v[110:113], v[148:151], v[172:175], v[110:113]
	v_mfma_f32_16x16x32_bf16 v[110:113], v[152:155], v[176:179], v[110:113]
	v_mfma_f32_16x16x32_bf16 v[106:109], v[156:159], v[172:175], v[106:109]
	v_mfma_f32_16x16x32_bf16 v[106:109], v[160:163], v[176:179], v[106:109]
	v_mfma_f32_16x16x32_bf16 v[94:97], v[148:151], v[180:183], v[94:97]
	v_mfma_f32_16x16x32_bf16 v[94:97], v[152:155], v[204:207], v[94:97]
	v_mfma_f32_16x16x32_bf16 v[90:93], v[156:159], v[180:183], v[90:93]
	v_mfma_f32_16x16x32_bf16 v[90:93], v[160:163], v[204:207], v[90:93]
	v_mfma_f32_16x16x32_bf16 v[78:81], v[148:151], v[208:211], v[78:81]
	v_mfma_f32_16x16x32_bf16 v[78:81], v[152:155], v[212:215], v[78:81]
	v_mfma_f32_16x16x32_bf16 v[74:77], v[156:159], v[208:211], v[74:77]
	v_mfma_f32_16x16x32_bf16 v[74:77], v[160:163], v[212:215], v[74:77]
	s_barrier
	s_add_i32 s4, 0, 0x1c000
	s_add_i32 s5, s16, s24
	s_mov_b32 m0, s5
	ds_read_b128 v[216:219], v248 offset:49152
	ds_read_b128 v[220:223], v248 offset:50176
	ds_read_b128 v[224:227], v248 offset:51200
	ds_read_b128 v[228:231], v248 offset:52224
	global_load_lds_dwordx4 v132, s[70:71]
	s_add_i32 m0, s5, 0x2000
	s_nop 0
	global_load_lds_dwordx4 v136, s[70:71]
	s_barrier
	s_waitcnt lgkmcnt(0)
	v_mfma_f32_16x16x32_bf16 v[114:117], v[216:219], v[164:167], v[114:117]
	v_mfma_f32_16x16x32_bf16 v[114:117], v[220:223], v[168:171], v[114:117]
	v_mfma_f32_16x16x32_bf16 v[118:121], v[224:227], v[164:167], v[118:121]
	v_mfma_f32_16x16x32_bf16 v[118:121], v[228:231], v[168:171], v[118:121]
	v_mfma_f32_16x16x32_bf16 v[98:101], v[216:219], v[172:175], v[98:101]
	v_mfma_f32_16x16x32_bf16 v[98:101], v[220:223], v[176:179], v[98:101]
	v_mfma_f32_16x16x32_bf16 v[102:105], v[224:227], v[172:175], v[102:105]
	v_mfma_f32_16x16x32_bf16 v[102:105], v[228:231], v[176:179], v[102:105]
	v_mfma_f32_16x16x32_bf16 v[82:85], v[216:219], v[180:183], v[82:85]
	v_mfma_f32_16x16x32_bf16 v[82:85], v[220:223], v[204:207], v[82:85]
	v_mfma_f32_16x16x32_bf16 v[86:89], v[224:227], v[180:183], v[86:89]
	v_mfma_f32_16x16x32_bf16 v[86:89], v[228:231], v[204:207], v[86:89]
	v_mfma_f32_16x16x32_bf16 v[66:69], v[216:219], v[208:211], v[66:69]
	v_mfma_f32_16x16x32_bf16 v[66:69], v[220:223], v[212:215], v[66:69]
	v_mfma_f32_16x16x32_bf16 v[70:73], v[224:227], v[208:211], v[70:73]
	v_mfma_f32_16x16x32_bf16 v[70:73], v[228:231], v[212:215], v[70:73]
	s_barrier
	s_mov_b32 m0, s35
	ds_read_b128 v[164:167], v146 offset:49152
	ds_read_b128 v[168:171], v146 offset:50176
	ds_read_b128 v[172:175], v146 offset:51200
	ds_read_b128 v[176:179], v146 offset:52224
	ds_read_b128 v[180:183], v146 offset:53248
	ds_read_b128 v[204:207], v146 offset:54272
	ds_read_b128 v[208:211], v146 offset:55296
	ds_read_b128 v[212:215], v146 offset:56320
	global_load_lds_dwordx4 v130, s[72:73]
	s_mov_b32 m0, s40
	s_nop 0
	global_load_lds_dwordx4 v134, s[72:73]
	s_barrier
	s_waitcnt lgkmcnt(0)
	v_mfma_f32_16x16x32_bf16 v[62:65], v[148:151], v[164:167], v[62:65]
	v_mfma_f32_16x16x32_bf16 v[62:65], v[152:155], v[168:171], v[62:65]
	v_mfma_f32_16x16x32_bf16 v[58:61], v[156:159], v[164:167], v[58:61]
	v_mfma_f32_16x16x32_bf16 v[58:61], v[160:163], v[168:171], v[58:61]
	v_mfma_f32_16x16x32_bf16 v[46:49], v[148:151], v[172:175], v[46:49]
	v_mfma_f32_16x16x32_bf16 v[46:49], v[152:155], v[176:179], v[46:49]
	v_mfma_f32_16x16x32_bf16 v[42:45], v[156:159], v[172:175], v[42:45]
	v_mfma_f32_16x16x32_bf16 v[42:45], v[160:163], v[176:179], v[42:45]
	v_mfma_f32_16x16x32_bf16 v[30:33], v[148:151], v[180:183], v[30:33]
	v_mfma_f32_16x16x32_bf16 v[30:33], v[152:155], v[204:207], v[30:33]
	v_mfma_f32_16x16x32_bf16 v[26:29], v[156:159], v[180:183], v[26:29]
	v_mfma_f32_16x16x32_bf16 v[26:29], v[160:163], v[204:207], v[26:29]
	v_mfma_f32_16x16x32_bf16 v[14:17], v[148:151], v[208:211], v[14:17]
	v_mfma_f32_16x16x32_bf16 v[14:17], v[152:155], v[212:215], v[14:17]
	v_mfma_f32_16x16x32_bf16 v[10:13], v[156:159], v[208:211], v[10:13]
	v_mfma_f32_16x16x32_bf16 v[10:13], v[160:163], v[212:215], v[10:13]
	s_barrier
	s_add_i32 s4, s4, s24
	s_mov_b32 m0, s4
	s_nop 0
	global_load_lds_dwordx4 v132, s[76:77]
	s_add_i32 m0, s4, 0x2000
	s_nop 0
	global_load_lds_dwordx4 v136, s[76:77]
	s_add_u32 s0, s0, 0x100
	s_addc_u32 s1, s1, 0
	s_add_u32 s47, s47, 0x100
	s_addc_u32 s48, s48, 0
	s_cmp_ge_u32 s49, s30
	s_mov_b32 s4, s49
	s_waitcnt vmcnt(6)
	s_barrier
	v_mfma_f32_16x16x32_bf16 v[50:53], v[216:219], v[164:167], v[50:53]
	v_mfma_f32_16x16x32_bf16 v[50:53], v[220:223], v[168:171], v[50:53]
	v_mfma_f32_16x16x32_bf16 v[54:57], v[224:227], v[164:167], v[54:57]
	v_mfma_f32_16x16x32_bf16 v[54:57], v[228:231], v[168:171], v[54:57]
	v_mfma_f32_16x16x32_bf16 v[34:37], v[216:219], v[172:175], v[34:37]
	v_mfma_f32_16x16x32_bf16 v[34:37], v[220:223], v[176:179], v[34:37]
	v_mfma_f32_16x16x32_bf16 v[38:41], v[224:227], v[172:175], v[38:41]
	v_mfma_f32_16x16x32_bf16 v[38:41], v[228:231], v[176:179], v[38:41]
	v_mfma_f32_16x16x32_bf16 v[18:21], v[216:219], v[180:183], v[18:21]
	v_mfma_f32_16x16x32_bf16 v[18:21], v[220:223], v[204:207], v[18:21]
	v_mfma_f32_16x16x32_bf16 v[22:25], v[224:227], v[180:183], v[22:25]
	v_mfma_f32_16x16x32_bf16 v[22:25], v[228:231], v[204:207], v[22:25]
	v_mfma_f32_16x16x32_bf16 v[6:9], v[216:219], v[208:211], v[6:9]
	v_mfma_f32_16x16x32_bf16 v[6:9], v[220:223], v[212:215], v[6:9]
	v_mfma_f32_16x16x32_bf16 v[2:5], v[224:227], v[208:211], v[2:5]
	v_mfma_f32_16x16x32_bf16 v[2:5], v[228:231], v[212:215], v[2:5]
	s_barrier
	s_cbranch_scc0 .LBB0_253

.LBB0_281:
	s_add_u32 s0, s0, 0x80
	s_addc_u32 s1, s1, 0
	s_add_u32 s20, s4, 0x100
	s_addc_u32 s21, s5, 0
	s_mov_b32 s4, 0
	s_waitcnt lgkmcnt(0)
	s_add_i32 s22, s4, 2
	s_add_u32 s10, s0, 0x80
	s_addc_u32 s5, s1, 0
	s_add_i32 s23, 0, 0x10000
	ds_read_b128 v[142:145], v248
	ds_read_b128 v[146:149], v248 offset:1024
	ds_read_b128 v[150:153], v248 offset:2048
	ds_read_b128 v[154:157], v248 offset:3072
	s_cmp_eq_u32 s44, s4
	s_cselect_b32 s4, s16, s10
	s_cselect_b32 s5, s17, s5
	s_cselect_b32 s11, s13, s21
	s_cselect_b32 s10, s12, s20
	s_add_i32 m0, s29, 0xc000
	ds_read_b128 v[158:161], v166
	ds_read_b128 v[168:171], v166 offset:1024
	ds_read_b128 v[172:175], v166 offset:2048
	ds_read_b128 v[176:179], v166 offset:3072
	ds_read_b128 v[180:183], v166 offset:4096
	ds_read_b128 v[204:207], v166 offset:5120
	ds_read_b128 v[208:211], v166 offset:6144
	ds_read_b128 v[212:215], v166 offset:7168
	global_load_lds_dwordx4 v138, s[0:1]
	s_add_i32 m0, s29, 0xe000
	s_nop 0
	global_load_lds_dwordx4 v140, s[0:1]
	s_waitcnt lgkmcnt(8)
	s_barrier
	s_waitcnt lgkmcnt(0)
	v_mfma_f32_16x16x32_bf16 v[126:129], v[142:145], v[158:161], 0
	v_mfma_f32_16x16x32_bf16 v[126:129], v[146:149], v[168:171], v[126:129]
	v_mfma_f32_16x16x32_bf16 v[122:125], v[150:153], v[158:161], 0
	v_mfma_f32_16x16x32_bf16 v[122:125], v[154:157], v[168:171], v[122:125]
	v_mfma_f32_16x16x32_bf16 v[110:113], v[142:145], v[172:175], 0
	v_mfma_f32_16x16x32_bf16 v[110:113], v[146:149], v[176:179], v[110:113]
	v_mfma_f32_16x16x32_bf16 v[106:109], v[150:153], v[172:175], 0
	v_mfma_f32_16x16x32_bf16 v[106:109], v[154:157], v[176:179], v[106:109]
	v_mfma_f32_16x16x32_bf16 v[94:97], v[142:145], v[180:183], 0
	v_mfma_f32_16x16x32_bf16 v[94:97], v[146:149], v[204:207], v[94:97]
	v_mfma_f32_16x16x32_bf16 v[90:93], v[150:153], v[180:183], 0
	v_mfma_f32_16x16x32_bf16 v[90:93], v[154:157], v[204:207], v[90:93]
	v_mfma_f32_16x16x32_bf16 v[78:81], v[142:145], v[208:211], 0
	v_mfma_f32_16x16x32_bf16 v[78:81], v[146:149], v[212:215], v[78:81]
	v_mfma_f32_16x16x32_bf16 v[74:77], v[150:153], v[208:211], 0
	v_mfma_f32_16x16x32_bf16 v[74:77], v[154:157], v[212:215], v[74:77]
	s_barrier
	s_add_i32 s24, 0, 0x14000
	s_add_i32 s23, s23, s28
	ds_read_b128 v[216:219], v248 offset:16384
	ds_read_b128 v[220:223], v248 offset:17408
	ds_read_b128 v[224:227], v248 offset:18432
	ds_read_b128 v[228:231], v248 offset:19456
	s_add_u32 s70, s10, s6
	s_addc_u32 s71, s11, s7
	s_mov_b32 m0, s23
	s_nop 0
	global_load_lds_dwordx4 v132, s[10:11]
	s_add_i32 m0, s23, 0x2000
	s_nop 0
	global_load_lds_dwordx4 v136, s[10:11]
	s_barrier
	s_waitcnt lgkmcnt(0)
	v_mfma_f32_16x16x32_bf16 v[118:121], v[216:219], v[158:161], 0
	v_mfma_f32_16x16x32_bf16 v[118:121], v[220:223], v[168:171], v[118:121]
	v_mfma_f32_16x16x32_bf16 v[114:117], v[224:227], v[158:161], 0
	v_mfma_f32_16x16x32_bf16 v[114:117], v[228:231], v[168:171], v[114:117]
	v_mfma_f32_16x16x32_bf16 v[102:105], v[216:219], v[172:175], 0
	v_mfma_f32_16x16x32_bf16 v[102:105], v[220:223], v[176:179], v[102:105]
	v_mfma_f32_16x16x32_bf16 v[98:101], v[224:227], v[172:175], 0
	v_mfma_f32_16x16x32_bf16 v[98:101], v[228:231], v[176:179], v[98:101]
	v_mfma_f32_16x16x32_bf16 v[86:89], v[216:219], v[180:183], 0
	v_mfma_f32_16x16x32_bf16 v[86:89], v[220:223], v[204:207], v[86:89]
	v_mfma_f32_16x16x32_bf16 v[82:85], v[224:227], v[180:183], 0
	v_mfma_f32_16x16x32_bf16 v[82:85], v[228:231], v[204:207], v[82:85]
	v_mfma_f32_16x16x32_bf16 v[70:73], v[216:219], v[208:211], 0
	v_mfma_f32_16x16x32_bf16 v[70:73], v[220:223], v[212:215], v[70:73]
	v_mfma_f32_16x16x32_bf16 v[66:69], v[224:227], v[208:211], 0
	v_mfma_f32_16x16x32_bf16 v[66:69], v[228:231], v[212:215], v[66:69]
	s_barrier
	s_mov_b32 m0, s29
	s_add_u32 s72, s4, s6
	s_addc_u32 s73, s5, s7
	ds_read_b128 v[158:161], v166 offset:16384
	ds_read_b128 v[168:171], v166 offset:17408
	ds_read_b128 v[172:175], v166 offset:18432
	ds_read_b128 v[176:179], v166 offset:19456
	ds_read_b128 v[180:183], v166 offset:20480
	ds_read_b128 v[204:207], v166 offset:21504
	ds_read_b128 v[208:211], v166 offset:22528
	ds_read_b128 v[212:215], v166 offset:23552
	global_load_lds_dwordx4 v130, s[4:5]
	s_mov_b32 m0, s30
	s_nop 0
	global_load_lds_dwordx4 v134, s[4:5]
	s_barrier
	s_waitcnt lgkmcnt(0)
	v_mfma_f32_16x16x32_bf16 v[62:65], v[142:145], v[158:161], 0
	v_mfma_f32_16x16x32_bf16 v[62:65], v[146:149], v[168:171], v[62:65]
	v_mfma_f32_16x16x32_bf16 v[58:61], v[150:153], v[158:161], 0
	v_mfma_f32_16x16x32_bf16 v[58:61], v[154:157], v[168:171], v[58:61]
	v_mfma_f32_16x16x32_bf16 v[46:49], v[142:145], v[172:175], 0
	v_mfma_f32_16x16x32_bf16 v[46:49], v[146:149], v[176:179], v[46:49]
	v_mfma_f32_16x16x32_bf16 v[42:45], v[150:153], v[172:175], 0
	v_mfma_f32_16x16x32_bf16 v[42:45], v[154:157], v[176:179], v[42:45]
	v_mfma_f32_16x16x32_bf16 v[30:33], v[142:145], v[180:183], 0
	v_mfma_f32_16x16x32_bf16 v[30:33], v[146:149], v[204:207], v[30:33]
	v_mfma_f32_16x16x32_bf16 v[26:29], v[150:153], v[180:183], 0
	v_mfma_f32_16x16x32_bf16 v[26:29], v[154:157], v[204:207], v[26:29]
	v_mfma_f32_16x16x32_bf16 v[14:17], v[142:145], v[208:211], 0
	v_mfma_f32_16x16x32_bf16 v[14:17], v[146:149], v[212:215], v[14:17]
	v_mfma_f32_16x16x32_bf16 v[10:13], v[150:153], v[208:211], 0
	v_mfma_f32_16x16x32_bf16 v[10:13], v[154:157], v[212:215], v[10:13]
	s_barrier
	s_add_u32 s10, s10, s92
	s_addc_u32 s11, s11, 0
	s_add_i32 s23, s24, s28
	s_add_u32 s80, s10, s6
	s_addc_u32 s81, s11, s7
	s_mov_b32 m0, s23
	s_nop 0
	global_load_lds_dwordx4 v132, s[10:11]
	s_add_i32 m0, s23, 0x2000
	s_nop 0
	global_load_lds_dwordx4 v136, s[10:11]
	s_waitcnt vmcnt(6)
	s_barrier
	v_mfma_f32_16x16x32_bf16 v[54:57], v[216:219], v[158:161], 0
	v_mfma_f32_16x16x32_bf16 v[54:57], v[220:223], v[168:171], v[54:57]
	v_mfma_f32_16x16x32_bf16 v[50:53], v[224:227], v[158:161], 0
	v_mfma_f32_16x16x32_bf16 v[50:53], v[228:231], v[168:171], v[50:53]
	v_mfma_f32_16x16x32_bf16 v[38:41], v[216:219], v[172:175], 0
	v_mfma_f32_16x16x32_bf16 v[38:41], v[220:223], v[176:179], v[38:41]
	v_mfma_f32_16x16x32_bf16 v[34:37], v[224:227], v[172:175], 0
	v_mfma_f32_16x16x32_bf16 v[34:37], v[228:231], v[176:179], v[34:37]
	v_mfma_f32_16x16x32_bf16 v[22:25], v[216:219], v[180:183], 0
	v_mfma_f32_16x16x32_bf16 v[22:25], v[220:223], v[204:207], v[22:25]
	v_mfma_f32_16x16x32_bf16 v[18:21], v[224:227], v[180:183], 0
	v_mfma_f32_16x16x32_bf16 v[18:21], v[228:231], v[204:207], v[18:21]
	v_mfma_f32_16x16x32_bf16 v[6:9], v[216:219], v[208:211], 0
	v_mfma_f32_16x16x32_bf16 v[6:9], v[220:223], v[212:215], v[6:9]
	v_mfma_f32_16x16x32_bf16 v[2:5], v[224:227], v[208:211], 0
	v_mfma_f32_16x16x32_bf16 v[2:5], v[228:231], v[212:215], v[2:5]
	s_barrier
	s_add_i32 s10, 0, 0x18000
	ds_read_b128 v[142:145], v248 offset:32768
	ds_read_b128 v[146:149], v248 offset:33792
	ds_read_b128 v[150:153], v248 offset:34816
	ds_read_b128 v[154:157], v248 offset:35840
	s_add_u32 s4, s4, s92
	s_addc_u32 s5, s5, 0
	s_mov_b32 m0, s31
	ds_read_b128 v[158:161], v166 offset:32768
	ds_read_b128 v[168:171], v166 offset:33792
	ds_read_b128 v[172:175], v166 offset:34816
	ds_read_b128 v[176:179], v166 offset:35840
	ds_read_b128 v[180:183], v166 offset:36864
	ds_read_b128 v[204:207], v166 offset:37888
	ds_read_b128 v[208:211], v166 offset:38912
	ds_read_b128 v[212:215], v166 offset:39936
	global_load_lds_dwordx4 v130, s[4:5]
	s_mov_b32 m0, s34
	s_nop 0
	global_load_lds_dwordx4 v134, s[4:5]
	s_waitcnt lgkmcnt(8)
	s_barrier
	s_waitcnt lgkmcnt(0)
	v_mfma_f32_16x16x32_bf16 v[126:129], v[142:145], v[158:161], v[126:129]
	v_mfma_f32_16x16x32_bf16 v[126:129], v[146:149], v[168:171], v[126:129]
	v_mfma_f32_16x16x32_bf16 v[122:125], v[150:153], v[158:161], v[122:125]
	v_mfma_f32_16x16x32_bf16 v[122:125], v[154:157], v[168:171], v[122:125]
	v_mfma_f32_16x16x32_bf16 v[110:113], v[142:145], v[172:175], v[110:113]
	v_mfma_f32_16x16x32_bf16 v[110:113], v[146:149], v[176:179], v[110:113]
	v_mfma_f32_16x16x32_bf16 v[106:109], v[150:153], v[172:175], v[106:109]
	v_mfma_f32_16x16x32_bf16 v[106:109], v[154:157], v[176:179], v[106:109]
	v_mfma_f32_16x16x32_bf16 v[94:97], v[142:145], v[180:183], v[94:97]
	v_mfma_f32_16x16x32_bf16 v[94:97], v[146:149], v[204:207], v[94:97]
	v_mfma_f32_16x16x32_bf16 v[90:93], v[150:153], v[180:183], v[90:93]
	v_mfma_f32_16x16x32_bf16 v[90:93], v[154:157], v[204:207], v[90:93]
	v_mfma_f32_16x16x32_bf16 v[78:81], v[142:145], v[208:211], v[78:81]
	v_mfma_f32_16x16x32_bf16 v[78:81], v[146:149], v[212:215], v[78:81]
	v_mfma_f32_16x16x32_bf16 v[74:77], v[150:153], v[208:211], v[74:77]
	v_mfma_f32_16x16x32_bf16 v[74:77], v[154:157], v[212:215], v[74:77]
	s_barrier
	s_add_i32 s4, 0, 0x1c000
	s_add_i32 s5, s10, s28
	s_mov_b32 m0, s5
	ds_read_b128 v[216:219], v248 offset:49152
	ds_read_b128 v[220:223], v248 offset:50176
	ds_read_b128 v[224:227], v248 offset:51200
	ds_read_b128 v[228:231], v248 offset:52224
	global_load_lds_dwordx4 v132, s[70:71]
	s_add_i32 m0, s5, 0x2000
	s_nop 0
	global_load_lds_dwordx4 v136, s[70:71]
	s_barrier
	s_waitcnt lgkmcnt(0)
	v_mfma_f32_16x16x32_bf16 v[118:121], v[216:219], v[158:161], v[118:121]
	v_mfma_f32_16x16x32_bf16 v[118:121], v[220:223], v[168:171], v[118:121]
	v_mfma_f32_16x16x32_bf16 v[114:117], v[224:227], v[158:161], v[114:117]
	v_mfma_f32_16x16x32_bf16 v[114:117], v[228:231], v[168:171], v[114:117]
	v_mfma_f32_16x16x32_bf16 v[102:105], v[216:219], v[172:175], v[102:105]
	v_mfma_f32_16x16x32_bf16 v[102:105], v[220:223], v[176:179], v[102:105]
	v_mfma_f32_16x16x32_bf16 v[98:101], v[224:227], v[172:175], v[98:101]
	v_mfma_f32_16x16x32_bf16 v[98:101], v[228:231], v[176:179], v[98:101]
	v_mfma_f32_16x16x32_bf16 v[86:89], v[216:219], v[180:183], v[86:89]
	v_mfma_f32_16x16x32_bf16 v[86:89], v[220:223], v[204:207], v[86:89]
	v_mfma_f32_16x16x32_bf16 v[82:85], v[224:227], v[180:183], v[82:85]
	v_mfma_f32_16x16x32_bf16 v[82:85], v[228:231], v[204:207], v[82:85]
	v_mfma_f32_16x16x32_bf16 v[70:73], v[216:219], v[208:211], v[70:73]
	v_mfma_f32_16x16x32_bf16 v[70:73], v[220:223], v[212:215], v[70:73]
	v_mfma_f32_16x16x32_bf16 v[66:69], v[224:227], v[208:211], v[66:69]
	v_mfma_f32_16x16x32_bf16 v[66:69], v[228:231], v[212:215], v[66:69]
	s_barrier
	s_mov_b32 m0, s42
	ds_read_b128 v[158:161], v166 offset:49152
	ds_read_b128 v[168:171], v166 offset:50176
	ds_read_b128 v[172:175], v166 offset:51200
	ds_read_b128 v[176:179], v166 offset:52224
	ds_read_b128 v[180:183], v166 offset:53248
	ds_read_b128 v[204:207], v166 offset:54272
	ds_read_b128 v[208:211], v166 offset:55296
	ds_read_b128 v[212:215], v166 offset:56320
	global_load_lds_dwordx4 v130, s[72:73]
	s_mov_b32 m0, s43
	s_nop 0
	global_load_lds_dwordx4 v134, s[72:73]
	s_barrier
	s_waitcnt lgkmcnt(0)
	v_mfma_f32_16x16x32_bf16 v[62:65], v[142:145], v[158:161], v[62:65]
	v_mfma_f32_16x16x32_bf16 v[62:65], v[146:149], v[168:171], v[62:65]
	v_mfma_f32_16x16x32_bf16 v[58:61], v[150:153], v[158:161], v[58:61]
	v_mfma_f32_16x16x32_bf16 v[58:61], v[154:157], v[168:171], v[58:61]
	v_mfma_f32_16x16x32_bf16 v[46:49], v[142:145], v[172:175], v[46:49]
	v_mfma_f32_16x16x32_bf16 v[46:49], v[146:149], v[176:179], v[46:49]
	v_mfma_f32_16x16x32_bf16 v[42:45], v[150:153], v[172:175], v[42:45]
	v_mfma_f32_16x16x32_bf16 v[42:45], v[154:157], v[176:179], v[42:45]
	v_mfma_f32_16x16x32_bf16 v[30:33], v[142:145], v[180:183], v[30:33]
	v_mfma_f32_16x16x32_bf16 v[30:33], v[146:149], v[204:207], v[30:33]
	v_mfma_f32_16x16x32_bf16 v[26:29], v[150:153], v[180:183], v[26:29]
	v_mfma_f32_16x16x32_bf16 v[26:29], v[154:157], v[204:207], v[26:29]
	v_mfma_f32_16x16x32_bf16 v[14:17], v[142:145], v[208:211], v[14:17]
	v_mfma_f32_16x16x32_bf16 v[14:17], v[146:149], v[212:215], v[14:17]
	v_mfma_f32_16x16x32_bf16 v[10:13], v[150:153], v[208:211], v[10:13]
	v_mfma_f32_16x16x32_bf16 v[10:13], v[154:157], v[212:215], v[10:13]
	s_barrier
	s_add_i32 s4, s4, s28
	s_mov_b32 m0, s4
	s_nop 0
	global_load_lds_dwordx4 v132, s[80:81]
	s_add_i32 m0, s4, 0x2000
	s_nop 0
	global_load_lds_dwordx4 v136, s[80:81]
	s_add_u32 s0, s0, 0x100
	s_addc_u32 s1, s1, 0
	s_add_u32 s20, s20, 0x100
	s_addc_u32 s21, s21, 0
	s_cmp_ge_u32 s22, s35
	s_mov_b32 s4, s22
	s_waitcnt vmcnt(6)
	s_barrier
	v_mfma_f32_16x16x32_bf16 v[54:57], v[216:219], v[158:161], v[54:57]
	v_mfma_f32_16x16x32_bf16 v[54:57], v[220:223], v[168:171], v[54:57]
	v_mfma_f32_16x16x32_bf16 v[50:53], v[224:227], v[158:161], v[50:53]
	v_mfma_f32_16x16x32_bf16 v[50:53], v[228:231], v[168:171], v[50:53]
	v_mfma_f32_16x16x32_bf16 v[38:41], v[216:219], v[172:175], v[38:41]
	v_mfma_f32_16x16x32_bf16 v[38:41], v[220:223], v[176:179], v[38:41]
	v_mfma_f32_16x16x32_bf16 v[34:37], v[224:227], v[172:175], v[34:37]
	v_mfma_f32_16x16x32_bf16 v[34:37], v[228:231], v[176:179], v[34:37]
	v_mfma_f32_16x16x32_bf16 v[22:25], v[216:219], v[180:183], v[22:25]
	v_mfma_f32_16x16x32_bf16 v[22:25], v[220:223], v[204:207], v[22:25]
	v_mfma_f32_16x16x32_bf16 v[18:21], v[224:227], v[180:183], v[18:21]
	v_mfma_f32_16x16x32_bf16 v[18:21], v[228:231], v[204:207], v[18:21]
	v_mfma_f32_16x16x32_bf16 v[6:9], v[216:219], v[208:211], v[6:9]
	v_mfma_f32_16x16x32_bf16 v[6:9], v[220:223], v[212:215], v[6:9]
	v_mfma_f32_16x16x32_bf16 v[2:5], v[224:227], v[208:211], v[2:5]
	v_mfma_f32_16x16x32_bf16 v[2:5], v[228:231], v[212:215], v[2:5]
	s_barrier
	s_cbranch_scc1 .Lkexit_282
.LBB0_282:
	s_add_i32 s22, s4, 2
	s_add_u32 s10, s0, 0x80
	s_addc_u32 s5, s1, 0
	s_add_i32 s23, 0, 0x10000
	ds_read_b128 v[142:145], v248
	ds_read_b128 v[146:149], v248 offset:1024
	ds_read_b128 v[150:153], v248 offset:2048
	ds_read_b128 v[154:157], v248 offset:3072
	s_cmp_eq_u32 s44, s4
	s_cselect_b32 s4, s16, s10
	s_cselect_b32 s5, s17, s5
	s_cselect_b32 s11, s13, s21
	s_cselect_b32 s10, s12, s20
	s_add_i32 m0, s29, 0xc000
	ds_read_b128 v[158:161], v166
	ds_read_b128 v[168:171], v166 offset:1024
	ds_read_b128 v[172:175], v166 offset:2048
	ds_read_b128 v[176:179], v166 offset:3072
	ds_read_b128 v[180:183], v166 offset:4096
	ds_read_b128 v[204:207], v166 offset:5120
	ds_read_b128 v[208:211], v166 offset:6144
	ds_read_b128 v[212:215], v166 offset:7168
	global_load_lds_dwordx4 v138, s[0:1]
	s_add_i32 m0, s29, 0xe000
	s_nop 0
	global_load_lds_dwordx4 v140, s[0:1]
	s_waitcnt lgkmcnt(8)
	s_barrier
	s_waitcnt lgkmcnt(0)
	v_mfma_f32_16x16x32_bf16 v[126:129], v[142:145], v[158:161], v[126:129]
	v_mfma_f32_16x16x32_bf16 v[126:129], v[146:149], v[168:171], v[126:129]
	v_mfma_f32_16x16x32_bf16 v[122:125], v[150:153], v[158:161], v[122:125]
	v_mfma_f32_16x16x32_bf16 v[122:125], v[154:157], v[168:171], v[122:125]
	v_mfma_f32_16x16x32_bf16 v[110:113], v[142:145], v[172:175], v[110:113]
	v_mfma_f32_16x16x32_bf16 v[110:113], v[146:149], v[176:179], v[110:113]
	v_mfma_f32_16x16x32_bf16 v[106:109], v[150:153], v[172:175], v[106:109]
	v_mfma_f32_16x16x32_bf16 v[106:109], v[154:157], v[176:179], v[106:109]
	v_mfma_f32_16x16x32_bf16 v[94:97], v[142:145], v[180:183], v[94:97]
	v_mfma_f32_16x16x32_bf16 v[94:97], v[146:149], v[204:207], v[94:97]
	v_mfma_f32_16x16x32_bf16 v[90:93], v[150:153], v[180:183], v[90:93]
	v_mfma_f32_16x16x32_bf16 v[90:93], v[154:157], v[204:207], v[90:93]
	v_mfma_f32_16x16x32_bf16 v[78:81], v[142:145], v[208:211], v[78:81]
	v_mfma_f32_16x16x32_bf16 v[78:81], v[146:149], v[212:215], v[78:81]
	v_mfma_f32_16x16x32_bf16 v[74:77], v[150:153], v[208:211], v[74:77]
	v_mfma_f32_16x16x32_bf16 v[74:77], v[154:157], v[212:215], v[74:77]
	s_barrier
	s_add_i32 s24, 0, 0x14000
	s_add_i32 s23, s23, s28
	ds_read_b128 v[216:219], v248 offset:16384
	ds_read_b128 v[220:223], v248 offset:17408
	ds_read_b128 v[224:227], v248 offset:18432
	ds_read_b128 v[228:231], v248 offset:19456
	s_add_u32 s70, s10, s6
	s_addc_u32 s71, s11, s7
	s_mov_b32 m0, s23
	s_nop 0
	global_load_lds_dwordx4 v132, s[10:11]
	s_add_i32 m0, s23, 0x2000
	s_nop 0
	global_load_lds_dwordx4 v136, s[10:11]
	s_barrier
	s_waitcnt lgkmcnt(0)
	v_mfma_f32_16x16x32_bf16 v[118:121], v[216:219], v[158:161], v[118:121]
	v_mfma_f32_16x16x32_bf16 v[118:121], v[220:223], v[168:171], v[118:121]
	v_mfma_f32_16x16x32_bf16 v[114:117], v[224:227], v[158:161], v[114:117]
	v_mfma_f32_16x16x32_bf16 v[114:117], v[228:231], v[168:171], v[114:117]
	v_mfma_f32_16x16x32_bf16 v[102:105], v[216:219], v[172:175], v[102:105]
	v_mfma_f32_16x16x32_bf16 v[102:105], v[220:223], v[176:179], v[102:105]
	v_mfma_f32_16x16x32_bf16 v[98:101], v[224:227], v[172:175], v[98:101]
	v_mfma_f32_16x16x32_bf16 v[98:101], v[228:231], v[176:179], v[98:101]
	v_mfma_f32_16x16x32_bf16 v[86:89], v[216:219], v[180:183], v[86:89]
	v_mfma_f32_16x16x32_bf16 v[86:89], v[220:223], v[204:207], v[86:89]
	v_mfma_f32_16x16x32_bf16 v[82:85], v[224:227], v[180:183], v[82:85]
	v_mfma_f32_16x16x32_bf16 v[82:85], v[228:231], v[204:207], v[82:85]
	v_mfma_f32_16x16x32_bf16 v[70:73], v[216:219], v[208:211], v[70:73]
	v_mfma_f32_16x16x32_bf16 v[70:73], v[220:223], v[212:215], v[70:73]
	v_mfma_f32_16x16x32_bf16 v[66:69], v[224:227], v[208:211], v[66:69]
	v_mfma_f32_16x16x32_bf16 v[66:69], v[228:231], v[212:215], v[66:69]
	s_barrier
	s_mov_b32 m0, s29
	s_add_u32 s72, s4, s6
	s_addc_u32 s73, s5, s7
	ds_read_b128 v[158:161], v166 offset:16384
	ds_read_b128 v[168:171], v166 offset:17408
	ds_read_b128 v[172:175], v166 offset:18432
	ds_read_b128 v[176:179], v166 offset:19456
	ds_read_b128 v[180:183], v166 offset:20480
	ds_read_b128 v[204:207], v166 offset:21504
	ds_read_b128 v[208:211], v166 offset:22528
	ds_read_b128 v[212:215], v166 offset:23552
	global_load_lds_dwordx4 v130, s[4:5]
	s_mov_b32 m0, s30
	s_nop 0
	global_load_lds_dwordx4 v134, s[4:5]
	s_barrier
	s_waitcnt lgkmcnt(0)
	v_mfma_f32_16x16x32_bf16 v[62:65], v[142:145], v[158:161], v[62:65]
	v_mfma_f32_16x16x32_bf16 v[62:65], v[146:149], v[168:171], v[62:65]
	v_mfma_f32_16x16x32_bf16 v[58:61], v[150:153], v[158:161], v[58:61]
	v_mfma_f32_16x16x32_bf16 v[58:61], v[154:157], v[168:171], v[58:61]
	v_mfma_f32_16x16x32_bf16 v[46:49], v[142:145], v[172:175], v[46:49]
	v_mfma_f32_16x16x32_bf16 v[46:49], v[146:149], v[176:179], v[46:49]
	v_mfma_f32_16x16x32_bf16 v[42:45], v[150:153], v[172:175], v[42:45]
	v_mfma_f32_16x16x32_bf16 v[42:45], v[154:157], v[176:179], v[42:45]
	v_mfma_f32_16x16x32_bf16 v[30:33], v[142:145], v[180:183], v[30:33]
	v_mfma_f32_16x16x32_bf16 v[30:33], v[146:149], v[204:207], v[30:33]
	v_mfma_f32_16x16x32_bf16 v[26:29], v[150:153], v[180:183], v[26:29]
	v_mfma_f32_16x16x32_bf16 v[26:29], v[154:157], v[204:207], v[26:29]
	v_mfma_f32_16x16x32_bf16 v[14:17], v[142:145], v[208:211], v[14:17]
	v_mfma_f32_16x16x32_bf16 v[14:17], v[146:149], v[212:215], v[14:17]
	v_mfma_f32_16x16x32_bf16 v[10:13], v[150:153], v[208:211], v[10:13]
	v_mfma_f32_16x16x32_bf16 v[10:13], v[154:157], v[212:215], v[10:13]
	s_barrier
	s_add_u32 s10, s10, s92
	s_addc_u32 s11, s11, 0
	s_add_i32 s23, s24, s28
	s_add_u32 s80, s10, s6
	s_addc_u32 s81, s11, s7
	s_mov_b32 m0, s23
	s_nop 0
	global_load_lds_dwordx4 v132, s[10:11]
	s_add_i32 m0, s23, 0x2000
	s_nop 0
	global_load_lds_dwordx4 v136, s[10:11]
	s_waitcnt vmcnt(6)
	s_barrier
	v_mfma_f32_16x16x32_bf16 v[54:57], v[216:219], v[158:161], v[54:57]
	v_mfma_f32_16x16x32_bf16 v[54:57], v[220:223], v[168:171], v[54:57]
	v_mfma_f32_16x16x32_bf16 v[50:53], v[224:227], v[158:161], v[50:53]
	v_mfma_f32_16x16x32_bf16 v[50:53], v[228:231], v[168:171], v[50:53]
	v_mfma_f32_16x16x32_bf16 v[38:41], v[216:219], v[172:175], v[38:41]
	v_mfma_f32_16x16x32_bf16 v[38:41], v[220:223], v[176:179], v[38:41]
	v_mfma_f32_16x16x32_bf16 v[34:37], v[224:227], v[172:175], v[34:37]
	v_mfma_f32_16x16x32_bf16 v[34:37], v[228:231], v[176:179], v[34:37]
	v_mfma_f32_16x16x32_bf16 v[22:25], v[216:219], v[180:183], v[22:25]
	v_mfma_f32_16x16x32_bf16 v[22:25], v[220:223], v[204:207], v[22:25]
	v_mfma_f32_16x16x32_bf16 v[18:21], v[224:227], v[180:183], v[18:21]
	v_mfma_f32_16x16x32_bf16 v[18:21], v[228:231], v[204:207], v[18:21]
	v_mfma_f32_16x16x32_bf16 v[6:9], v[216:219], v[208:211], v[6:9]
	v_mfma_f32_16x16x32_bf16 v[6:9], v[220:223], v[212:215], v[6:9]
	v_mfma_f32_16x16x32_bf16 v[2:5], v[224:227], v[208:211], v[2:5]
	v_mfma_f32_16x16x32_bf16 v[2:5], v[228:231], v[212:215], v[2:5]
	s_barrier
	s_add_i32 s10, 0, 0x18000
	ds_read_b128 v[142:145], v248 offset:32768
	ds_read_b128 v[146:149], v248 offset:33792
	ds_read_b128 v[150:153], v248 offset:34816
	ds_read_b128 v[154:157], v248 offset:35840
	s_add_u32 s4, s4, s92
	s_addc_u32 s5, s5, 0
	s_mov_b32 m0, s31
	ds_read_b128 v[158:161], v166 offset:32768
	ds_read_b128 v[168:171], v166 offset:33792
	ds_read_b128 v[172:175], v166 offset:34816
	ds_read_b128 v[176:179], v166 offset:35840
	ds_read_b128 v[180:183], v166 offset:36864
	ds_read_b128 v[204:207], v166 offset:37888
	ds_read_b128 v[208:211], v166 offset:38912
	ds_read_b128 v[212:215], v166 offset:39936
	global_load_lds_dwordx4 v130, s[4:5]
	s_mov_b32 m0, s34
	s_nop 0
	global_load_lds_dwordx4 v134, s[4:5]
	s_waitcnt lgkmcnt(8)
	s_barrier
	s_waitcnt lgkmcnt(0)
	v_mfma_f32_16x16x32_bf16 v[126:129], v[142:145], v[158:161], v[126:129]
	v_mfma_f32_16x16x32_bf16 v[126:129], v[146:149], v[168:171], v[126:129]
	v_mfma_f32_16x16x32_bf16 v[122:125], v[150:153], v[158:161], v[122:125]
	v_mfma_f32_16x16x32_bf16 v[122:125], v[154:157], v[168:171], v[122:125]
	v_mfma_f32_16x16x32_bf16 v[110:113], v[142:145], v[172:175], v[110:113]
	v_mfma_f32_16x16x32_bf16 v[110:113], v[146:149], v[176:179], v[110:113]
	v_mfma_f32_16x16x32_bf16 v[106:109], v[150:153], v[172:175], v[106:109]
	v_mfma_f32_16x16x32_bf16 v[106:109], v[154:157], v[176:179], v[106:109]
	v_mfma_f32_16x16x32_bf16 v[94:97], v[142:145], v[180:183], v[94:97]
	v_mfma_f32_16x16x32_bf16 v[94:97], v[146:149], v[204:207], v[94:97]
	v_mfma_f32_16x16x32_bf16 v[90:93], v[150:153], v[180:183], v[90:93]
	v_mfma_f32_16x16x32_bf16 v[90:93], v[154:157], v[204:207], v[90:93]
	v_mfma_f32_16x16x32_bf16 v[78:81], v[142:145], v[208:211], v[78:81]
	v_mfma_f32_16x16x32_bf16 v[78:81], v[146:149], v[212:215], v[78:81]
	v_mfma_f32_16x16x32_bf16 v[74:77], v[150:153], v[208:211], v[74:77]
	v_mfma_f32_16x16x32_bf16 v[74:77], v[154:157], v[212:215], v[74:77]
	s_barrier
	s_add_i32 s4, 0, 0x1c000
	s_add_i32 s5, s10, s28
	s_mov_b32 m0, s5
	ds_read_b128 v[216:219], v248 offset:49152
	ds_read_b128 v[220:223], v248 offset:50176
	ds_read_b128 v[224:227], v248 offset:51200
	ds_read_b128 v[228:231], v248 offset:52224
	global_load_lds_dwordx4 v132, s[70:71]
	s_add_i32 m0, s5, 0x2000
	s_nop 0
	global_load_lds_dwordx4 v136, s[70:71]
	s_barrier
	s_waitcnt lgkmcnt(0)
	v_mfma_f32_16x16x32_bf16 v[118:121], v[216:219], v[158:161], v[118:121]
	v_mfma_f32_16x16x32_bf16 v[118:121], v[220:223], v[168:171], v[118:121]
	v_mfma_f32_16x16x32_bf16 v[114:117], v[224:227], v[158:161], v[114:117]
	v_mfma_f32_16x16x32_bf16 v[114:117], v[228:231], v[168:171], v[114:117]
	v_mfma_f32_16x16x32_bf16 v[102:105], v[216:219], v[172:175], v[102:105]
	v_mfma_f32_16x16x32_bf16 v[102:105], v[220:223], v[176:179], v[102:105]
	v_mfma_f32_16x16x32_bf16 v[98:101], v[224:227], v[172:175], v[98:101]
	v_mfma_f32_16x16x32_bf16 v[98:101], v[228:231], v[176:179], v[98:101]
	v_mfma_f32_16x16x32_bf16 v[86:89], v[216:219], v[180:183], v[86:89]
	v_mfma_f32_16x16x32_bf16 v[86:89], v[220:223], v[204:207], v[86:89]
	v_mfma_f32_16x16x32_bf16 v[82:85], v[224:227], v[180:183], v[82:85]
	v_mfma_f32_16x16x32_bf16 v[82:85], v[228:231], v[204:207], v[82:85]
	v_mfma_f32_16x16x32_bf16 v[70:73], v[216:219], v[208:211], v[70:73]
	v_mfma_f32_16x16x32_bf16 v[70:73], v[220:223], v[212:215], v[70:73]
	v_mfma_f32_16x16x32_bf16 v[66:69], v[224:227], v[208:211], v[66:69]
	v_mfma_f32_16x16x32_bf16 v[66:69], v[228:231], v[212:215], v[66:69]
	s_barrier
	s_mov_b32 m0, s42
	ds_read_b128 v[158:161], v166 offset:49152
	ds_read_b128 v[168:171], v166 offset:50176
	ds_read_b128 v[172:175], v166 offset:51200
	ds_read_b128 v[176:179], v166 offset:52224
	ds_read_b128 v[180:183], v166 offset:53248
	ds_read_b128 v[204:207], v166 offset:54272
	ds_read_b128 v[208:211], v166 offset:55296
	ds_read_b128 v[212:215], v166 offset:56320
	global_load_lds_dwordx4 v130, s[72:73]
	s_mov_b32 m0, s43
	s_nop 0
	global_load_lds_dwordx4 v134, s[72:73]
	s_barrier
	s_waitcnt lgkmcnt(0)
	v_mfma_f32_16x16x32_bf16 v[62:65], v[142:145], v[158:161], v[62:65]
	v_mfma_f32_16x16x32_bf16 v[62:65], v[146:149], v[168:171], v[62:65]
	v_mfma_f32_16x16x32_bf16 v[58:61], v[150:153], v[158:161], v[58:61]
	v_mfma_f32_16x16x32_bf16 v[58:61], v[154:157], v[168:171], v[58:61]
	v_mfma_f32_16x16x32_bf16 v[46:49], v[142:145], v[172:175], v[46:49]
	v_mfma_f32_16x16x32_bf16 v[46:49], v[146:149], v[176:179], v[46:49]
	v_mfma_f32_16x16x32_bf16 v[42:45], v[150:153], v[172:175], v[42:45]
	v_mfma_f32_16x16x32_bf16 v[42:45], v[154:157], v[176:179], v[42:45]
	v_mfma_f32_16x16x32_bf16 v[30:33], v[142:145], v[180:183], v[30:33]
	v_mfma_f32_16x16x32_bf16 v[30:33], v[146:149], v[204:207], v[30:33]
	v_mfma_f32_16x16x32_bf16 v[26:29], v[150:153], v[180:183], v[26:29]
	v_mfma_f32_16x16x32_bf16 v[26:29], v[154:157], v[204:207], v[26:29]
	v_mfma_f32_16x16x32_bf16 v[14:17], v[142:145], v[208:211], v[14:17]
	v_mfma_f32_16x16x32_bf16 v[14:17], v[146:149], v[212:215], v[14:17]
	v_mfma_f32_16x16x32_bf16 v[10:13], v[150:153], v[208:211], v[10:13]
	v_mfma_f32_16x16x32_bf16 v[10:13], v[154:157], v[212:215], v[10:13]
	s_barrier
	s_add_i32 s4, s4, s28
	s_mov_b32 m0, s4
	s_nop 0
	global_load_lds_dwordx4 v132, s[80:81]
	s_add_i32 m0, s4, 0x2000
	s_nop 0
	global_load_lds_dwordx4 v136, s[80:81]
	s_add_u32 s0, s0, 0x100
	s_addc_u32 s1, s1, 0
	s_add_u32 s20, s20, 0x100
	s_addc_u32 s21, s21, 0
	s_cmp_ge_u32 s22, s35
	s_mov_b32 s4, s22
	s_waitcnt vmcnt(6)
	s_barrier
	v_mfma_f32_16x16x32_bf16 v[54:57], v[216:219], v[158:161], v[54:57]
	v_mfma_f32_16x16x32_bf16 v[54:57], v[220:223], v[168:171], v[54:57]
	v_mfma_f32_16x16x32_bf16 v[50:53], v[224:227], v[158:161], v[50:53]
	v_mfma_f32_16x16x32_bf16 v[50:53], v[228:231], v[168:171], v[50:53]
	v_mfma_f32_16x16x32_bf16 v[38:41], v[216:219], v[172:175], v[38:41]
	v_mfma_f32_16x16x32_bf16 v[38:41], v[220:223], v[176:179], v[38:41]
	v_mfma_f32_16x16x32_bf16 v[34:37], v[224:227], v[172:175], v[34:37]
	v_mfma_f32_16x16x32_bf16 v[34:37], v[228:231], v[176:179], v[34:37]
	v_mfma_f32_16x16x32_bf16 v[22:25], v[216:219], v[180:183], v[22:25]
	v_mfma_f32_16x16x32_bf16 v[22:25], v[220:223], v[204:207], v[22:25]
	v_mfma_f32_16x16x32_bf16 v[18:21], v[224:227], v[180:183], v[18:21]
	v_mfma_f32_16x16x32_bf16 v[18:21], v[228:231], v[204:207], v[18:21]
	v_mfma_f32_16x16x32_bf16 v[6:9], v[216:219], v[208:211], v[6:9]
	v_mfma_f32_16x16x32_bf16 v[6:9], v[220:223], v[212:215], v[6:9]
	v_mfma_f32_16x16x32_bf16 v[2:5], v[224:227], v[208:211], v[2:5]
	v_mfma_f32_16x16x32_bf16 v[2:5], v[228:231], v[212:215], v[2:5]
	s_barrier
	s_cbranch_scc0 .LBB0_282

.LBB0_346:
	s_add_u32 s0, s0, 0x80
	s_addc_u32 s1, s1, 0
	s_add_u32 s12, s4, 0x100
	s_addc_u32 s13, s5, 0
	s_mov_b32 s4, 0
	s_waitcnt lgkmcnt(0)
	s_waitcnt vmcnt(0)
	s_add_i32 s15, s4, 2
	s_add_u32 s10, s0, 0x80
	s_addc_u32 s5, s1, 0
	s_add_i32 s16, 0, 0x10000
	ds_read_b128 v[130:133], v248
	ds_read_b128 v[134:137], v248 offset:1024
	ds_read_b128 v[138:141], v248 offset:2048
	ds_read_b128 v[142:145], v248 offset:3072
	s_cmp_eq_u32 s79, s4
	s_cselect_b32 s4, s44, s10
	s_cselect_b32 s5, s45, s5
	s_cselect_b32 s11, s47, s13
	s_cselect_b32 s10, s46, s12
	s_add_i32 m0, s71, 0xc000
	ds_read_b128 v[158:161], v206
	ds_read_b128 v[162:165], v206 offset:1024
	ds_read_b128 v[166:169], v206 offset:2048
	ds_read_b128 v[170:173], v206 offset:3072
	ds_read_b128 v[174:177], v206 offset:4096
	ds_read_b128 v[178:181], v206 offset:5120
	ds_read_b128 v[182:185], v206 offset:6144
	ds_read_b128 v[208:211], v206 offset:7168
	global_load_lds_dwordx4 v154, s[0:1]
	s_add_i32 m0, s71, 0xe000
	s_nop 0
	global_load_lds_dwordx4 v156, s[0:1]
	s_waitcnt lgkmcnt(8)
	s_barrier
	s_waitcnt lgkmcnt(0)
	v_mfma_f32_16x16x32_bf16 v[126:129], v[130:133], v[158:161], 0
	v_mfma_f32_16x16x32_bf16 v[126:129], v[134:137], v[162:165], v[126:129]
	v_mfma_f32_16x16x32_bf16 v[122:125], v[138:141], v[158:161], 0
	v_mfma_f32_16x16x32_bf16 v[122:125], v[142:145], v[162:165], v[122:125]
	v_mfma_f32_16x16x32_bf16 v[110:113], v[130:133], v[166:169], 0
	v_mfma_f32_16x16x32_bf16 v[110:113], v[134:137], v[170:173], v[110:113]
	v_mfma_f32_16x16x32_bf16 v[106:109], v[138:141], v[166:169], 0
	v_mfma_f32_16x16x32_bf16 v[106:109], v[142:145], v[170:173], v[106:109]
	v_mfma_f32_16x16x32_bf16 v[94:97], v[130:133], v[174:177], 0
	v_mfma_f32_16x16x32_bf16 v[94:97], v[134:137], v[178:181], v[94:97]
	v_mfma_f32_16x16x32_bf16 v[90:93], v[138:141], v[174:177], 0
	v_mfma_f32_16x16x32_bf16 v[90:93], v[142:145], v[178:181], v[90:93]
	v_mfma_f32_16x16x32_bf16 v[78:81], v[130:133], v[182:185], 0
	v_mfma_f32_16x16x32_bf16 v[78:81], v[134:137], v[208:211], v[78:81]
	v_mfma_f32_16x16x32_bf16 v[74:77], v[138:141], v[182:185], 0
	v_mfma_f32_16x16x32_bf16 v[74:77], v[142:145], v[208:211], v[74:77]
	s_barrier
	s_add_i32 s17, 0, 0x14000
	s_add_i32 s16, s16, s70
	s_add_u32 s2, s10, s6
	s_addc_u32 s3, s11, s7
	s_mov_b32 m0, s16
	ds_read_b128 v[212:215], v248 offset:16384
	ds_read_b128 v[216:219], v248 offset:17408
	ds_read_b128 v[220:223], v248 offset:18432
	ds_read_b128 v[224:227], v248 offset:19456
	global_load_lds_dwordx4 v148, s[10:11]
	s_add_i32 m0, s16, 0x2000
	s_nop 0
	global_load_lds_dwordx4 v152, s[10:11]
	s_barrier
	s_waitcnt lgkmcnt(0)
	v_mfma_f32_16x16x32_bf16 v[118:121], v[212:215], v[158:161], 0
	v_mfma_f32_16x16x32_bf16 v[118:121], v[216:219], v[162:165], v[118:121]
	v_mfma_f32_16x16x32_bf16 v[114:117], v[220:223], v[158:161], 0
	v_mfma_f32_16x16x32_bf16 v[114:117], v[224:227], v[162:165], v[114:117]
	v_mfma_f32_16x16x32_bf16 v[102:105], v[212:215], v[166:169], 0
	v_mfma_f32_16x16x32_bf16 v[102:105], v[216:219], v[170:173], v[102:105]
	v_mfma_f32_16x16x32_bf16 v[98:101], v[220:223], v[166:169], 0
	v_mfma_f32_16x16x32_bf16 v[98:101], v[224:227], v[170:173], v[98:101]
	v_mfma_f32_16x16x32_bf16 v[86:89], v[212:215], v[174:177], 0
	v_mfma_f32_16x16x32_bf16 v[86:89], v[216:219], v[178:181], v[86:89]
	v_mfma_f32_16x16x32_bf16 v[82:85], v[220:223], v[174:177], 0
	v_mfma_f32_16x16x32_bf16 v[82:85], v[224:227], v[178:181], v[82:85]
	v_mfma_f32_16x16x32_bf16 v[70:73], v[212:215], v[182:185], 0
	v_mfma_f32_16x16x32_bf16 v[70:73], v[216:219], v[208:211], v[70:73]
	v_mfma_f32_16x16x32_bf16 v[66:69], v[220:223], v[182:185], 0
	v_mfma_f32_16x16x32_bf16 v[66:69], v[224:227], v[208:211], v[66:69]
	s_barrier
	s_mov_b32 m0, s71
	s_add_u32 s98, s4, s6
	s_addc_u32 s99, s5, s7
	ds_read_b128 v[158:161], v206 offset:16384
	ds_read_b128 v[162:165], v206 offset:17408
	ds_read_b128 v[166:169], v206 offset:18432
	ds_read_b128 v[170:173], v206 offset:19456
	ds_read_b128 v[174:177], v206 offset:20480
	ds_read_b128 v[178:181], v206 offset:21504
	ds_read_b128 v[182:185], v206 offset:22528
	ds_read_b128 v[208:211], v206 offset:23552
	global_load_lds_dwordx4 v146, s[4:5]
	s_mov_b32 m0, s72
	s_nop 0
	global_load_lds_dwordx4 v150, s[4:5]
	s_barrier
	s_waitcnt lgkmcnt(0)
	v_mfma_f32_16x16x32_bf16 v[62:65], v[130:133], v[158:161], 0
	v_mfma_f32_16x16x32_bf16 v[62:65], v[134:137], v[162:165], v[62:65]
	v_mfma_f32_16x16x32_bf16 v[58:61], v[138:141], v[158:161], 0
	v_mfma_f32_16x16x32_bf16 v[58:61], v[142:145], v[162:165], v[58:61]
	v_mfma_f32_16x16x32_bf16 v[46:49], v[130:133], v[166:169], 0
	v_mfma_f32_16x16x32_bf16 v[46:49], v[134:137], v[170:173], v[46:49]
	v_mfma_f32_16x16x32_bf16 v[42:45], v[138:141], v[166:169], 0
	v_mfma_f32_16x16x32_bf16 v[42:45], v[142:145], v[170:173], v[42:45]
	v_mfma_f32_16x16x32_bf16 v[30:33], v[130:133], v[174:177], 0
	v_mfma_f32_16x16x32_bf16 v[30:33], v[134:137], v[178:181], v[30:33]
	v_mfma_f32_16x16x32_bf16 v[26:29], v[138:141], v[174:177], 0
	v_mfma_f32_16x16x32_bf16 v[26:29], v[142:145], v[178:181], v[26:29]
	v_mfma_f32_16x16x32_bf16 v[14:17], v[130:133], v[182:185], 0
	v_mfma_f32_16x16x32_bf16 v[14:17], v[134:137], v[208:211], v[14:17]
	v_mfma_f32_16x16x32_bf16 v[10:13], v[138:141], v[182:185], 0
	v_mfma_f32_16x16x32_bf16 v[10:13], v[142:145], v[208:211], v[10:13]
	s_barrier
	s_add_u32 s10, s10, s92
	s_addc_u32 s11, s11, 0
	s_add_i32 s16, s17, s70
	v_lshl_add_u64 v[236:237], s[10:11], 0, v[148:149]
	s_mov_b32 m0, s16
	v_lshl_add_u64 v[238:239], s[10:11], 0, v[152:153]
	global_load_lds_dwordx4 v[236:237], off
	s_add_i32 m0, s16, 0x2000
	s_nop 0
	global_load_lds_dwordx4 v[238:239], off
	s_waitcnt vmcnt(6)
	s_barrier
	v_mfma_f32_16x16x32_bf16 v[54:57], v[212:215], v[158:161], 0
	v_mfma_f32_16x16x32_bf16 v[54:57], v[216:219], v[162:165], v[54:57]
	v_mfma_f32_16x16x32_bf16 v[50:53], v[220:223], v[158:161], 0
	v_mfma_f32_16x16x32_bf16 v[50:53], v[224:227], v[162:165], v[50:53]
	v_mfma_f32_16x16x32_bf16 v[38:41], v[212:215], v[166:169], 0
	v_mfma_f32_16x16x32_bf16 v[38:41], v[216:219], v[170:173], v[38:41]
	v_mfma_f32_16x16x32_bf16 v[34:37], v[220:223], v[166:169], 0
	v_mfma_f32_16x16x32_bf16 v[34:37], v[224:227], v[170:173], v[34:37]
	v_mfma_f32_16x16x32_bf16 v[22:25], v[212:215], v[174:177], 0
	v_mfma_f32_16x16x32_bf16 v[22:25], v[216:219], v[178:181], v[22:25]
	v_mfma_f32_16x16x32_bf16 v[18:21], v[220:223], v[174:177], 0
	v_mfma_f32_16x16x32_bf16 v[18:21], v[224:227], v[178:181], v[18:21]
	v_mfma_f32_16x16x32_bf16 v[6:9], v[212:215], v[182:185], 0
	v_mfma_f32_16x16x32_bf16 v[6:9], v[216:219], v[208:211], v[6:9]
	v_mfma_f32_16x16x32_bf16 v[2:5], v[220:223], v[182:185], 0
	v_mfma_f32_16x16x32_bf16 v[2:5], v[224:227], v[208:211], v[2:5]
	s_barrier
	s_add_i32 s10, 0, 0x18000
	ds_read_b128 v[130:133], v248 offset:32768
	ds_read_b128 v[134:137], v248 offset:33792
	ds_read_b128 v[138:141], v248 offset:34816
	ds_read_b128 v[142:145], v248 offset:35840
	s_add_u32 s4, s4, s92
	s_addc_u32 s5, s5, 0
	s_mov_b32 m0, s73
	ds_read_b128 v[158:161], v206 offset:32768
	ds_read_b128 v[162:165], v206 offset:33792
	ds_read_b128 v[166:169], v206 offset:34816
	ds_read_b128 v[170:173], v206 offset:35840
	ds_read_b128 v[174:177], v206 offset:36864
	ds_read_b128 v[178:181], v206 offset:37888
	ds_read_b128 v[182:185], v206 offset:38912
	ds_read_b128 v[208:211], v206 offset:39936
	global_load_lds_dwordx4 v146, s[4:5]
	s_mov_b32 m0, s74
	s_nop 0
	global_load_lds_dwordx4 v150, s[4:5]
	s_waitcnt lgkmcnt(8)
	s_barrier
	s_waitcnt lgkmcnt(0)
	v_mfma_f32_16x16x32_bf16 v[126:129], v[130:133], v[158:161], v[126:129]
	v_mfma_f32_16x16x32_bf16 v[126:129], v[134:137], v[162:165], v[126:129]
	v_mfma_f32_16x16x32_bf16 v[122:125], v[138:141], v[158:161], v[122:125]
	v_mfma_f32_16x16x32_bf16 v[122:125], v[142:145], v[162:165], v[122:125]
	v_mfma_f32_16x16x32_bf16 v[110:113], v[130:133], v[166:169], v[110:113]
	v_mfma_f32_16x16x32_bf16 v[110:113], v[134:137], v[170:173], v[110:113]
	v_mfma_f32_16x16x32_bf16 v[106:109], v[138:141], v[166:169], v[106:109]
	v_mfma_f32_16x16x32_bf16 v[106:109], v[142:145], v[170:173], v[106:109]
	v_mfma_f32_16x16x32_bf16 v[94:97], v[130:133], v[174:177], v[94:97]
	v_mfma_f32_16x16x32_bf16 v[94:97], v[134:137], v[178:181], v[94:97]
	v_mfma_f32_16x16x32_bf16 v[90:93], v[138:141], v[174:177], v[90:93]
	v_mfma_f32_16x16x32_bf16 v[90:93], v[142:145], v[178:181], v[90:93]
	v_mfma_f32_16x16x32_bf16 v[78:81], v[130:133], v[182:185], v[78:81]
	v_mfma_f32_16x16x32_bf16 v[78:81], v[134:137], v[208:211], v[78:81]
	v_mfma_f32_16x16x32_bf16 v[74:77], v[138:141], v[182:185], v[74:77]
	v_mfma_f32_16x16x32_bf16 v[74:77], v[142:145], v[208:211], v[74:77]
	s_barrier
	s_add_i32 s4, 0, 0x1c000
	s_add_i32 s5, s10, s70
	s_mov_b32 m0, s5
	ds_read_b128 v[212:215], v248 offset:49152
	ds_read_b128 v[216:219], v248 offset:50176
	ds_read_b128 v[220:223], v248 offset:51200
	ds_read_b128 v[224:227], v248 offset:52224
	global_load_lds_dwordx4 v148, s[2:3]
	s_add_i32 m0, s5, 0x2000
	s_nop 0
	global_load_lds_dwordx4 v152, s[2:3]
	s_barrier
	s_waitcnt lgkmcnt(0)
	v_mfma_f32_16x16x32_bf16 v[118:121], v[212:215], v[158:161], v[118:121]
	v_mfma_f32_16x16x32_bf16 v[118:121], v[216:219], v[162:165], v[118:121]
	v_mfma_f32_16x16x32_bf16 v[114:117], v[220:223], v[158:161], v[114:117]
	v_mfma_f32_16x16x32_bf16 v[114:117], v[224:227], v[162:165], v[114:117]
	v_mfma_f32_16x16x32_bf16 v[102:105], v[212:215], v[166:169], v[102:105]
	v_mfma_f32_16x16x32_bf16 v[102:105], v[216:219], v[170:173], v[102:105]
	v_mfma_f32_16x16x32_bf16 v[98:101], v[220:223], v[166:169], v[98:101]
	v_mfma_f32_16x16x32_bf16 v[98:101], v[224:227], v[170:173], v[98:101]
	v_mfma_f32_16x16x32_bf16 v[86:89], v[212:215], v[174:177], v[86:89]
	v_mfma_f32_16x16x32_bf16 v[86:89], v[216:219], v[178:181], v[86:89]
	v_mfma_f32_16x16x32_bf16 v[82:85], v[220:223], v[174:177], v[82:85]
	v_mfma_f32_16x16x32_bf16 v[82:85], v[224:227], v[178:181], v[82:85]
	v_mfma_f32_16x16x32_bf16 v[70:73], v[212:215], v[182:185], v[70:73]
	v_mfma_f32_16x16x32_bf16 v[70:73], v[216:219], v[208:211], v[70:73]
	v_mfma_f32_16x16x32_bf16 v[66:69], v[220:223], v[182:185], v[66:69]
	v_mfma_f32_16x16x32_bf16 v[66:69], v[224:227], v[208:211], v[66:69]
	s_barrier
	s_mov_b32 m0, s77
	ds_read_b128 v[158:161], v206 offset:49152
	ds_read_b128 v[162:165], v206 offset:50176
	ds_read_b128 v[166:169], v206 offset:51200
	ds_read_b128 v[170:173], v206 offset:52224
	ds_read_b128 v[174:177], v206 offset:53248
	ds_read_b128 v[178:181], v206 offset:54272
	ds_read_b128 v[182:185], v206 offset:55296
	ds_read_b128 v[208:211], v206 offset:56320
	global_load_lds_dwordx4 v146, s[98:99]
	s_mov_b32 m0, s78
	s_nop 0
	global_load_lds_dwordx4 v150, s[98:99]
	s_barrier
	s_waitcnt lgkmcnt(0)
	v_mfma_f32_16x16x32_bf16 v[62:65], v[130:133], v[158:161], v[62:65]
	v_mfma_f32_16x16x32_bf16 v[62:65], v[134:137], v[162:165], v[62:65]
	v_mfma_f32_16x16x32_bf16 v[58:61], v[138:141], v[158:161], v[58:61]
	v_mfma_f32_16x16x32_bf16 v[58:61], v[142:145], v[162:165], v[58:61]
	v_mfma_f32_16x16x32_bf16 v[46:49], v[130:133], v[166:169], v[46:49]
	v_mfma_f32_16x16x32_bf16 v[46:49], v[134:137], v[170:173], v[46:49]
	v_mfma_f32_16x16x32_bf16 v[42:45], v[138:141], v[166:169], v[42:45]
	v_mfma_f32_16x16x32_bf16 v[42:45], v[142:145], v[170:173], v[42:45]
	v_mfma_f32_16x16x32_bf16 v[30:33], v[130:133], v[174:177], v[30:33]
	v_mfma_f32_16x16x32_bf16 v[30:33], v[134:137], v[178:181], v[30:33]
	v_mfma_f32_16x16x32_bf16 v[26:29], v[138:141], v[174:177], v[26:29]
	v_mfma_f32_16x16x32_bf16 v[26:29], v[142:145], v[178:181], v[26:29]
	v_mfma_f32_16x16x32_bf16 v[14:17], v[130:133], v[182:185], v[14:17]
	v_mfma_f32_16x16x32_bf16 v[14:17], v[134:137], v[208:211], v[14:17]
	v_mfma_f32_16x16x32_bf16 v[10:13], v[138:141], v[182:185], v[10:13]
	v_mfma_f32_16x16x32_bf16 v[10:13], v[142:145], v[208:211], v[10:13]
	s_barrier
	s_add_i32 s4, s4, s70
	v_lshl_add_u64 v[130:131], v[236:237], 0, s[6:7]
	s_mov_b32 m0, s4
	s_nop 0
	global_load_lds_dwordx4 v[130:131], off
	v_lshl_add_u64 v[130:131], v[238:239], 0, s[6:7]
	s_add_i32 m0, s4, 0x2000
	s_nop 0
	global_load_lds_dwordx4 v[130:131], off
	s_add_u32 s0, s0, 0x100
	s_addc_u32 s1, s1, 0
	s_add_u32 s12, s12, 0x100
	s_addc_u32 s13, s13, 0
	s_cmp_ge_u32 s15, s75
	s_mov_b32 s4, s15
	s_waitcnt vmcnt(6)
	s_barrier
	v_mfma_f32_16x16x32_bf16 v[54:57], v[212:215], v[158:161], v[54:57]
	v_mfma_f32_16x16x32_bf16 v[54:57], v[216:219], v[162:165], v[54:57]
	v_mfma_f32_16x16x32_bf16 v[50:53], v[220:223], v[158:161], v[50:53]
	v_mfma_f32_16x16x32_bf16 v[50:53], v[224:227], v[162:165], v[50:53]
	v_mfma_f32_16x16x32_bf16 v[38:41], v[212:215], v[166:169], v[38:41]
	v_mfma_f32_16x16x32_bf16 v[38:41], v[216:219], v[170:173], v[38:41]
	v_mfma_f32_16x16x32_bf16 v[34:37], v[220:223], v[166:169], v[34:37]
	v_mfma_f32_16x16x32_bf16 v[34:37], v[224:227], v[170:173], v[34:37]
	v_mfma_f32_16x16x32_bf16 v[22:25], v[212:215], v[174:177], v[22:25]
	v_mfma_f32_16x16x32_bf16 v[22:25], v[216:219], v[178:181], v[22:25]
	v_mfma_f32_16x16x32_bf16 v[18:21], v[220:223], v[174:177], v[18:21]
	v_mfma_f32_16x16x32_bf16 v[18:21], v[224:227], v[178:181], v[18:21]
	v_mfma_f32_16x16x32_bf16 v[6:9], v[212:215], v[182:185], v[6:9]
	v_mfma_f32_16x16x32_bf16 v[6:9], v[216:219], v[208:211], v[6:9]
	v_mfma_f32_16x16x32_bf16 v[2:5], v[220:223], v[182:185], v[2:5]
	v_mfma_f32_16x16x32_bf16 v[2:5], v[224:227], v[208:211], v[2:5]
	s_barrier
	s_cbranch_scc1 .Lkexit_347
.LBB0_347:
	s_add_i32 s15, s4, 2
	s_add_u32 s10, s0, 0x80
	s_addc_u32 s5, s1, 0
	s_add_i32 s16, 0, 0x10000
	ds_read_b128 v[130:133], v248
	ds_read_b128 v[134:137], v248 offset:1024
	ds_read_b128 v[138:141], v248 offset:2048
	ds_read_b128 v[142:145], v248 offset:3072
	s_cmp_eq_u32 s79, s4
	s_cselect_b32 s4, s44, s10
	s_cselect_b32 s5, s45, s5
	s_cselect_b32 s11, s47, s13
	s_cselect_b32 s10, s46, s12
	s_add_i32 m0, s71, 0xc000
	ds_read_b128 v[158:161], v206
	ds_read_b128 v[162:165], v206 offset:1024
	ds_read_b128 v[166:169], v206 offset:2048
	ds_read_b128 v[170:173], v206 offset:3072
	ds_read_b128 v[174:177], v206 offset:4096
	ds_read_b128 v[178:181], v206 offset:5120
	ds_read_b128 v[182:185], v206 offset:6144
	ds_read_b128 v[208:211], v206 offset:7168
	global_load_lds_dwordx4 v154, s[0:1]
	s_add_i32 m0, s71, 0xe000
	s_nop 0
	global_load_lds_dwordx4 v156, s[0:1]
	s_waitcnt lgkmcnt(8)
	s_barrier
	s_waitcnt lgkmcnt(0)
	v_mfma_f32_16x16x32_bf16 v[126:129], v[130:133], v[158:161], v[126:129]
	v_mfma_f32_16x16x32_bf16 v[126:129], v[134:137], v[162:165], v[126:129]
	v_mfma_f32_16x16x32_bf16 v[122:125], v[138:141], v[158:161], v[122:125]
	v_mfma_f32_16x16x32_bf16 v[122:125], v[142:145], v[162:165], v[122:125]
	v_mfma_f32_16x16x32_bf16 v[110:113], v[130:133], v[166:169], v[110:113]
	v_mfma_f32_16x16x32_bf16 v[110:113], v[134:137], v[170:173], v[110:113]
	v_mfma_f32_16x16x32_bf16 v[106:109], v[138:141], v[166:169], v[106:109]
	v_mfma_f32_16x16x32_bf16 v[106:109], v[142:145], v[170:173], v[106:109]
	v_mfma_f32_16x16x32_bf16 v[94:97], v[130:133], v[174:177], v[94:97]
	v_mfma_f32_16x16x32_bf16 v[94:97], v[134:137], v[178:181], v[94:97]
	v_mfma_f32_16x16x32_bf16 v[90:93], v[138:141], v[174:177], v[90:93]
	v_mfma_f32_16x16x32_bf16 v[90:93], v[142:145], v[178:181], v[90:93]
	v_mfma_f32_16x16x32_bf16 v[78:81], v[130:133], v[182:185], v[78:81]
	v_mfma_f32_16x16x32_bf16 v[78:81], v[134:137], v[208:211], v[78:81]
	v_mfma_f32_16x16x32_bf16 v[74:77], v[138:141], v[182:185], v[74:77]
	v_mfma_f32_16x16x32_bf16 v[74:77], v[142:145], v[208:211], v[74:77]
	s_barrier
	s_add_i32 s17, 0, 0x14000
	s_add_i32 s16, s16, s70
	s_add_u32 s2, s10, s6
	s_addc_u32 s3, s11, s7
	s_mov_b32 m0, s16
	ds_read_b128 v[212:215], v248 offset:16384
	ds_read_b128 v[216:219], v248 offset:17408
	ds_read_b128 v[220:223], v248 offset:18432
	ds_read_b128 v[224:227], v248 offset:19456
	global_load_lds_dwordx4 v148, s[10:11]
	s_add_i32 m0, s16, 0x2000
	s_nop 0
	global_load_lds_dwordx4 v152, s[10:11]
	s_barrier
	s_waitcnt lgkmcnt(0)
	v_mfma_f32_16x16x32_bf16 v[118:121], v[212:215], v[158:161], v[118:121]
	v_mfma_f32_16x16x32_bf16 v[118:121], v[216:219], v[162:165], v[118:121]
	v_mfma_f32_16x16x32_bf16 v[114:117], v[220:223], v[158:161], v[114:117]
	v_mfma_f32_16x16x32_bf16 v[114:117], v[224:227], v[162:165], v[114:117]
	v_mfma_f32_16x16x32_bf16 v[102:105], v[212:215], v[166:169], v[102:105]
	v_mfma_f32_16x16x32_bf16 v[102:105], v[216:219], v[170:173], v[102:105]
	v_mfma_f32_16x16x32_bf16 v[98:101], v[220:223], v[166:169], v[98:101]
	v_mfma_f32_16x16x32_bf16 v[98:101], v[224:227], v[170:173], v[98:101]
	v_mfma_f32_16x16x32_bf16 v[86:89], v[212:215], v[174:177], v[86:89]
	v_mfma_f32_16x16x32_bf16 v[86:89], v[216:219], v[178:181], v[86:89]
	v_mfma_f32_16x16x32_bf16 v[82:85], v[220:223], v[174:177], v[82:85]
	v_mfma_f32_16x16x32_bf16 v[82:85], v[224:227], v[178:181], v[82:85]
	v_mfma_f32_16x16x32_bf16 v[70:73], v[212:215], v[182:185], v[70:73]
	v_mfma_f32_16x16x32_bf16 v[70:73], v[216:219], v[208:211], v[70:73]
	v_mfma_f32_16x16x32_bf16 v[66:69], v[220:223], v[182:185], v[66:69]
	v_mfma_f32_16x16x32_bf16 v[66:69], v[224:227], v[208:211], v[66:69]
	s_barrier
	s_mov_b32 m0, s71
	s_add_u32 s98, s4, s6
	s_addc_u32 s99, s5, s7
	ds_read_b128 v[158:161], v206 offset:16384
	ds_read_b128 v[162:165], v206 offset:17408
	ds_read_b128 v[166:169], v206 offset:18432
	ds_read_b128 v[170:173], v206 offset:19456
	ds_read_b128 v[174:177], v206 offset:20480
	ds_read_b128 v[178:181], v206 offset:21504
	ds_read_b128 v[182:185], v206 offset:22528
	ds_read_b128 v[208:211], v206 offset:23552
	global_load_lds_dwordx4 v146, s[4:5]
	s_mov_b32 m0, s72
	s_nop 0
	global_load_lds_dwordx4 v150, s[4:5]
	s_barrier
	s_waitcnt lgkmcnt(0)
	v_mfma_f32_16x16x32_bf16 v[62:65], v[130:133], v[158:161], v[62:65]
	v_mfma_f32_16x16x32_bf16 v[62:65], v[134:137], v[162:165], v[62:65]
	v_mfma_f32_16x16x32_bf16 v[58:61], v[138:141], v[158:161], v[58:61]
	v_mfma_f32_16x16x32_bf16 v[58:61], v[142:145], v[162:165], v[58:61]
	v_mfma_f32_16x16x32_bf16 v[46:49], v[130:133], v[166:169], v[46:49]
	v_mfma_f32_16x16x32_bf16 v[46:49], v[134:137], v[170:173], v[46:49]
	v_mfma_f32_16x16x32_bf16 v[42:45], v[138:141], v[166:169], v[42:45]
	v_mfma_f32_16x16x32_bf16 v[42:45], v[142:145], v[170:173], v[42:45]
	v_mfma_f32_16x16x32_bf16 v[30:33], v[130:133], v[174:177], v[30:33]
	v_mfma_f32_16x16x32_bf16 v[30:33], v[134:137], v[178:181], v[30:33]
	v_mfma_f32_16x16x32_bf16 v[26:29], v[138:141], v[174:177], v[26:29]
	v_mfma_f32_16x16x32_bf16 v[26:29], v[142:145], v[178:181], v[26:29]
	v_mfma_f32_16x16x32_bf16 v[14:17], v[130:133], v[182:185], v[14:17]
	v_mfma_f32_16x16x32_bf16 v[14:17], v[134:137], v[208:211], v[14:17]
	v_mfma_f32_16x16x32_bf16 v[10:13], v[138:141], v[182:185], v[10:13]
	v_mfma_f32_16x16x32_bf16 v[10:13], v[142:145], v[208:211], v[10:13]
	s_barrier
	s_add_u32 s10, s10, s92
	s_addc_u32 s11, s11, 0
	s_add_i32 s16, s17, s70
	v_lshl_add_u64 v[236:237], s[10:11], 0, v[148:149]
	s_mov_b32 m0, s16
	v_lshl_add_u64 v[238:239], s[10:11], 0, v[152:153]
	global_load_lds_dwordx4 v[236:237], off
	s_add_i32 m0, s16, 0x2000
	s_nop 0
	global_load_lds_dwordx4 v[238:239], off
	s_waitcnt vmcnt(6)
	s_barrier
	v_mfma_f32_16x16x32_bf16 v[54:57], v[212:215], v[158:161], v[54:57]
	v_mfma_f32_16x16x32_bf16 v[54:57], v[216:219], v[162:165], v[54:57]
	v_mfma_f32_16x16x32_bf16 v[50:53], v[220:223], v[158:161], v[50:53]
	v_mfma_f32_16x16x32_bf16 v[50:53], v[224:227], v[162:165], v[50:53]
	v_mfma_f32_16x16x32_bf16 v[38:41], v[212:215], v[166:169], v[38:41]
	v_mfma_f32_16x16x32_bf16 v[38:41], v[216:219], v[170:173], v[38:41]
	v_mfma_f32_16x16x32_bf16 v[34:37], v[220:223], v[166:169], v[34:37]
	v_mfma_f32_16x16x32_bf16 v[34:37], v[224:227], v[170:173], v[34:37]
	v_mfma_f32_16x16x32_bf16 v[22:25], v[212:215], v[174:177], v[22:25]
	v_mfma_f32_16x16x32_bf16 v[22:25], v[216:219], v[178:181], v[22:25]
	v_mfma_f32_16x16x32_bf16 v[18:21], v[220:223], v[174:177], v[18:21]
	v_mfma_f32_16x16x32_bf16 v[18:21], v[224:227], v[178:181], v[18:21]
	v_mfma_f32_16x16x32_bf16 v[6:9], v[212:215], v[182:185], v[6:9]
	v_mfma_f32_16x16x32_bf16 v[6:9], v[216:219], v[208:211], v[6:9]
	v_mfma_f32_16x16x32_bf16 v[2:5], v[220:223], v[182:185], v[2:5]
	v_mfma_f32_16x16x32_bf16 v[2:5], v[224:227], v[208:211], v[2:5]
	s_barrier
	s_add_i32 s10, 0, 0x18000
	ds_read_b128 v[130:133], v248 offset:32768
	ds_read_b128 v[134:137], v248 offset:33792
	ds_read_b128 v[138:141], v248 offset:34816
	ds_read_b128 v[142:145], v248 offset:35840
	s_add_u32 s4, s4, s92
	s_addc_u32 s5, s5, 0
	s_mov_b32 m0, s73
	ds_read_b128 v[158:161], v206 offset:32768
	ds_read_b128 v[162:165], v206 offset:33792
	ds_read_b128 v[166:169], v206 offset:34816
	ds_read_b128 v[170:173], v206 offset:35840
	ds_read_b128 v[174:177], v206 offset:36864
	ds_read_b128 v[178:181], v206 offset:37888
	ds_read_b128 v[182:185], v206 offset:38912
	ds_read_b128 v[208:211], v206 offset:39936
	global_load_lds_dwordx4 v146, s[4:5]
	s_mov_b32 m0, s74
	s_nop 0
	global_load_lds_dwordx4 v150, s[4:5]
	s_waitcnt lgkmcnt(8)
	s_barrier
	s_waitcnt lgkmcnt(0)
	v_mfma_f32_16x16x32_bf16 v[126:129], v[130:133], v[158:161], v[126:129]
	v_mfma_f32_16x16x32_bf16 v[126:129], v[134:137], v[162:165], v[126:129]
	v_mfma_f32_16x16x32_bf16 v[122:125], v[138:141], v[158:161], v[122:125]
	v_mfma_f32_16x16x32_bf16 v[122:125], v[142:145], v[162:165], v[122:125]
	v_mfma_f32_16x16x32_bf16 v[110:113], v[130:133], v[166:169], v[110:113]
	v_mfma_f32_16x16x32_bf16 v[110:113], v[134:137], v[170:173], v[110:113]
	v_mfma_f32_16x16x32_bf16 v[106:109], v[138:141], v[166:169], v[106:109]
	v_mfma_f32_16x16x32_bf16 v[106:109], v[142:145], v[170:173], v[106:109]
	v_mfma_f32_16x16x32_bf16 v[94:97], v[130:133], v[174:177], v[94:97]
	v_mfma_f32_16x16x32_bf16 v[94:97], v[134:137], v[178:181], v[94:97]
	v_mfma_f32_16x16x32_bf16 v[90:93], v[138:141], v[174:177], v[90:93]
	v_mfma_f32_16x16x32_bf16 v[90:93], v[142:145], v[178:181], v[90:93]
	v_mfma_f32_16x16x32_bf16 v[78:81], v[130:133], v[182:185], v[78:81]
	v_mfma_f32_16x16x32_bf16 v[78:81], v[134:137], v[208:211], v[78:81]
	v_mfma_f32_16x16x32_bf16 v[74:77], v[138:141], v[182:185], v[74:77]
	v_mfma_f32_16x16x32_bf16 v[74:77], v[142:145], v[208:211], v[74:77]
	s_barrier
	s_add_i32 s4, 0, 0x1c000
	s_add_i32 s5, s10, s70
	s_mov_b32 m0, s5
	ds_read_b128 v[212:215], v248 offset:49152
	ds_read_b128 v[216:219], v248 offset:50176
	ds_read_b128 v[220:223], v248 offset:51200
	ds_read_b128 v[224:227], v248 offset:52224
	global_load_lds_dwordx4 v148, s[2:3]
	s_add_i32 m0, s5, 0x2000
	s_nop 0
	global_load_lds_dwordx4 v152, s[2:3]
	s_barrier
	s_waitcnt lgkmcnt(0)
	v_mfma_f32_16x16x32_bf16 v[118:121], v[212:215], v[158:161], v[118:121]
	v_mfma_f32_16x16x32_bf16 v[118:121], v[216:219], v[162:165], v[118:121]
	v_mfma_f32_16x16x32_bf16 v[114:117], v[220:223], v[158:161], v[114:117]
	v_mfma_f32_16x16x32_bf16 v[114:117], v[224:227], v[162:165], v[114:117]
	v_mfma_f32_16x16x32_bf16 v[102:105], v[212:215], v[166:169], v[102:105]
	v_mfma_f32_16x16x32_bf16 v[102:105], v[216:219], v[170:173], v[102:105]
	v_mfma_f32_16x16x32_bf16 v[98:101], v[220:223], v[166:169], v[98:101]
	v_mfma_f32_16x16x32_bf16 v[98:101], v[224:227], v[170:173], v[98:101]
	v_mfma_f32_16x16x32_bf16 v[86:89], v[212:215], v[174:177], v[86:89]
	v_mfma_f32_16x16x32_bf16 v[86:89], v[216:219], v[178:181], v[86:89]
	v_mfma_f32_16x16x32_bf16 v[82:85], v[220:223], v[174:177], v[82:85]
	v_mfma_f32_16x16x32_bf16 v[82:85], v[224:227], v[178:181], v[82:85]
	v_mfma_f32_16x16x32_bf16 v[70:73], v[212:215], v[182:185], v[70:73]
	v_mfma_f32_16x16x32_bf16 v[70:73], v[216:219], v[208:211], v[70:73]
	v_mfma_f32_16x16x32_bf16 v[66:69], v[220:223], v[182:185], v[66:69]
	v_mfma_f32_16x16x32_bf16 v[66:69], v[224:227], v[208:211], v[66:69]
	s_barrier
	s_mov_b32 m0, s77
	ds_read_b128 v[158:161], v206 offset:49152
	ds_read_b128 v[162:165], v206 offset:50176
	ds_read_b128 v[166:169], v206 offset:51200
	ds_read_b128 v[170:173], v206 offset:52224
	ds_read_b128 v[174:177], v206 offset:53248
	ds_read_b128 v[178:181], v206 offset:54272
	ds_read_b128 v[182:185], v206 offset:55296
	ds_read_b128 v[208:211], v206 offset:56320
	global_load_lds_dwordx4 v146, s[98:99]
	s_mov_b32 m0, s78
	s_nop 0
	global_load_lds_dwordx4 v150, s[98:99]
	s_barrier
	s_waitcnt lgkmcnt(0)
	v_mfma_f32_16x16x32_bf16 v[62:65], v[130:133], v[158:161], v[62:65]
	v_mfma_f32_16x16x32_bf16 v[62:65], v[134:137], v[162:165], v[62:65]
	v_mfma_f32_16x16x32_bf16 v[58:61], v[138:141], v[158:161], v[58:61]
	v_mfma_f32_16x16x32_bf16 v[58:61], v[142:145], v[162:165], v[58:61]
	v_mfma_f32_16x16x32_bf16 v[46:49], v[130:133], v[166:169], v[46:49]
	v_mfma_f32_16x16x32_bf16 v[46:49], v[134:137], v[170:173], v[46:49]
	v_mfma_f32_16x16x32_bf16 v[42:45], v[138:141], v[166:169], v[42:45]
	v_mfma_f32_16x16x32_bf16 v[42:45], v[142:145], v[170:173], v[42:45]
	v_mfma_f32_16x16x32_bf16 v[30:33], v[130:133], v[174:177], v[30:33]
	v_mfma_f32_16x16x32_bf16 v[30:33], v[134:137], v[178:181], v[30:33]
	v_mfma_f32_16x16x32_bf16 v[26:29], v[138:141], v[174:177], v[26:29]
	v_mfma_f32_16x16x32_bf16 v[26:29], v[142:145], v[178:181], v[26:29]
	v_mfma_f32_16x16x32_bf16 v[14:17], v[130:133], v[182:185], v[14:17]
	v_mfma_f32_16x16x32_bf16 v[14:17], v[134:137], v[208:211], v[14:17]
	v_mfma_f32_16x16x32_bf16 v[10:13], v[138:141], v[182:185], v[10:13]
	v_mfma_f32_16x16x32_bf16 v[10:13], v[142:145], v[208:211], v[10:13]
	s_barrier
	s_add_i32 s4, s4, s70
	v_lshl_add_u64 v[130:131], v[236:237], 0, s[6:7]
	s_mov_b32 m0, s4
	s_nop 0
	global_load_lds_dwordx4 v[130:131], off
	v_lshl_add_u64 v[130:131], v[238:239], 0, s[6:7]
	s_add_i32 m0, s4, 0x2000
	s_nop 0
	global_load_lds_dwordx4 v[130:131], off
	s_add_u32 s0, s0, 0x100
	s_addc_u32 s1, s1, 0
	s_add_u32 s12, s12, 0x100
	s_addc_u32 s13, s13, 0
	s_cmp_ge_u32 s15, s75
	s_mov_b32 s4, s15
	s_waitcnt vmcnt(6)
	s_barrier
	v_mfma_f32_16x16x32_bf16 v[54:57], v[212:215], v[158:161], v[54:57]
	v_mfma_f32_16x16x32_bf16 v[54:57], v[216:219], v[162:165], v[54:57]
	v_mfma_f32_16x16x32_bf16 v[50:53], v[220:223], v[158:161], v[50:53]
	v_mfma_f32_16x16x32_bf16 v[50:53], v[224:227], v[162:165], v[50:53]
	v_mfma_f32_16x16x32_bf16 v[38:41], v[212:215], v[166:169], v[38:41]
	v_mfma_f32_16x16x32_bf16 v[38:41], v[216:219], v[170:173], v[38:41]
	v_mfma_f32_16x16x32_bf16 v[34:37], v[220:223], v[166:169], v[34:37]
	v_mfma_f32_16x16x32_bf16 v[34:37], v[224:227], v[170:173], v[34:37]
	v_mfma_f32_16x16x32_bf16 v[22:25], v[212:215], v[174:177], v[22:25]
	v_mfma_f32_16x16x32_bf16 v[22:25], v[216:219], v[178:181], v[22:25]
	v_mfma_f32_16x16x32_bf16 v[18:21], v[220:223], v[174:177], v[18:21]
	v_mfma_f32_16x16x32_bf16 v[18:21], v[224:227], v[178:181], v[18:21]
	v_mfma_f32_16x16x32_bf16 v[6:9], v[212:215], v[182:185], v[6:9]
	v_mfma_f32_16x16x32_bf16 v[6:9], v[216:219], v[208:211], v[6:9]
	v_mfma_f32_16x16x32_bf16 v[2:5], v[220:223], v[182:185], v[2:5]
	v_mfma_f32_16x16x32_bf16 v[2:5], v[224:227], v[208:211], v[2:5]
	s_barrier
	s_cbranch_scc0 .LBB0_347

.LBB0_663:
	s_add_u32 s0, s0, 0x80
	s_addc_u32 s1, s1, 0
	s_add_u32 s49, s4, 0x100
	s_addc_u32 s65, s5, 0
	s_mov_b32 s4, 0
	s_waitcnt lgkmcnt(0)
	s_waitcnt vmcnt(0)
	s_add_i32 s66, s4, 2
	s_add_u32 s18, s0, 0x80
	s_addc_u32 s5, s1, 0
	s_add_i32 s68, 0, 0x10000
	ds_read_b128 v[142:145], v248
	ds_read_b128 v[146:149], v248 offset:1024
	ds_read_b128 v[156:159], v248 offset:2048
	ds_read_b128 v[160:163], v248 offset:3072
	s_cmp_eq_u32 s43, s4
	s_cselect_b32 s4, s10, s18
	s_cselect_b32 s5, s11, s5
	s_cselect_b32 s19, s13, s65
	s_cselect_b32 s18, s12, s49
	s_add_i32 m0, s28, 0xc000
	ds_read_b128 v[164:167], v154
	ds_read_b128 v[168:171], v154 offset:1024
	ds_read_b128 v[172:175], v154 offset:2048
	ds_read_b128 v[176:179], v154 offset:3072
	ds_read_b128 v[180:183], v154 offset:4096
	ds_read_b128 v[204:207], v154 offset:5120
	ds_read_b128 v[208:211], v154 offset:6144
	ds_read_b128 v[212:215], v154 offset:7168
	global_load_lds_dwordx4 v138, s[0:1]
	s_add_i32 m0, s28, 0xe000
	s_nop 0
	global_load_lds_dwordx4 v140, s[0:1]
	s_waitcnt lgkmcnt(8)
	s_barrier
	s_waitcnt lgkmcnt(0)
	v_mfma_f32_16x16x32_bf16 v[126:129], v[142:145], v[164:167], 0
	v_mfma_f32_16x16x32_bf16 v[126:129], v[146:149], v[168:171], v[126:129]
	v_mfma_f32_16x16x32_bf16 v[122:125], v[156:159], v[164:167], 0
	v_mfma_f32_16x16x32_bf16 v[122:125], v[160:163], v[168:171], v[122:125]
	v_mfma_f32_16x16x32_bf16 v[110:113], v[142:145], v[172:175], 0
	v_mfma_f32_16x16x32_bf16 v[110:113], v[146:149], v[176:179], v[110:113]
	v_mfma_f32_16x16x32_bf16 v[106:109], v[156:159], v[172:175], 0
	v_mfma_f32_16x16x32_bf16 v[106:109], v[160:163], v[176:179], v[106:109]
	v_mfma_f32_16x16x32_bf16 v[94:97], v[142:145], v[180:183], 0
	v_mfma_f32_16x16x32_bf16 v[94:97], v[146:149], v[204:207], v[94:97]
	v_mfma_f32_16x16x32_bf16 v[90:93], v[156:159], v[180:183], 0
	v_mfma_f32_16x16x32_bf16 v[90:93], v[160:163], v[204:207], v[90:93]
	v_mfma_f32_16x16x32_bf16 v[78:81], v[142:145], v[208:211], 0
	v_mfma_f32_16x16x32_bf16 v[78:81], v[146:149], v[212:215], v[78:81]
	v_mfma_f32_16x16x32_bf16 v[74:77], v[156:159], v[208:211], 0
	v_mfma_f32_16x16x32_bf16 v[74:77], v[160:163], v[212:215], v[74:77]
	s_barrier
	s_add_i32 s69, 0, 0x14000
	s_add_i32 s68, s68, s25
	ds_read_b128 v[216:219], v248 offset:16384
	ds_read_b128 v[220:223], v248 offset:17408
	ds_read_b128 v[224:227], v248 offset:18432
	ds_read_b128 v[228:231], v248 offset:19456
	s_add_u32 s70, s18, s6
	s_addc_u32 s71, s19, s7
	s_mov_b32 m0, s68
	s_nop 0
	global_load_lds_dwordx4 v132, s[18:19]
	s_add_i32 m0, s68, 0x2000
	s_nop 0
	global_load_lds_dwordx4 v136, s[18:19]
	s_barrier
	s_waitcnt lgkmcnt(0)
	v_mfma_f32_16x16x32_bf16 v[118:121], v[216:219], v[164:167], 0
	v_mfma_f32_16x16x32_bf16 v[118:121], v[220:223], v[168:171], v[118:121]
	v_mfma_f32_16x16x32_bf16 v[114:117], v[224:227], v[164:167], 0
	v_mfma_f32_16x16x32_bf16 v[114:117], v[228:231], v[168:171], v[114:117]
	v_mfma_f32_16x16x32_bf16 v[102:105], v[216:219], v[172:175], 0
	v_mfma_f32_16x16x32_bf16 v[102:105], v[220:223], v[176:179], v[102:105]
	v_mfma_f32_16x16x32_bf16 v[98:101], v[224:227], v[172:175], 0
	v_mfma_f32_16x16x32_bf16 v[98:101], v[228:231], v[176:179], v[98:101]
	v_mfma_f32_16x16x32_bf16 v[86:89], v[216:219], v[180:183], 0
	v_mfma_f32_16x16x32_bf16 v[86:89], v[220:223], v[204:207], v[86:89]
	v_mfma_f32_16x16x32_bf16 v[82:85], v[224:227], v[180:183], 0
	v_mfma_f32_16x16x32_bf16 v[82:85], v[228:231], v[204:207], v[82:85]
	v_mfma_f32_16x16x32_bf16 v[70:73], v[216:219], v[208:211], 0
	v_mfma_f32_16x16x32_bf16 v[70:73], v[220:223], v[212:215], v[70:73]
	v_mfma_f32_16x16x32_bf16 v[66:69], v[224:227], v[208:211], 0
	v_mfma_f32_16x16x32_bf16 v[66:69], v[228:231], v[212:215], v[66:69]
	s_barrier
	s_mov_b32 m0, s28
	s_add_u32 s72, s4, s6
	s_addc_u32 s73, s5, s7
	ds_read_b128 v[164:167], v154 offset:16384
	ds_read_b128 v[168:171], v154 offset:17408
	ds_read_b128 v[172:175], v154 offset:18432
	ds_read_b128 v[176:179], v154 offset:19456
	ds_read_b128 v[180:183], v154 offset:20480
	ds_read_b128 v[204:207], v154 offset:21504
	ds_read_b128 v[208:211], v154 offset:22528
	ds_read_b128 v[212:215], v154 offset:23552
	global_load_lds_dwordx4 v130, s[4:5]
	s_mov_b32 m0, s29
	s_nop 0
	global_load_lds_dwordx4 v134, s[4:5]
	s_barrier
	s_waitcnt lgkmcnt(0)
	v_mfma_f32_16x16x32_bf16 v[62:65], v[142:145], v[164:167], 0
	v_mfma_f32_16x16x32_bf16 v[62:65], v[146:149], v[168:171], v[62:65]
	v_mfma_f32_16x16x32_bf16 v[58:61], v[156:159], v[164:167], 0
	v_mfma_f32_16x16x32_bf16 v[58:61], v[160:163], v[168:171], v[58:61]
	v_mfma_f32_16x16x32_bf16 v[46:49], v[142:145], v[172:175], 0
	v_mfma_f32_16x16x32_bf16 v[46:49], v[146:149], v[176:179], v[46:49]
	v_mfma_f32_16x16x32_bf16 v[42:45], v[156:159], v[172:175], 0
	v_mfma_f32_16x16x32_bf16 v[42:45], v[160:163], v[176:179], v[42:45]
	v_mfma_f32_16x16x32_bf16 v[30:33], v[142:145], v[180:183], 0
	v_mfma_f32_16x16x32_bf16 v[30:33], v[146:149], v[204:207], v[30:33]
	v_mfma_f32_16x16x32_bf16 v[26:29], v[156:159], v[180:183], 0
	v_mfma_f32_16x16x32_bf16 v[26:29], v[160:163], v[204:207], v[26:29]
	v_mfma_f32_16x16x32_bf16 v[14:17], v[142:145], v[208:211], 0
	v_mfma_f32_16x16x32_bf16 v[14:17], v[146:149], v[212:215], v[14:17]
	v_mfma_f32_16x16x32_bf16 v[10:13], v[156:159], v[208:211], 0
	v_mfma_f32_16x16x32_bf16 v[10:13], v[160:163], v[212:215], v[10:13]
	s_barrier
	s_add_u32 s18, s18, s14
	s_addc_u32 s19, s19, 0
	s_add_i32 s68, s69, s25
	s_add_u32 s76, s18, s6
	s_addc_u32 s77, s19, s7
	s_mov_b32 m0, s68
	s_nop 0
	global_load_lds_dwordx4 v132, s[18:19]
	s_add_i32 m0, s68, 0x2000
	s_nop 0
	global_load_lds_dwordx4 v136, s[18:19]
	s_waitcnt vmcnt(6)
	s_barrier
	v_mfma_f32_16x16x32_bf16 v[54:57], v[216:219], v[164:167], 0
	v_mfma_f32_16x16x32_bf16 v[54:57], v[220:223], v[168:171], v[54:57]
	v_mfma_f32_16x16x32_bf16 v[50:53], v[224:227], v[164:167], 0
	v_mfma_f32_16x16x32_bf16 v[50:53], v[228:231], v[168:171], v[50:53]
	v_mfma_f32_16x16x32_bf16 v[38:41], v[216:219], v[172:175], 0
	v_mfma_f32_16x16x32_bf16 v[38:41], v[220:223], v[176:179], v[38:41]
	v_mfma_f32_16x16x32_bf16 v[34:37], v[224:227], v[172:175], 0
	v_mfma_f32_16x16x32_bf16 v[34:37], v[228:231], v[176:179], v[34:37]
	v_mfma_f32_16x16x32_bf16 v[22:25], v[216:219], v[180:183], 0
	v_mfma_f32_16x16x32_bf16 v[22:25], v[220:223], v[204:207], v[22:25]
	v_mfma_f32_16x16x32_bf16 v[18:21], v[224:227], v[180:183], 0
	v_mfma_f32_16x16x32_bf16 v[18:21], v[228:231], v[204:207], v[18:21]
	v_mfma_f32_16x16x32_bf16 v[6:9], v[216:219], v[208:211], 0
	v_mfma_f32_16x16x32_bf16 v[6:9], v[220:223], v[212:215], v[6:9]
	v_mfma_f32_16x16x32_bf16 v[2:5], v[224:227], v[208:211], 0
	v_mfma_f32_16x16x32_bf16 v[2:5], v[228:231], v[212:215], v[2:5]
	s_barrier
	s_add_i32 s18, 0, 0x18000
	ds_read_b128 v[142:145], v248 offset:32768
	ds_read_b128 v[146:149], v248 offset:33792
	ds_read_b128 v[156:159], v248 offset:34816
	ds_read_b128 v[160:163], v248 offset:35840
	s_add_u32 s4, s4, s14
	s_addc_u32 s5, s5, 0
	s_mov_b32 m0, s31
	ds_read_b128 v[164:167], v154 offset:32768
	ds_read_b128 v[168:171], v154 offset:33792
	ds_read_b128 v[172:175], v154 offset:34816
	ds_read_b128 v[176:179], v154 offset:35840
	ds_read_b128 v[180:183], v154 offset:36864
	ds_read_b128 v[204:207], v154 offset:37888
	ds_read_b128 v[208:211], v154 offset:38912
	ds_read_b128 v[212:215], v154 offset:39936
	global_load_lds_dwordx4 v130, s[4:5]
	s_mov_b32 m0, s34
	s_nop 0
	global_load_lds_dwordx4 v134, s[4:5]
	s_waitcnt lgkmcnt(8)
	s_barrier
	s_waitcnt lgkmcnt(0)
	v_mfma_f32_16x16x32_bf16 v[126:129], v[142:145], v[164:167], v[126:129]
	v_mfma_f32_16x16x32_bf16 v[126:129], v[146:149], v[168:171], v[126:129]
	v_mfma_f32_16x16x32_bf16 v[122:125], v[156:159], v[164:167], v[122:125]
	v_mfma_f32_16x16x32_bf16 v[122:125], v[160:163], v[168:171], v[122:125]
	v_mfma_f32_16x16x32_bf16 v[110:113], v[142:145], v[172:175], v[110:113]
	v_mfma_f32_16x16x32_bf16 v[110:113], v[146:149], v[176:179], v[110:113]
	v_mfma_f32_16x16x32_bf16 v[106:109], v[156:159], v[172:175], v[106:109]
	v_mfma_f32_16x16x32_bf16 v[106:109], v[160:163], v[176:179], v[106:109]
	v_mfma_f32_16x16x32_bf16 v[94:97], v[142:145], v[180:183], v[94:97]
	v_mfma_f32_16x16x32_bf16 v[94:97], v[146:149], v[204:207], v[94:97]
	v_mfma_f32_16x16x32_bf16 v[90:93], v[156:159], v[180:183], v[90:93]
	v_mfma_f32_16x16x32_bf16 v[90:93], v[160:163], v[204:207], v[90:93]
	v_mfma_f32_16x16x32_bf16 v[78:81], v[142:145], v[208:211], v[78:81]
	v_mfma_f32_16x16x32_bf16 v[78:81], v[146:149], v[212:215], v[78:81]
	v_mfma_f32_16x16x32_bf16 v[74:77], v[156:159], v[208:211], v[74:77]
	v_mfma_f32_16x16x32_bf16 v[74:77], v[160:163], v[212:215], v[74:77]
	s_barrier
	s_add_i32 s4, 0, 0x1c000
	s_add_i32 s5, s18, s25
	s_mov_b32 m0, s5
	ds_read_b128 v[216:219], v248 offset:49152
	ds_read_b128 v[220:223], v248 offset:50176
	ds_read_b128 v[224:227], v248 offset:51200
	ds_read_b128 v[228:231], v248 offset:52224
	global_load_lds_dwordx4 v132, s[70:71]
	s_add_i32 m0, s5, 0x2000
	s_nop 0
	global_load_lds_dwordx4 v136, s[70:71]
	s_barrier
	s_waitcnt lgkmcnt(0)
	v_mfma_f32_16x16x32_bf16 v[118:121], v[216:219], v[164:167], v[118:121]
	v_mfma_f32_16x16x32_bf16 v[118:121], v[220:223], v[168:171], v[118:121]
	v_mfma_f32_16x16x32_bf16 v[114:117], v[224:227], v[164:167], v[114:117]
	v_mfma_f32_16x16x32_bf16 v[114:117], v[228:231], v[168:171], v[114:117]
	v_mfma_f32_16x16x32_bf16 v[102:105], v[216:219], v[172:175], v[102:105]
	v_mfma_f32_16x16x32_bf16 v[102:105], v[220:223], v[176:179], v[102:105]
	v_mfma_f32_16x16x32_bf16 v[98:101], v[224:227], v[172:175], v[98:101]
	v_mfma_f32_16x16x32_bf16 v[98:101], v[228:231], v[176:179], v[98:101]
	v_mfma_f32_16x16x32_bf16 v[86:89], v[216:219], v[180:183], v[86:89]
	v_mfma_f32_16x16x32_bf16 v[86:89], v[220:223], v[204:207], v[86:89]
	v_mfma_f32_16x16x32_bf16 v[82:85], v[224:227], v[180:183], v[82:85]
	v_mfma_f32_16x16x32_bf16 v[82:85], v[228:231], v[204:207], v[82:85]
	v_mfma_f32_16x16x32_bf16 v[70:73], v[216:219], v[208:211], v[70:73]
	v_mfma_f32_16x16x32_bf16 v[70:73], v[220:223], v[212:215], v[70:73]
	v_mfma_f32_16x16x32_bf16 v[66:69], v[224:227], v[208:211], v[66:69]
	v_mfma_f32_16x16x32_bf16 v[66:69], v[228:231], v[212:215], v[66:69]
	s_barrier
	s_mov_b32 m0, s41
	ds_read_b128 v[164:167], v154 offset:49152
	ds_read_b128 v[168:171], v154 offset:50176
	ds_read_b128 v[172:175], v154 offset:51200
	ds_read_b128 v[176:179], v154 offset:52224
	ds_read_b128 v[180:183], v154 offset:53248
	ds_read_b128 v[204:207], v154 offset:54272
	ds_read_b128 v[208:211], v154 offset:55296
	ds_read_b128 v[212:215], v154 offset:56320
	global_load_lds_dwordx4 v130, s[72:73]
	s_mov_b32 m0, s42
	s_nop 0
	global_load_lds_dwordx4 v134, s[72:73]
	s_barrier
	s_waitcnt lgkmcnt(0)
	v_mfma_f32_16x16x32_bf16 v[62:65], v[142:145], v[164:167], v[62:65]
	v_mfma_f32_16x16x32_bf16 v[62:65], v[146:149], v[168:171], v[62:65]
	v_mfma_f32_16x16x32_bf16 v[58:61], v[156:159], v[164:167], v[58:61]
	v_mfma_f32_16x16x32_bf16 v[58:61], v[160:163], v[168:171], v[58:61]
	v_mfma_f32_16x16x32_bf16 v[46:49], v[142:145], v[172:175], v[46:49]
	v_mfma_f32_16x16x32_bf16 v[46:49], v[146:149], v[176:179], v[46:49]
	v_mfma_f32_16x16x32_bf16 v[42:45], v[156:159], v[172:175], v[42:45]
	v_mfma_f32_16x16x32_bf16 v[42:45], v[160:163], v[176:179], v[42:45]
	v_mfma_f32_16x16x32_bf16 v[30:33], v[142:145], v[180:183], v[30:33]
	v_mfma_f32_16x16x32_bf16 v[30:33], v[146:149], v[204:207], v[30:33]
	v_mfma_f32_16x16x32_bf16 v[26:29], v[156:159], v[180:183], v[26:29]
	v_mfma_f32_16x16x32_bf16 v[26:29], v[160:163], v[204:207], v[26:29]
	v_mfma_f32_16x16x32_bf16 v[14:17], v[142:145], v[208:211], v[14:17]
	v_mfma_f32_16x16x32_bf16 v[14:17], v[146:149], v[212:215], v[14:17]
	v_mfma_f32_16x16x32_bf16 v[10:13], v[156:159], v[208:211], v[10:13]
	v_mfma_f32_16x16x32_bf16 v[10:13], v[160:163], v[212:215], v[10:13]
	s_barrier
	s_add_i32 s4, s4, s25
	s_mov_b32 m0, s4
	s_nop 0
	global_load_lds_dwordx4 v132, s[76:77]
	s_add_i32 m0, s4, 0x2000
	s_nop 0
	global_load_lds_dwordx4 v136, s[76:77]
	s_add_u32 s0, s0, 0x100
	s_addc_u32 s1, s1, 0
	s_add_u32 s49, s49, 0x100
	s_addc_u32 s65, s65, 0
	s_cmp_ge_u32 s66, s35
	s_mov_b32 s4, s66
	s_waitcnt vmcnt(6)
	s_barrier
	v_mfma_f32_16x16x32_bf16 v[54:57], v[216:219], v[164:167], v[54:57]
	v_mfma_f32_16x16x32_bf16 v[54:57], v[220:223], v[168:171], v[54:57]
	v_mfma_f32_16x16x32_bf16 v[50:53], v[224:227], v[164:167], v[50:53]
	v_mfma_f32_16x16x32_bf16 v[50:53], v[228:231], v[168:171], v[50:53]
	v_mfma_f32_16x16x32_bf16 v[38:41], v[216:219], v[172:175], v[38:41]
	v_mfma_f32_16x16x32_bf16 v[38:41], v[220:223], v[176:179], v[38:41]
	v_mfma_f32_16x16x32_bf16 v[34:37], v[224:227], v[172:175], v[34:37]
	v_mfma_f32_16x16x32_bf16 v[34:37], v[228:231], v[176:179], v[34:37]
	v_mfma_f32_16x16x32_bf16 v[22:25], v[216:219], v[180:183], v[22:25]
	v_mfma_f32_16x16x32_bf16 v[22:25], v[220:223], v[204:207], v[22:25]
	v_mfma_f32_16x16x32_bf16 v[18:21], v[224:227], v[180:183], v[18:21]
	v_mfma_f32_16x16x32_bf16 v[18:21], v[228:231], v[204:207], v[18:21]
	v_mfma_f32_16x16x32_bf16 v[6:9], v[216:219], v[208:211], v[6:9]
	v_mfma_f32_16x16x32_bf16 v[6:9], v[220:223], v[212:215], v[6:9]
	v_mfma_f32_16x16x32_bf16 v[2:5], v[224:227], v[208:211], v[2:5]
	v_mfma_f32_16x16x32_bf16 v[2:5], v[228:231], v[212:215], v[2:5]
	s_barrier
	s_cbranch_scc1 .Lkexit_664
.LBB0_664:
	s_add_i32 s66, s4, 2
	s_add_u32 s18, s0, 0x80
	s_addc_u32 s5, s1, 0
	s_add_i32 s68, 0, 0x10000
	ds_read_b128 v[142:145], v248
	ds_read_b128 v[146:149], v248 offset:1024
	ds_read_b128 v[156:159], v248 offset:2048
	ds_read_b128 v[160:163], v248 offset:3072
	s_cmp_eq_u32 s43, s4
	s_cselect_b32 s4, s10, s18
	s_cselect_b32 s5, s11, s5
	s_cselect_b32 s19, s13, s65
	s_cselect_b32 s18, s12, s49
	s_add_i32 m0, s28, 0xc000
	ds_read_b128 v[164:167], v154
	ds_read_b128 v[168:171], v154 offset:1024
	ds_read_b128 v[172:175], v154 offset:2048
	ds_read_b128 v[176:179], v154 offset:3072
	ds_read_b128 v[180:183], v154 offset:4096
	ds_read_b128 v[204:207], v154 offset:5120
	ds_read_b128 v[208:211], v154 offset:6144
	ds_read_b128 v[212:215], v154 offset:7168
	global_load_lds_dwordx4 v138, s[0:1]
	s_add_i32 m0, s28, 0xe000
	s_nop 0
	global_load_lds_dwordx4 v140, s[0:1]
	s_waitcnt lgkmcnt(8)
	s_barrier
	s_waitcnt lgkmcnt(0)
	v_mfma_f32_16x16x32_bf16 v[126:129], v[142:145], v[164:167], v[126:129]
	v_mfma_f32_16x16x32_bf16 v[126:129], v[146:149], v[168:171], v[126:129]
	v_mfma_f32_16x16x32_bf16 v[122:125], v[156:159], v[164:167], v[122:125]
	v_mfma_f32_16x16x32_bf16 v[122:125], v[160:163], v[168:171], v[122:125]
	v_mfma_f32_16x16x32_bf16 v[110:113], v[142:145], v[172:175], v[110:113]
	v_mfma_f32_16x16x32_bf16 v[110:113], v[146:149], v[176:179], v[110:113]
	v_mfma_f32_16x16x32_bf16 v[106:109], v[156:159], v[172:175], v[106:109]
	v_mfma_f32_16x16x32_bf16 v[106:109], v[160:163], v[176:179], v[106:109]
	v_mfma_f32_16x16x32_bf16 v[94:97], v[142:145], v[180:183], v[94:97]
	v_mfma_f32_16x16x32_bf16 v[94:97], v[146:149], v[204:207], v[94:97]
	v_mfma_f32_16x16x32_bf16 v[90:93], v[156:159], v[180:183], v[90:93]
	v_mfma_f32_16x16x32_bf16 v[90:93], v[160:163], v[204:207], v[90:93]
	v_mfma_f32_16x16x32_bf16 v[78:81], v[142:145], v[208:211], v[78:81]
	v_mfma_f32_16x16x32_bf16 v[78:81], v[146:149], v[212:215], v[78:81]
	v_mfma_f32_16x16x32_bf16 v[74:77], v[156:159], v[208:211], v[74:77]
	v_mfma_f32_16x16x32_bf16 v[74:77], v[160:163], v[212:215], v[74:77]
	s_barrier
	s_add_i32 s69, 0, 0x14000
	s_add_i32 s68, s68, s25
	ds_read_b128 v[216:219], v248 offset:16384
	ds_read_b128 v[220:223], v248 offset:17408
	ds_read_b128 v[224:227], v248 offset:18432
	ds_read_b128 v[228:231], v248 offset:19456
	s_add_u32 s70, s18, s6
	s_addc_u32 s71, s19, s7
	s_mov_b32 m0, s68
	s_nop 0
	global_load_lds_dwordx4 v132, s[18:19]
	s_add_i32 m0, s68, 0x2000
	s_nop 0
	global_load_lds_dwordx4 v136, s[18:19]
	s_barrier
	s_waitcnt lgkmcnt(0)
	v_mfma_f32_16x16x32_bf16 v[118:121], v[216:219], v[164:167], v[118:121]
	v_mfma_f32_16x16x32_bf16 v[118:121], v[220:223], v[168:171], v[118:121]
	v_mfma_f32_16x16x32_bf16 v[114:117], v[224:227], v[164:167], v[114:117]
	v_mfma_f32_16x16x32_bf16 v[114:117], v[228:231], v[168:171], v[114:117]
	v_mfma_f32_16x16x32_bf16 v[102:105], v[216:219], v[172:175], v[102:105]
	v_mfma_f32_16x16x32_bf16 v[102:105], v[220:223], v[176:179], v[102:105]
	v_mfma_f32_16x16x32_bf16 v[98:101], v[224:227], v[172:175], v[98:101]
	v_mfma_f32_16x16x32_bf16 v[98:101], v[228:231], v[176:179], v[98:101]
	v_mfma_f32_16x16x32_bf16 v[86:89], v[216:219], v[180:183], v[86:89]
	v_mfma_f32_16x16x32_bf16 v[86:89], v[220:223], v[204:207], v[86:89]
	v_mfma_f32_16x16x32_bf16 v[82:85], v[224:227], v[180:183], v[82:85]
	v_mfma_f32_16x16x32_bf16 v[82:85], v[228:231], v[204:207], v[82:85]
	v_mfma_f32_16x16x32_bf16 v[70:73], v[216:219], v[208:211], v[70:73]
	v_mfma_f32_16x16x32_bf16 v[70:73], v[220:223], v[212:215], v[70:73]
	v_mfma_f32_16x16x32_bf16 v[66:69], v[224:227], v[208:211], v[66:69]
	v_mfma_f32_16x16x32_bf16 v[66:69], v[228:231], v[212:215], v[66:69]
	s_barrier
	s_mov_b32 m0, s28
	s_add_u32 s72, s4, s6
	s_addc_u32 s73, s5, s7
	ds_read_b128 v[164:167], v154 offset:16384
	ds_read_b128 v[168:171], v154 offset:17408
	ds_read_b128 v[172:175], v154 offset:18432
	ds_read_b128 v[176:179], v154 offset:19456
	ds_read_b128 v[180:183], v154 offset:20480
	ds_read_b128 v[204:207], v154 offset:21504
	ds_read_b128 v[208:211], v154 offset:22528
	ds_read_b128 v[212:215], v154 offset:23552
	global_load_lds_dwordx4 v130, s[4:5]
	s_mov_b32 m0, s29
	s_nop 0
	global_load_lds_dwordx4 v134, s[4:5]
	s_barrier
	s_waitcnt lgkmcnt(0)
	v_mfma_f32_16x16x32_bf16 v[62:65], v[142:145], v[164:167], v[62:65]
	v_mfma_f32_16x16x32_bf16 v[62:65], v[146:149], v[168:171], v[62:65]
	v_mfma_f32_16x16x32_bf16 v[58:61], v[156:159], v[164:167], v[58:61]
	v_mfma_f32_16x16x32_bf16 v[58:61], v[160:163], v[168:171], v[58:61]
	v_mfma_f32_16x16x32_bf16 v[46:49], v[142:145], v[172:175], v[46:49]
	v_mfma_f32_16x16x32_bf16 v[46:49], v[146:149], v[176:179], v[46:49]
	v_mfma_f32_16x16x32_bf16 v[42:45], v[156:159], v[172:175], v[42:45]
	v_mfma_f32_16x16x32_bf16 v[42:45], v[160:163], v[176:179], v[42:45]
	v_mfma_f32_16x16x32_bf16 v[30:33], v[142:145], v[180:183], v[30:33]
	v_mfma_f32_16x16x32_bf16 v[30:33], v[146:149], v[204:207], v[30:33]
	v_mfma_f32_16x16x32_bf16 v[26:29], v[156:159], v[180:183], v[26:29]
	v_mfma_f32_16x16x32_bf16 v[26:29], v[160:163], v[204:207], v[26:29]
	v_mfma_f32_16x16x32_bf16 v[14:17], v[142:145], v[208:211], v[14:17]
	v_mfma_f32_16x16x32_bf16 v[14:17], v[146:149], v[212:215], v[14:17]
	v_mfma_f32_16x16x32_bf16 v[10:13], v[156:159], v[208:211], v[10:13]
	v_mfma_f32_16x16x32_bf16 v[10:13], v[160:163], v[212:215], v[10:13]
	s_barrier
	s_add_u32 s18, s18, s14
	s_addc_u32 s19, s19, 0
	s_add_i32 s68, s69, s25
	s_add_u32 s76, s18, s6
	s_addc_u32 s77, s19, s7
	s_mov_b32 m0, s68
	s_nop 0
	global_load_lds_dwordx4 v132, s[18:19]
	s_add_i32 m0, s68, 0x2000
	s_nop 0
	global_load_lds_dwordx4 v136, s[18:19]
	s_waitcnt vmcnt(6)
	s_barrier
	v_mfma_f32_16x16x32_bf16 v[54:57], v[216:219], v[164:167], v[54:57]
	v_mfma_f32_16x16x32_bf16 v[54:57], v[220:223], v[168:171], v[54:57]
	v_mfma_f32_16x16x32_bf16 v[50:53], v[224:227], v[164:167], v[50:53]
	v_mfma_f32_16x16x32_bf16 v[50:53], v[228:231], v[168:171], v[50:53]
	v_mfma_f32_16x16x32_bf16 v[38:41], v[216:219], v[172:175], v[38:41]
	v_mfma_f32_16x16x32_bf16 v[38:41], v[220:223], v[176:179], v[38:41]
	v_mfma_f32_16x16x32_bf16 v[34:37], v[224:227], v[172:175], v[34:37]
	v_mfma_f32_16x16x32_bf16 v[34:37], v[228:231], v[176:179], v[34:37]
	v_mfma_f32_16x16x32_bf16 v[22:25], v[216:219], v[180:183], v[22:25]
	v_mfma_f32_16x16x32_bf16 v[22:25], v[220:223], v[204:207], v[22:25]
	v_mfma_f32_16x16x32_bf16 v[18:21], v[224:227], v[180:183], v[18:21]
	v_mfma_f32_16x16x32_bf16 v[18:21], v[228:231], v[204:207], v[18:21]
	v_mfma_f32_16x16x32_bf16 v[6:9], v[216:219], v[208:211], v[6:9]
	v_mfma_f32_16x16x32_bf16 v[6:9], v[220:223], v[212:215], v[6:9]
	v_mfma_f32_16x16x32_bf16 v[2:5], v[224:227], v[208:211], v[2:5]
	v_mfma_f32_16x16x32_bf16 v[2:5], v[228:231], v[212:215], v[2:5]
	s_barrier
	s_add_i32 s18, 0, 0x18000
	ds_read_b128 v[142:145], v248 offset:32768
	ds_read_b128 v[146:149], v248 offset:33792
	ds_read_b128 v[156:159], v248 offset:34816
	ds_read_b128 v[160:163], v248 offset:35840
	s_add_u32 s4, s4, s14
	s_addc_u32 s5, s5, 0
	s_mov_b32 m0, s31
	ds_read_b128 v[164:167], v154 offset:32768
	ds_read_b128 v[168:171], v154 offset:33792
	ds_read_b128 v[172:175], v154 offset:34816
	ds_read_b128 v[176:179], v154 offset:35840
	ds_read_b128 v[180:183], v154 offset:36864
	ds_read_b128 v[204:207], v154 offset:37888
	ds_read_b128 v[208:211], v154 offset:38912
	ds_read_b128 v[212:215], v154 offset:39936
	global_load_lds_dwordx4 v130, s[4:5]
	s_mov_b32 m0, s34
	s_nop 0
	global_load_lds_dwordx4 v134, s[4:5]
	s_waitcnt lgkmcnt(8)
	s_barrier
	s_waitcnt lgkmcnt(0)
	v_mfma_f32_16x16x32_bf16 v[126:129], v[142:145], v[164:167], v[126:129]
	v_mfma_f32_16x16x32_bf16 v[126:129], v[146:149], v[168:171], v[126:129]
	v_mfma_f32_16x16x32_bf16 v[122:125], v[156:159], v[164:167], v[122:125]
	v_mfma_f32_16x16x32_bf16 v[122:125], v[160:163], v[168:171], v[122:125]
	v_mfma_f32_16x16x32_bf16 v[110:113], v[142:145], v[172:175], v[110:113]
	v_mfma_f32_16x16x32_bf16 v[110:113], v[146:149], v[176:179], v[110:113]
	v_mfma_f32_16x16x32_bf16 v[106:109], v[156:159], v[172:175], v[106:109]
	v_mfma_f32_16x16x32_bf16 v[106:109], v[160:163], v[176:179], v[106:109]
	v_mfma_f32_16x16x32_bf16 v[94:97], v[142:145], v[180:183], v[94:97]
	v_mfma_f32_16x16x32_bf16 v[94:97], v[146:149], v[204:207], v[94:97]
	v_mfma_f32_16x16x32_bf16 v[90:93], v[156:159], v[180:183], v[90:93]
	v_mfma_f32_16x16x32_bf16 v[90:93], v[160:163], v[204:207], v[90:93]
	v_mfma_f32_16x16x32_bf16 v[78:81], v[142:145], v[208:211], v[78:81]
	v_mfma_f32_16x16x32_bf16 v[78:81], v[146:149], v[212:215], v[78:81]
	v_mfma_f32_16x16x32_bf16 v[74:77], v[156:159], v[208:211], v[74:77]
	v_mfma_f32_16x16x32_bf16 v[74:77], v[160:163], v[212:215], v[74:77]
	s_barrier
	s_add_i32 s4, 0, 0x1c000
	s_add_i32 s5, s18, s25
	s_mov_b32 m0, s5
	ds_read_b128 v[216:219], v248 offset:49152
	ds_read_b128 v[220:223], v248 offset:50176
	ds_read_b128 v[224:227], v248 offset:51200
	ds_read_b128 v[228:231], v248 offset:52224
	global_load_lds_dwordx4 v132, s[70:71]
	s_add_i32 m0, s5, 0x2000
	s_nop 0
	global_load_lds_dwordx4 v136, s[70:71]
	s_barrier
	s_waitcnt lgkmcnt(0)
	v_mfma_f32_16x16x32_bf16 v[118:121], v[216:219], v[164:167], v[118:121]
	v_mfma_f32_16x16x32_bf16 v[118:121], v[220:223], v[168:171], v[118:121]
	v_mfma_f32_16x16x32_bf16 v[114:117], v[224:227], v[164:167], v[114:117]
	v_mfma_f32_16x16x32_bf16 v[114:117], v[228:231], v[168:171], v[114:117]
	v_mfma_f32_16x16x32_bf16 v[102:105], v[216:219], v[172:175], v[102:105]
	v_mfma_f32_16x16x32_bf16 v[102:105], v[220:223], v[176:179], v[102:105]
	v_mfma_f32_16x16x32_bf16 v[98:101], v[224:227], v[172:175], v[98:101]
	v_mfma_f32_16x16x32_bf16 v[98:101], v[228:231], v[176:179], v[98:101]
	v_mfma_f32_16x16x32_bf16 v[86:89], v[216:219], v[180:183], v[86:89]
	v_mfma_f32_16x16x32_bf16 v[86:89], v[220:223], v[204:207], v[86:89]
	v_mfma_f32_16x16x32_bf16 v[82:85], v[224:227], v[180:183], v[82:85]
	v_mfma_f32_16x16x32_bf16 v[82:85], v[228:231], v[204:207], v[82:85]
	v_mfma_f32_16x16x32_bf16 v[70:73], v[216:219], v[208:211], v[70:73]
	v_mfma_f32_16x16x32_bf16 v[70:73], v[220:223], v[212:215], v[70:73]
	v_mfma_f32_16x16x32_bf16 v[66:69], v[224:227], v[208:211], v[66:69]
	v_mfma_f32_16x16x32_bf16 v[66:69], v[228:231], v[212:215], v[66:69]
	s_barrier
	s_mov_b32 m0, s41
	ds_read_b128 v[164:167], v154 offset:49152
	ds_read_b128 v[168:171], v154 offset:50176
	ds_read_b128 v[172:175], v154 offset:51200
	ds_read_b128 v[176:179], v154 offset:52224
	ds_read_b128 v[180:183], v154 offset:53248
	ds_read_b128 v[204:207], v154 offset:54272
	ds_read_b128 v[208:211], v154 offset:55296
	ds_read_b128 v[212:215], v154 offset:56320
	global_load_lds_dwordx4 v130, s[72:73]
	s_mov_b32 m0, s42
	s_nop 0
	global_load_lds_dwordx4 v134, s[72:73]
	s_barrier
	s_waitcnt lgkmcnt(0)
	v_mfma_f32_16x16x32_bf16 v[62:65], v[142:145], v[164:167], v[62:65]
	v_mfma_f32_16x16x32_bf16 v[62:65], v[146:149], v[168:171], v[62:65]
	v_mfma_f32_16x16x32_bf16 v[58:61], v[156:159], v[164:167], v[58:61]
	v_mfma_f32_16x16x32_bf16 v[58:61], v[160:163], v[168:171], v[58:61]
	v_mfma_f32_16x16x32_bf16 v[46:49], v[142:145], v[172:175], v[46:49]
	v_mfma_f32_16x16x32_bf16 v[46:49], v[146:149], v[176:179], v[46:49]
	v_mfma_f32_16x16x32_bf16 v[42:45], v[156:159], v[172:175], v[42:45]
	v_mfma_f32_16x16x32_bf16 v[42:45], v[160:163], v[176:179], v[42:45]
	v_mfma_f32_16x16x32_bf16 v[30:33], v[142:145], v[180:183], v[30:33]
	v_mfma_f32_16x16x32_bf16 v[30:33], v[146:149], v[204:207], v[30:33]
	v_mfma_f32_16x16x32_bf16 v[26:29], v[156:159], v[180:183], v[26:29]
	v_mfma_f32_16x16x32_bf16 v[26:29], v[160:163], v[204:207], v[26:29]
	v_mfma_f32_16x16x32_bf16 v[14:17], v[142:145], v[208:211], v[14:17]
	v_mfma_f32_16x16x32_bf16 v[14:17], v[146:149], v[212:215], v[14:17]
	v_mfma_f32_16x16x32_bf16 v[10:13], v[156:159], v[208:211], v[10:13]
	v_mfma_f32_16x16x32_bf16 v[10:13], v[160:163], v[212:215], v[10:13]
	s_barrier
	s_add_i32 s4, s4, s25
	s_mov_b32 m0, s4
	s_nop 0
	global_load_lds_dwordx4 v132, s[76:77]
	s_add_i32 m0, s4, 0x2000
	s_nop 0
	global_load_lds_dwordx4 v136, s[76:77]
	s_add_u32 s0, s0, 0x100
	s_addc_u32 s1, s1, 0
	s_add_u32 s49, s49, 0x100
	s_addc_u32 s65, s65, 0
	s_cmp_ge_u32 s66, s35
	s_mov_b32 s4, s66
	s_waitcnt vmcnt(6)
	s_barrier
	v_mfma_f32_16x16x32_bf16 v[54:57], v[216:219], v[164:167], v[54:57]
	v_mfma_f32_16x16x32_bf16 v[54:57], v[220:223], v[168:171], v[54:57]
	v_mfma_f32_16x16x32_bf16 v[50:53], v[224:227], v[164:167], v[50:53]
	v_mfma_f32_16x16x32_bf16 v[50:53], v[228:231], v[168:171], v[50:53]
	v_mfma_f32_16x16x32_bf16 v[38:41], v[216:219], v[172:175], v[38:41]
	v_mfma_f32_16x16x32_bf16 v[38:41], v[220:223], v[176:179], v[38:41]
	v_mfma_f32_16x16x32_bf16 v[34:37], v[224:227], v[172:175], v[34:37]
	v_mfma_f32_16x16x32_bf16 v[34:37], v[228:231], v[176:179], v[34:37]
	v_mfma_f32_16x16x32_bf16 v[22:25], v[216:219], v[180:183], v[22:25]
	v_mfma_f32_16x16x32_bf16 v[22:25], v[220:223], v[204:207], v[22:25]
	v_mfma_f32_16x16x32_bf16 v[18:21], v[224:227], v[180:183], v[18:21]
	v_mfma_f32_16x16x32_bf16 v[18:21], v[228:231], v[204:207], v[18:21]
	v_mfma_f32_16x16x32_bf16 v[6:9], v[216:219], v[208:211], v[6:9]
	v_mfma_f32_16x16x32_bf16 v[6:9], v[220:223], v[212:215], v[6:9]
	v_mfma_f32_16x16x32_bf16 v[2:5], v[224:227], v[208:211], v[2:5]
	v_mfma_f32_16x16x32_bf16 v[2:5], v[228:231], v[212:215], v[2:5]
	s_barrier
	s_cbranch_scc0 .LBB0_664

.LBB0_697:
	s_add_u32 s0, s0, 0x80
	s_addc_u32 s1, s1, 0
	s_add_u32 s48, s4, 0x100
	s_addc_u32 s49, s5, 0
	s_mov_b32 s4, 0
	s_waitcnt lgkmcnt(0)
	s_waitcnt vmcnt(0)
	s_add_i32 s65, s4, 2
	s_add_u32 s18, s0, 0x80
	s_addc_u32 s5, s1, 0
	s_add_i32 s66, 0, 0x10000
	ds_read_b128 v[142:145], v248
	ds_read_b128 v[152:155], v248 offset:1024
	ds_read_b128 v[156:159], v248 offset:2048
	ds_read_b128 v[160:163], v248 offset:3072
	s_cmp_eq_u32 s34, s4
	s_cselect_b32 s4, s10, s18
	s_cselect_b32 s5, s11, s5
	s_cselect_b32 s19, s13, s49
	s_cselect_b32 s18, s12, s48
	s_add_i32 m0, s22, 0xc000
	ds_read_b128 v[164:167], v150
	ds_read_b128 v[168:171], v150 offset:1024
	ds_read_b128 v[172:175], v150 offset:2048
	ds_read_b128 v[176:179], v150 offset:3072
	ds_read_b128 v[180:183], v150 offset:4096
	ds_read_b128 v[204:207], v150 offset:5120
	ds_read_b128 v[208:211], v150 offset:6144
	ds_read_b128 v[212:215], v150 offset:7168
	global_load_lds_dwordx4 v138, s[0:1]
	s_add_i32 m0, s22, 0xe000
	s_nop 0
	global_load_lds_dwordx4 v140, s[0:1]
	s_waitcnt lgkmcnt(8)
	s_barrier
	s_waitcnt lgkmcnt(0)
	v_mfma_f32_16x16x32_bf16 v[126:129], v[142:145], v[164:167], 0
	v_mfma_f32_16x16x32_bf16 v[126:129], v[152:155], v[168:171], v[126:129]
	v_mfma_f32_16x16x32_bf16 v[122:125], v[156:159], v[164:167], 0
	v_mfma_f32_16x16x32_bf16 v[122:125], v[160:163], v[168:171], v[122:125]
	v_mfma_f32_16x16x32_bf16 v[110:113], v[142:145], v[172:175], 0
	v_mfma_f32_16x16x32_bf16 v[110:113], v[152:155], v[176:179], v[110:113]
	v_mfma_f32_16x16x32_bf16 v[106:109], v[156:159], v[172:175], 0
	v_mfma_f32_16x16x32_bf16 v[106:109], v[160:163], v[176:179], v[106:109]
	v_mfma_f32_16x16x32_bf16 v[94:97], v[142:145], v[180:183], 0
	v_mfma_f32_16x16x32_bf16 v[94:97], v[152:155], v[204:207], v[94:97]
	v_mfma_f32_16x16x32_bf16 v[90:93], v[156:159], v[180:183], 0
	v_mfma_f32_16x16x32_bf16 v[90:93], v[160:163], v[204:207], v[90:93]
	v_mfma_f32_16x16x32_bf16 v[78:81], v[142:145], v[208:211], 0
	v_mfma_f32_16x16x32_bf16 v[78:81], v[152:155], v[212:215], v[78:81]
	v_mfma_f32_16x16x32_bf16 v[74:77], v[156:159], v[208:211], 0
	v_mfma_f32_16x16x32_bf16 v[74:77], v[160:163], v[212:215], v[74:77]
	s_barrier
	s_add_i32 s67, 0, 0x14000
	s_add_i32 s66, s66, s21
	ds_read_b128 v[216:219], v248 offset:16384
	ds_read_b128 v[220:223], v248 offset:17408
	ds_read_b128 v[224:227], v248 offset:18432
	ds_read_b128 v[228:231], v248 offset:19456
	s_add_u32 s70, s18, s6
	s_addc_u32 s71, s19, s7
	s_mov_b32 m0, s66
	s_nop 0
	global_load_lds_dwordx4 v132, s[18:19]
	s_add_i32 m0, s66, 0x2000
	s_nop 0
	global_load_lds_dwordx4 v136, s[18:19]
	s_barrier
	s_waitcnt lgkmcnt(0)
	v_mfma_f32_16x16x32_bf16 v[118:121], v[216:219], v[164:167], 0
	v_mfma_f32_16x16x32_bf16 v[118:121], v[220:223], v[168:171], v[118:121]
	v_mfma_f32_16x16x32_bf16 v[114:117], v[224:227], v[164:167], 0
	v_mfma_f32_16x16x32_bf16 v[114:117], v[228:231], v[168:171], v[114:117]
	v_mfma_f32_16x16x32_bf16 v[102:105], v[216:219], v[172:175], 0
	v_mfma_f32_16x16x32_bf16 v[102:105], v[220:223], v[176:179], v[102:105]
	v_mfma_f32_16x16x32_bf16 v[98:101], v[224:227], v[172:175], 0
	v_mfma_f32_16x16x32_bf16 v[98:101], v[228:231], v[176:179], v[98:101]
	v_mfma_f32_16x16x32_bf16 v[86:89], v[216:219], v[180:183], 0
	v_mfma_f32_16x16x32_bf16 v[86:89], v[220:223], v[204:207], v[86:89]
	v_mfma_f32_16x16x32_bf16 v[82:85], v[224:227], v[180:183], 0
	v_mfma_f32_16x16x32_bf16 v[82:85], v[228:231], v[204:207], v[82:85]
	v_mfma_f32_16x16x32_bf16 v[70:73], v[216:219], v[208:211], 0
	v_mfma_f32_16x16x32_bf16 v[70:73], v[220:223], v[212:215], v[70:73]
	v_mfma_f32_16x16x32_bf16 v[66:69], v[224:227], v[208:211], 0
	v_mfma_f32_16x16x32_bf16 v[66:69], v[228:231], v[212:215], v[66:69]
	s_barrier
	s_mov_b32 m0, s22
	s_add_u32 s72, s4, s6
	s_addc_u32 s73, s5, s7
	ds_read_b128 v[164:167], v150 offset:16384
	ds_read_b128 v[168:171], v150 offset:17408
	ds_read_b128 v[172:175], v150 offset:18432
	ds_read_b128 v[176:179], v150 offset:19456
	ds_read_b128 v[180:183], v150 offset:20480
	ds_read_b128 v[204:207], v150 offset:21504
	ds_read_b128 v[208:211], v150 offset:22528
	ds_read_b128 v[212:215], v150 offset:23552
	global_load_lds_dwordx4 v130, s[4:5]
	s_mov_b32 m0, s23
	s_nop 0
	global_load_lds_dwordx4 v134, s[4:5]
	s_barrier
	s_waitcnt lgkmcnt(0)
	v_mfma_f32_16x16x32_bf16 v[62:65], v[142:145], v[164:167], 0
	v_mfma_f32_16x16x32_bf16 v[62:65], v[152:155], v[168:171], v[62:65]
	v_mfma_f32_16x16x32_bf16 v[58:61], v[156:159], v[164:167], 0
	v_mfma_f32_16x16x32_bf16 v[58:61], v[160:163], v[168:171], v[58:61]
	v_mfma_f32_16x16x32_bf16 v[46:49], v[142:145], v[172:175], 0
	v_mfma_f32_16x16x32_bf16 v[46:49], v[152:155], v[176:179], v[46:49]
	v_mfma_f32_16x16x32_bf16 v[42:45], v[156:159], v[172:175], 0
	v_mfma_f32_16x16x32_bf16 v[42:45], v[160:163], v[176:179], v[42:45]
	v_mfma_f32_16x16x32_bf16 v[30:33], v[142:145], v[180:183], 0
	v_mfma_f32_16x16x32_bf16 v[30:33], v[152:155], v[204:207], v[30:33]
	v_mfma_f32_16x16x32_bf16 v[26:29], v[156:159], v[180:183], 0
	v_mfma_f32_16x16x32_bf16 v[26:29], v[160:163], v[204:207], v[26:29]
	v_mfma_f32_16x16x32_bf16 v[14:17], v[142:145], v[208:211], 0
	v_mfma_f32_16x16x32_bf16 v[14:17], v[152:155], v[212:215], v[14:17]
	v_mfma_f32_16x16x32_bf16 v[10:13], v[156:159], v[208:211], 0
	v_mfma_f32_16x16x32_bf16 v[10:13], v[160:163], v[212:215], v[10:13]
	s_barrier
	s_add_u32 s18, s18, s2
	s_addc_u32 s19, s19, 0
	s_add_i32 s66, s67, s21
	s_add_u32 s76, s18, s6
	s_addc_u32 s77, s19, s7
	s_mov_b32 m0, s66
	s_nop 0
	global_load_lds_dwordx4 v132, s[18:19]
	s_add_i32 m0, s66, 0x2000
	s_nop 0
	global_load_lds_dwordx4 v136, s[18:19]
	s_waitcnt vmcnt(6)
	s_barrier
	v_mfma_f32_16x16x32_bf16 v[54:57], v[216:219], v[164:167], 0
	v_mfma_f32_16x16x32_bf16 v[54:57], v[220:223], v[168:171], v[54:57]
	v_mfma_f32_16x16x32_bf16 v[50:53], v[224:227], v[164:167], 0
	v_mfma_f32_16x16x32_bf16 v[50:53], v[228:231], v[168:171], v[50:53]
	v_mfma_f32_16x16x32_bf16 v[38:41], v[216:219], v[172:175], 0
	v_mfma_f32_16x16x32_bf16 v[38:41], v[220:223], v[176:179], v[38:41]
	v_mfma_f32_16x16x32_bf16 v[34:37], v[224:227], v[172:175], 0
	v_mfma_f32_16x16x32_bf16 v[34:37], v[228:231], v[176:179], v[34:37]
	v_mfma_f32_16x16x32_bf16 v[22:25], v[216:219], v[180:183], 0
	v_mfma_f32_16x16x32_bf16 v[22:25], v[220:223], v[204:207], v[22:25]
	v_mfma_f32_16x16x32_bf16 v[18:21], v[224:227], v[180:183], 0
	v_mfma_f32_16x16x32_bf16 v[18:21], v[228:231], v[204:207], v[18:21]
	v_mfma_f32_16x16x32_bf16 v[6:9], v[216:219], v[208:211], 0
	v_mfma_f32_16x16x32_bf16 v[6:9], v[220:223], v[212:215], v[6:9]
	v_mfma_f32_16x16x32_bf16 v[2:5], v[224:227], v[208:211], 0
	v_mfma_f32_16x16x32_bf16 v[2:5], v[228:231], v[212:215], v[2:5]
	s_barrier
	s_add_i32 s18, 0, 0x18000
	ds_read_b128 v[142:145], v248 offset:32768
	ds_read_b128 v[152:155], v248 offset:33792
	ds_read_b128 v[156:159], v248 offset:34816
	ds_read_b128 v[160:163], v248 offset:35840
	s_add_u32 s4, s4, s2
	s_addc_u32 s5, s5, 0
	s_mov_b32 m0, s24
	ds_read_b128 v[164:167], v150 offset:32768
	ds_read_b128 v[168:171], v150 offset:33792
	ds_read_b128 v[172:175], v150 offset:34816
	ds_read_b128 v[176:179], v150 offset:35840
	ds_read_b128 v[180:183], v150 offset:36864
	ds_read_b128 v[204:207], v150 offset:37888
	ds_read_b128 v[208:211], v150 offset:38912
	ds_read_b128 v[212:215], v150 offset:39936
	global_load_lds_dwordx4 v130, s[4:5]
	s_mov_b32 m0, s25
	s_nop 0
	global_load_lds_dwordx4 v134, s[4:5]
	s_waitcnt lgkmcnt(8)
	s_barrier
	s_waitcnt lgkmcnt(0)
	v_mfma_f32_16x16x32_bf16 v[126:129], v[142:145], v[164:167], v[126:129]
	v_mfma_f32_16x16x32_bf16 v[126:129], v[152:155], v[168:171], v[126:129]
	v_mfma_f32_16x16x32_bf16 v[122:125], v[156:159], v[164:167], v[122:125]
	v_mfma_f32_16x16x32_bf16 v[122:125], v[160:163], v[168:171], v[122:125]
	v_mfma_f32_16x16x32_bf16 v[110:113], v[142:145], v[172:175], v[110:113]
	v_mfma_f32_16x16x32_bf16 v[110:113], v[152:155], v[176:179], v[110:113]
	v_mfma_f32_16x16x32_bf16 v[106:109], v[156:159], v[172:175], v[106:109]
	v_mfma_f32_16x16x32_bf16 v[106:109], v[160:163], v[176:179], v[106:109]
	v_mfma_f32_16x16x32_bf16 v[94:97], v[142:145], v[180:183], v[94:97]
	v_mfma_f32_16x16x32_bf16 v[94:97], v[152:155], v[204:207], v[94:97]
	v_mfma_f32_16x16x32_bf16 v[90:93], v[156:159], v[180:183], v[90:93]
	v_mfma_f32_16x16x32_bf16 v[90:93], v[160:163], v[204:207], v[90:93]
	v_mfma_f32_16x16x32_bf16 v[78:81], v[142:145], v[208:211], v[78:81]
	v_mfma_f32_16x16x32_bf16 v[78:81], v[152:155], v[212:215], v[78:81]
	v_mfma_f32_16x16x32_bf16 v[74:77], v[156:159], v[208:211], v[74:77]
	v_mfma_f32_16x16x32_bf16 v[74:77], v[160:163], v[212:215], v[74:77]
	s_barrier
	s_add_i32 s4, 0, 0x1c000
	s_add_i32 s5, s18, s21
	s_mov_b32 m0, s5
	ds_read_b128 v[216:219], v248 offset:49152
	ds_read_b128 v[220:223], v248 offset:50176
	ds_read_b128 v[224:227], v248 offset:51200
	ds_read_b128 v[228:231], v248 offset:52224
	global_load_lds_dwordx4 v132, s[70:71]
	s_add_i32 m0, s5, 0x2000
	s_nop 0
	global_load_lds_dwordx4 v136, s[70:71]
	s_barrier
	s_waitcnt lgkmcnt(0)
	v_mfma_f32_16x16x32_bf16 v[118:121], v[216:219], v[164:167], v[118:121]
	v_mfma_f32_16x16x32_bf16 v[118:121], v[220:223], v[168:171], v[118:121]
	v_mfma_f32_16x16x32_bf16 v[114:117], v[224:227], v[164:167], v[114:117]
	v_mfma_f32_16x16x32_bf16 v[114:117], v[228:231], v[168:171], v[114:117]
	v_mfma_f32_16x16x32_bf16 v[102:105], v[216:219], v[172:175], v[102:105]
	v_mfma_f32_16x16x32_bf16 v[102:105], v[220:223], v[176:179], v[102:105]
	v_mfma_f32_16x16x32_bf16 v[98:101], v[224:227], v[172:175], v[98:101]
	v_mfma_f32_16x16x32_bf16 v[98:101], v[228:231], v[176:179], v[98:101]
	v_mfma_f32_16x16x32_bf16 v[86:89], v[216:219], v[180:183], v[86:89]
	v_mfma_f32_16x16x32_bf16 v[86:89], v[220:223], v[204:207], v[86:89]
	v_mfma_f32_16x16x32_bf16 v[82:85], v[224:227], v[180:183], v[82:85]
	v_mfma_f32_16x16x32_bf16 v[82:85], v[228:231], v[204:207], v[82:85]
	v_mfma_f32_16x16x32_bf16 v[70:73], v[216:219], v[208:211], v[70:73]
	v_mfma_f32_16x16x32_bf16 v[70:73], v[220:223], v[212:215], v[70:73]
	v_mfma_f32_16x16x32_bf16 v[66:69], v[224:227], v[208:211], v[66:69]
	v_mfma_f32_16x16x32_bf16 v[66:69], v[228:231], v[212:215], v[66:69]
	s_barrier
	s_mov_b32 m0, s30
	ds_read_b128 v[164:167], v150 offset:49152
	ds_read_b128 v[168:171], v150 offset:50176
	ds_read_b128 v[172:175], v150 offset:51200
	ds_read_b128 v[176:179], v150 offset:52224
	ds_read_b128 v[180:183], v150 offset:53248
	ds_read_b128 v[204:207], v150 offset:54272
	ds_read_b128 v[208:211], v150 offset:55296
	ds_read_b128 v[212:215], v150 offset:56320
	global_load_lds_dwordx4 v130, s[72:73]
	s_mov_b32 m0, s31
	s_nop 0
	global_load_lds_dwordx4 v134, s[72:73]
	s_barrier
	s_waitcnt lgkmcnt(0)
	v_mfma_f32_16x16x32_bf16 v[62:65], v[142:145], v[164:167], v[62:65]
	v_mfma_f32_16x16x32_bf16 v[62:65], v[152:155], v[168:171], v[62:65]
	v_mfma_f32_16x16x32_bf16 v[58:61], v[156:159], v[164:167], v[58:61]
	v_mfma_f32_16x16x32_bf16 v[58:61], v[160:163], v[168:171], v[58:61]
	v_mfma_f32_16x16x32_bf16 v[46:49], v[142:145], v[172:175], v[46:49]
	v_mfma_f32_16x16x32_bf16 v[46:49], v[152:155], v[176:179], v[46:49]
	v_mfma_f32_16x16x32_bf16 v[42:45], v[156:159], v[172:175], v[42:45]
	v_mfma_f32_16x16x32_bf16 v[42:45], v[160:163], v[176:179], v[42:45]
	v_mfma_f32_16x16x32_bf16 v[30:33], v[142:145], v[180:183], v[30:33]
	v_mfma_f32_16x16x32_bf16 v[30:33], v[152:155], v[204:207], v[30:33]
	v_mfma_f32_16x16x32_bf16 v[26:29], v[156:159], v[180:183], v[26:29]
	v_mfma_f32_16x16x32_bf16 v[26:29], v[160:163], v[204:207], v[26:29]
	v_mfma_f32_16x16x32_bf16 v[14:17], v[142:145], v[208:211], v[14:17]
	v_mfma_f32_16x16x32_bf16 v[14:17], v[152:155], v[212:215], v[14:17]
	v_mfma_f32_16x16x32_bf16 v[10:13], v[156:159], v[208:211], v[10:13]
	v_mfma_f32_16x16x32_bf16 v[10:13], v[160:163], v[212:215], v[10:13]
	s_barrier
	s_add_i32 s4, s4, s21
	s_mov_b32 m0, s4
	s_nop 0
	global_load_lds_dwordx4 v132, s[76:77]
	s_add_i32 m0, s4, 0x2000
	s_nop 0
	global_load_lds_dwordx4 v136, s[76:77]
	s_add_u32 s0, s0, 0x100
	s_addc_u32 s1, s1, 0
	s_add_u32 s48, s48, 0x100
	s_addc_u32 s49, s49, 0
	s_cmp_ge_u32 s65, s27
	s_mov_b32 s4, s65
	s_waitcnt vmcnt(6)
	s_barrier
	v_mfma_f32_16x16x32_bf16 v[54:57], v[216:219], v[164:167], v[54:57]
	v_mfma_f32_16x16x32_bf16 v[54:57], v[220:223], v[168:171], v[54:57]
	v_mfma_f32_16x16x32_bf16 v[50:53], v[224:227], v[164:167], v[50:53]
	v_mfma_f32_16x16x32_bf16 v[50:53], v[228:231], v[168:171], v[50:53]
	v_mfma_f32_16x16x32_bf16 v[38:41], v[216:219], v[172:175], v[38:41]
	v_mfma_f32_16x16x32_bf16 v[38:41], v[220:223], v[176:179], v[38:41]
	v_mfma_f32_16x16x32_bf16 v[34:37], v[224:227], v[172:175], v[34:37]
	v_mfma_f32_16x16x32_bf16 v[34:37], v[228:231], v[176:179], v[34:37]
	v_mfma_f32_16x16x32_bf16 v[22:25], v[216:219], v[180:183], v[22:25]
	v_mfma_f32_16x16x32_bf16 v[22:25], v[220:223], v[204:207], v[22:25]
	v_mfma_f32_16x16x32_bf16 v[18:21], v[224:227], v[180:183], v[18:21]
	v_mfma_f32_16x16x32_bf16 v[18:21], v[228:231], v[204:207], v[18:21]
	v_mfma_f32_16x16x32_bf16 v[6:9], v[216:219], v[208:211], v[6:9]
	v_mfma_f32_16x16x32_bf16 v[6:9], v[220:223], v[212:215], v[6:9]
	v_mfma_f32_16x16x32_bf16 v[2:5], v[224:227], v[208:211], v[2:5]
	v_mfma_f32_16x16x32_bf16 v[2:5], v[228:231], v[212:215], v[2:5]
	s_barrier
	s_cbranch_scc1 .Lkexit_698
.LBB0_698:
	s_add_i32 s65, s4, 2
	s_add_u32 s18, s0, 0x80
	s_addc_u32 s5, s1, 0
	s_add_i32 s66, 0, 0x10000
	ds_read_b128 v[142:145], v248
	ds_read_b128 v[152:155], v248 offset:1024
	ds_read_b128 v[156:159], v248 offset:2048
	ds_read_b128 v[160:163], v248 offset:3072
	s_cmp_eq_u32 s34, s4
	s_cselect_b32 s4, s10, s18
	s_cselect_b32 s5, s11, s5
	s_cselect_b32 s19, s13, s49
	s_cselect_b32 s18, s12, s48
	s_add_i32 m0, s22, 0xc000
	ds_read_b128 v[164:167], v150
	ds_read_b128 v[168:171], v150 offset:1024
	ds_read_b128 v[172:175], v150 offset:2048
	ds_read_b128 v[176:179], v150 offset:3072
	ds_read_b128 v[180:183], v150 offset:4096
	ds_read_b128 v[204:207], v150 offset:5120
	ds_read_b128 v[208:211], v150 offset:6144
	ds_read_b128 v[212:215], v150 offset:7168
	global_load_lds_dwordx4 v138, s[0:1]
	s_add_i32 m0, s22, 0xe000
	s_nop 0
	global_load_lds_dwordx4 v140, s[0:1]
	s_waitcnt lgkmcnt(8)
	s_barrier
	s_waitcnt lgkmcnt(0)
	v_mfma_f32_16x16x32_bf16 v[126:129], v[142:145], v[164:167], v[126:129]
	v_mfma_f32_16x16x32_bf16 v[126:129], v[152:155], v[168:171], v[126:129]
	v_mfma_f32_16x16x32_bf16 v[122:125], v[156:159], v[164:167], v[122:125]
	v_mfma_f32_16x16x32_bf16 v[122:125], v[160:163], v[168:171], v[122:125]
	v_mfma_f32_16x16x32_bf16 v[110:113], v[142:145], v[172:175], v[110:113]
	v_mfma_f32_16x16x32_bf16 v[110:113], v[152:155], v[176:179], v[110:113]
	v_mfma_f32_16x16x32_bf16 v[106:109], v[156:159], v[172:175], v[106:109]
	v_mfma_f32_16x16x32_bf16 v[106:109], v[160:163], v[176:179], v[106:109]
	v_mfma_f32_16x16x32_bf16 v[94:97], v[142:145], v[180:183], v[94:97]
	v_mfma_f32_16x16x32_bf16 v[94:97], v[152:155], v[204:207], v[94:97]
	v_mfma_f32_16x16x32_bf16 v[90:93], v[156:159], v[180:183], v[90:93]
	v_mfma_f32_16x16x32_bf16 v[90:93], v[160:163], v[204:207], v[90:93]
	v_mfma_f32_16x16x32_bf16 v[78:81], v[142:145], v[208:211], v[78:81]
	v_mfma_f32_16x16x32_bf16 v[78:81], v[152:155], v[212:215], v[78:81]
	v_mfma_f32_16x16x32_bf16 v[74:77], v[156:159], v[208:211], v[74:77]
	v_mfma_f32_16x16x32_bf16 v[74:77], v[160:163], v[212:215], v[74:77]
	s_barrier
	s_add_i32 s67, 0, 0x14000
	s_add_i32 s66, s66, s21
	ds_read_b128 v[216:219], v248 offset:16384
	ds_read_b128 v[220:223], v248 offset:17408
	ds_read_b128 v[224:227], v248 offset:18432
	ds_read_b128 v[228:231], v248 offset:19456
	s_add_u32 s70, s18, s6
	s_addc_u32 s71, s19, s7
	s_mov_b32 m0, s66
	s_nop 0
	global_load_lds_dwordx4 v132, s[18:19]
	s_add_i32 m0, s66, 0x2000
	s_nop 0
	global_load_lds_dwordx4 v136, s[18:19]
	s_barrier
	s_waitcnt lgkmcnt(0)
	v_mfma_f32_16x16x32_bf16 v[118:121], v[216:219], v[164:167], v[118:121]
	v_mfma_f32_16x16x32_bf16 v[118:121], v[220:223], v[168:171], v[118:121]
	v_mfma_f32_16x16x32_bf16 v[114:117], v[224:227], v[164:167], v[114:117]
	v_mfma_f32_16x16x32_bf16 v[114:117], v[228:231], v[168:171], v[114:117]
	v_mfma_f32_16x16x32_bf16 v[102:105], v[216:219], v[172:175], v[102:105]
	v_mfma_f32_16x16x32_bf16 v[102:105], v[220:223], v[176:179], v[102:105]
	v_mfma_f32_16x16x32_bf16 v[98:101], v[224:227], v[172:175], v[98:101]
	v_mfma_f32_16x16x32_bf16 v[98:101], v[228:231], v[176:179], v[98:101]
	v_mfma_f32_16x16x32_bf16 v[86:89], v[216:219], v[180:183], v[86:89]
	v_mfma_f32_16x16x32_bf16 v[86:89], v[220:223], v[204:207], v[86:89]
	v_mfma_f32_16x16x32_bf16 v[82:85], v[224:227], v[180:183], v[82:85]
	v_mfma_f32_16x16x32_bf16 v[82:85], v[228:231], v[204:207], v[82:85]
	v_mfma_f32_16x16x32_bf16 v[70:73], v[216:219], v[208:211], v[70:73]
	v_mfma_f32_16x16x32_bf16 v[70:73], v[220:223], v[212:215], v[70:73]
	v_mfma_f32_16x16x32_bf16 v[66:69], v[224:227], v[208:211], v[66:69]
	v_mfma_f32_16x16x32_bf16 v[66:69], v[228:231], v[212:215], v[66:69]
	s_barrier
	s_mov_b32 m0, s22
	s_add_u32 s72, s4, s6
	s_addc_u32 s73, s5, s7
	ds_read_b128 v[164:167], v150 offset:16384
	ds_read_b128 v[168:171], v150 offset:17408
	ds_read_b128 v[172:175], v150 offset:18432
	ds_read_b128 v[176:179], v150 offset:19456
	ds_read_b128 v[180:183], v150 offset:20480
	ds_read_b128 v[204:207], v150 offset:21504
	ds_read_b128 v[208:211], v150 offset:22528
	ds_read_b128 v[212:215], v150 offset:23552
	global_load_lds_dwordx4 v130, s[4:5]
	s_mov_b32 m0, s23
	s_nop 0
	global_load_lds_dwordx4 v134, s[4:5]
	s_barrier
	s_waitcnt lgkmcnt(0)
	v_mfma_f32_16x16x32_bf16 v[62:65], v[142:145], v[164:167], v[62:65]
	v_mfma_f32_16x16x32_bf16 v[62:65], v[152:155], v[168:171], v[62:65]
	v_mfma_f32_16x16x32_bf16 v[58:61], v[156:159], v[164:167], v[58:61]
	v_mfma_f32_16x16x32_bf16 v[58:61], v[160:163], v[168:171], v[58:61]
	v_mfma_f32_16x16x32_bf16 v[46:49], v[142:145], v[172:175], v[46:49]
	v_mfma_f32_16x16x32_bf16 v[46:49], v[152:155], v[176:179], v[46:49]
	v_mfma_f32_16x16x32_bf16 v[42:45], v[156:159], v[172:175], v[42:45]
	v_mfma_f32_16x16x32_bf16 v[42:45], v[160:163], v[176:179], v[42:45]
	v_mfma_f32_16x16x32_bf16 v[30:33], v[142:145], v[180:183], v[30:33]
	v_mfma_f32_16x16x32_bf16 v[30:33], v[152:155], v[204:207], v[30:33]
	v_mfma_f32_16x16x32_bf16 v[26:29], v[156:159], v[180:183], v[26:29]
	v_mfma_f32_16x16x32_bf16 v[26:29], v[160:163], v[204:207], v[26:29]
	v_mfma_f32_16x16x32_bf16 v[14:17], v[142:145], v[208:211], v[14:17]
	v_mfma_f32_16x16x32_bf16 v[14:17], v[152:155], v[212:215], v[14:17]
	v_mfma_f32_16x16x32_bf16 v[10:13], v[156:159], v[208:211], v[10:13]
	v_mfma_f32_16x16x32_bf16 v[10:13], v[160:163], v[212:215], v[10:13]
	s_barrier
	s_add_u32 s18, s18, s2
	s_addc_u32 s19, s19, 0
	s_add_i32 s66, s67, s21
	s_add_u32 s76, s18, s6
	s_addc_u32 s77, s19, s7
	s_mov_b32 m0, s66
	s_nop 0
	global_load_lds_dwordx4 v132, s[18:19]
	s_add_i32 m0, s66, 0x2000
	s_nop 0
	global_load_lds_dwordx4 v136, s[18:19]
	s_waitcnt vmcnt(6)
	s_barrier
	v_mfma_f32_16x16x32_bf16 v[54:57], v[216:219], v[164:167], v[54:57]
	v_mfma_f32_16x16x32_bf16 v[54:57], v[220:223], v[168:171], v[54:57]
	v_mfma_f32_16x16x32_bf16 v[50:53], v[224:227], v[164:167], v[50:53]
	v_mfma_f32_16x16x32_bf16 v[50:53], v[228:231], v[168:171], v[50:53]
	v_mfma_f32_16x16x32_bf16 v[38:41], v[216:219], v[172:175], v[38:41]
	v_mfma_f32_16x16x32_bf16 v[38:41], v[220:223], v[176:179], v[38:41]
	v_mfma_f32_16x16x32_bf16 v[34:37], v[224:227], v[172:175], v[34:37]
	v_mfma_f32_16x16x32_bf16 v[34:37], v[228:231], v[176:179], v[34:37]
	v_mfma_f32_16x16x32_bf16 v[22:25], v[216:219], v[180:183], v[22:25]
	v_mfma_f32_16x16x32_bf16 v[22:25], v[220:223], v[204:207], v[22:25]
	v_mfma_f32_16x16x32_bf16 v[18:21], v[224:227], v[180:183], v[18:21]
	v_mfma_f32_16x16x32_bf16 v[18:21], v[228:231], v[204:207], v[18:21]
	v_mfma_f32_16x16x32_bf16 v[6:9], v[216:219], v[208:211], v[6:9]
	v_mfma_f32_16x16x32_bf16 v[6:9], v[220:223], v[212:215], v[6:9]
	v_mfma_f32_16x16x32_bf16 v[2:5], v[224:227], v[208:211], v[2:5]
	v_mfma_f32_16x16x32_bf16 v[2:5], v[228:231], v[212:215], v[2:5]
	s_barrier
	s_add_i32 s18, 0, 0x18000
	ds_read_b128 v[142:145], v248 offset:32768
	ds_read_b128 v[152:155], v248 offset:33792
	ds_read_b128 v[156:159], v248 offset:34816
	ds_read_b128 v[160:163], v248 offset:35840
	s_add_u32 s4, s4, s2
	s_addc_u32 s5, s5, 0
	s_mov_b32 m0, s24
	ds_read_b128 v[164:167], v150 offset:32768
	ds_read_b128 v[168:171], v150 offset:33792
	ds_read_b128 v[172:175], v150 offset:34816
	ds_read_b128 v[176:179], v150 offset:35840
	ds_read_b128 v[180:183], v150 offset:36864
	ds_read_b128 v[204:207], v150 offset:37888
	ds_read_b128 v[208:211], v150 offset:38912
	ds_read_b128 v[212:215], v150 offset:39936
	global_load_lds_dwordx4 v130, s[4:5]
	s_mov_b32 m0, s25
	s_nop 0
	global_load_lds_dwordx4 v134, s[4:5]
	s_waitcnt lgkmcnt(8)
	s_barrier
	s_waitcnt lgkmcnt(0)
	v_mfma_f32_16x16x32_bf16 v[126:129], v[142:145], v[164:167], v[126:129]
	v_mfma_f32_16x16x32_bf16 v[126:129], v[152:155], v[168:171], v[126:129]
	v_mfma_f32_16x16x32_bf16 v[122:125], v[156:159], v[164:167], v[122:125]
	v_mfma_f32_16x16x32_bf16 v[122:125], v[160:163], v[168:171], v[122:125]
	v_mfma_f32_16x16x32_bf16 v[110:113], v[142:145], v[172:175], v[110:113]
	v_mfma_f32_16x16x32_bf16 v[110:113], v[152:155], v[176:179], v[110:113]
	v_mfma_f32_16x16x32_bf16 v[106:109], v[156:159], v[172:175], v[106:109]
	v_mfma_f32_16x16x32_bf16 v[106:109], v[160:163], v[176:179], v[106:109]
	v_mfma_f32_16x16x32_bf16 v[94:97], v[142:145], v[180:183], v[94:97]
	v_mfma_f32_16x16x32_bf16 v[94:97], v[152:155], v[204:207], v[94:97]
	v_mfma_f32_16x16x32_bf16 v[90:93], v[156:159], v[180:183], v[90:93]
	v_mfma_f32_16x16x32_bf16 v[90:93], v[160:163], v[204:207], v[90:93]
	v_mfma_f32_16x16x32_bf16 v[78:81], v[142:145], v[208:211], v[78:81]
	v_mfma_f32_16x16x32_bf16 v[78:81], v[152:155], v[212:215], v[78:81]
	v_mfma_f32_16x16x32_bf16 v[74:77], v[156:159], v[208:211], v[74:77]
	v_mfma_f32_16x16x32_bf16 v[74:77], v[160:163], v[212:215], v[74:77]
	s_barrier
	s_add_i32 s4, 0, 0x1c000
	s_add_i32 s5, s18, s21
	s_mov_b32 m0, s5
	ds_read_b128 v[216:219], v248 offset:49152
	ds_read_b128 v[220:223], v248 offset:50176
	ds_read_b128 v[224:227], v248 offset:51200
	ds_read_b128 v[228:231], v248 offset:52224
	global_load_lds_dwordx4 v132, s[70:71]
	s_add_i32 m0, s5, 0x2000
	s_nop 0
	global_load_lds_dwordx4 v136, s[70:71]
	s_barrier
	s_waitcnt lgkmcnt(0)
	v_mfma_f32_16x16x32_bf16 v[118:121], v[216:219], v[164:167], v[118:121]
	v_mfma_f32_16x16x32_bf16 v[118:121], v[220:223], v[168:171], v[118:121]
	v_mfma_f32_16x16x32_bf16 v[114:117], v[224:227], v[164:167], v[114:117]
	v_mfma_f32_16x16x32_bf16 v[114:117], v[228:231], v[168:171], v[114:117]
	v_mfma_f32_16x16x32_bf16 v[102:105], v[216:219], v[172:175], v[102:105]
	v_mfma_f32_16x16x32_bf16 v[102:105], v[220:223], v[176:179], v[102:105]
	v_mfma_f32_16x16x32_bf16 v[98:101], v[224:227], v[172:175], v[98:101]
	v_mfma_f32_16x16x32_bf16 v[98:101], v[228:231], v[176:179], v[98:101]
	v_mfma_f32_16x16x32_bf16 v[86:89], v[216:219], v[180:183], v[86:89]
	v_mfma_f32_16x16x32_bf16 v[86:89], v[220:223], v[204:207], v[86:89]
	v_mfma_f32_16x16x32_bf16 v[82:85], v[224:227], v[180:183], v[82:85]
	v_mfma_f32_16x16x32_bf16 v[82:85], v[228:231], v[204:207], v[82:85]
	v_mfma_f32_16x16x32_bf16 v[70:73], v[216:219], v[208:211], v[70:73]
	v_mfma_f32_16x16x32_bf16 v[70:73], v[220:223], v[212:215], v[70:73]
	v_mfma_f32_16x16x32_bf16 v[66:69], v[224:227], v[208:211], v[66:69]
	v_mfma_f32_16x16x32_bf16 v[66:69], v[228:231], v[212:215], v[66:69]
	s_barrier
	s_mov_b32 m0, s30
	ds_read_b128 v[164:167], v150 offset:49152
	ds_read_b128 v[168:171], v150 offset:50176
	ds_read_b128 v[172:175], v150 offset:51200
	ds_read_b128 v[176:179], v150 offset:52224
	ds_read_b128 v[180:183], v150 offset:53248
	ds_read_b128 v[204:207], v150 offset:54272
	ds_read_b128 v[208:211], v150 offset:55296
	ds_read_b128 v[212:215], v150 offset:56320
	global_load_lds_dwordx4 v130, s[72:73]
	s_mov_b32 m0, s31
	s_nop 0
	global_load_lds_dwordx4 v134, s[72:73]
	s_barrier
	s_waitcnt lgkmcnt(0)
	v_mfma_f32_16x16x32_bf16 v[62:65], v[142:145], v[164:167], v[62:65]
	v_mfma_f32_16x16x32_bf16 v[62:65], v[152:155], v[168:171], v[62:65]
	v_mfma_f32_16x16x32_bf16 v[58:61], v[156:159], v[164:167], v[58:61]
	v_mfma_f32_16x16x32_bf16 v[58:61], v[160:163], v[168:171], v[58:61]
	v_mfma_f32_16x16x32_bf16 v[46:49], v[142:145], v[172:175], v[46:49]
	v_mfma_f32_16x16x32_bf16 v[46:49], v[152:155], v[176:179], v[46:49]
	v_mfma_f32_16x16x32_bf16 v[42:45], v[156:159], v[172:175], v[42:45]
	v_mfma_f32_16x16x32_bf16 v[42:45], v[160:163], v[176:179], v[42:45]
	v_mfma_f32_16x16x32_bf16 v[30:33], v[142:145], v[180:183], v[30:33]
	v_mfma_f32_16x16x32_bf16 v[30:33], v[152:155], v[204:207], v[30:33]
	v_mfma_f32_16x16x32_bf16 v[26:29], v[156:159], v[180:183], v[26:29]
	v_mfma_f32_16x16x32_bf16 v[26:29], v[160:163], v[204:207], v[26:29]
	v_mfma_f32_16x16x32_bf16 v[14:17], v[142:145], v[208:211], v[14:17]
	v_mfma_f32_16x16x32_bf16 v[14:17], v[152:155], v[212:215], v[14:17]
	v_mfma_f32_16x16x32_bf16 v[10:13], v[156:159], v[208:211], v[10:13]
	v_mfma_f32_16x16x32_bf16 v[10:13], v[160:163], v[212:215], v[10:13]
	s_barrier
	s_add_i32 s4, s4, s21
	s_mov_b32 m0, s4
	s_nop 0
	global_load_lds_dwordx4 v132, s[76:77]
	s_add_i32 m0, s4, 0x2000
	s_nop 0
	global_load_lds_dwordx4 v136, s[76:77]
	s_add_u32 s0, s0, 0x100
	s_addc_u32 s1, s1, 0
	s_add_u32 s48, s48, 0x100
	s_addc_u32 s49, s49, 0
	s_cmp_ge_u32 s65, s27
	s_mov_b32 s4, s65
	s_waitcnt vmcnt(6)
	s_barrier
	v_mfma_f32_16x16x32_bf16 v[54:57], v[216:219], v[164:167], v[54:57]
	v_mfma_f32_16x16x32_bf16 v[54:57], v[220:223], v[168:171], v[54:57]
	v_mfma_f32_16x16x32_bf16 v[50:53], v[224:227], v[164:167], v[50:53]
	v_mfma_f32_16x16x32_bf16 v[50:53], v[228:231], v[168:171], v[50:53]
	v_mfma_f32_16x16x32_bf16 v[38:41], v[216:219], v[172:175], v[38:41]
	v_mfma_f32_16x16x32_bf16 v[38:41], v[220:223], v[176:179], v[38:41]
	v_mfma_f32_16x16x32_bf16 v[34:37], v[224:227], v[172:175], v[34:37]
	v_mfma_f32_16x16x32_bf16 v[34:37], v[228:231], v[176:179], v[34:37]
	v_mfma_f32_16x16x32_bf16 v[22:25], v[216:219], v[180:183], v[22:25]
	v_mfma_f32_16x16x32_bf16 v[22:25], v[220:223], v[204:207], v[22:25]
	v_mfma_f32_16x16x32_bf16 v[18:21], v[224:227], v[180:183], v[18:21]
	v_mfma_f32_16x16x32_bf16 v[18:21], v[228:231], v[204:207], v[18:21]
	v_mfma_f32_16x16x32_bf16 v[6:9], v[216:219], v[208:211], v[6:9]
	v_mfma_f32_16x16x32_bf16 v[6:9], v[220:223], v[212:215], v[6:9]
	v_mfma_f32_16x16x32_bf16 v[2:5], v[224:227], v[208:211], v[2:5]
	v_mfma_f32_16x16x32_bf16 v[2:5], v[228:231], v[212:215], v[2:5]
	s_barrier
	s_cbranch_scc0 .LBB0_698

.LBB0_741:
	s_add_u32 s0, s0, 0x80
	s_addc_u32 s1, s1, 0
	s_add_u32 s65, s4, 0x100
	s_addc_u32 s66, s5, 0
	s_mov_b32 s4, 0
	s_add_i32 s70, s4, 2
	s_add_u32 s10, s0, 0x80
	s_addc_u32 s5, s1, 0
	s_add_i32 s71, 0, 0x10000
	ds_read_b128 v[142:145], v248
	ds_read_b128 v[146:149], v248 offset:1024
	ds_read_b128 v[150:153], v248 offset:2048
	ds_read_b128 v[154:157], v248 offset:3072
	s_cmp_eq_u32 s43, s4
	s_cselect_b32 s4, s22, s10
	s_cselect_b32 s5, s23, s5
	s_cselect_b32 s11, s13, s66
	s_cselect_b32 s10, s12, s65
	s_add_i32 m0, s29, 0xc000
	ds_read_b128 v[158:161], v166
	ds_read_b128 v[168:171], v166 offset:1024
	ds_read_b128 v[172:175], v166 offset:2048
	ds_read_b128 v[176:179], v166 offset:3072
	ds_read_b128 v[180:183], v166 offset:4096
	ds_read_b128 v[204:207], v166 offset:5120
	ds_read_b128 v[208:211], v166 offset:6144
	ds_read_b128 v[212:215], v166 offset:7168
	global_load_lds_dwordx4 v138, s[0:1]
	s_add_i32 m0, s29, 0xe000
	s_nop 0
	global_load_lds_dwordx4 v140, s[0:1]
	s_waitcnt lgkmcnt(8)
	s_barrier
	s_waitcnt lgkmcnt(0)
	v_mfma_f32_16x16x32_bf16 v[126:129], v[142:145], v[158:161], 0
	v_mfma_f32_16x16x32_bf16 v[126:129], v[146:149], v[168:171], v[126:129]
	v_mfma_f32_16x16x32_bf16 v[122:125], v[150:153], v[158:161], 0
	v_mfma_f32_16x16x32_bf16 v[122:125], v[154:157], v[168:171], v[122:125]
	v_mfma_f32_16x16x32_bf16 v[110:113], v[142:145], v[172:175], 0
	v_mfma_f32_16x16x32_bf16 v[110:113], v[146:149], v[176:179], v[110:113]
	v_mfma_f32_16x16x32_bf16 v[106:109], v[150:153], v[172:175], 0
	v_mfma_f32_16x16x32_bf16 v[106:109], v[154:157], v[176:179], v[106:109]
	v_mfma_f32_16x16x32_bf16 v[94:97], v[142:145], v[180:183], 0
	v_mfma_f32_16x16x32_bf16 v[94:97], v[146:149], v[204:207], v[94:97]
	v_mfma_f32_16x16x32_bf16 v[90:93], v[150:153], v[180:183], 0
	v_mfma_f32_16x16x32_bf16 v[90:93], v[154:157], v[204:207], v[90:93]
	v_mfma_f32_16x16x32_bf16 v[78:81], v[142:145], v[208:211], 0
	v_mfma_f32_16x16x32_bf16 v[78:81], v[146:149], v[212:215], v[78:81]
	v_mfma_f32_16x16x32_bf16 v[74:77], v[150:153], v[208:211], 0
	v_mfma_f32_16x16x32_bf16 v[74:77], v[154:157], v[212:215], v[74:77]
	s_barrier
	s_add_i32 s72, 0, 0x14000
	s_add_i32 s71, s71, s28
	ds_read_b128 v[216:219], v248 offset:16384
	ds_read_b128 v[220:223], v248 offset:17408
	ds_read_b128 v[224:227], v248 offset:18432
	ds_read_b128 v[228:231], v248 offset:19456
	s_add_u32 s76, s10, s6
	s_addc_u32 s77, s11, s7
	s_mov_b32 m0, s71
	s_nop 0
	global_load_lds_dwordx4 v132, s[10:11]
	s_add_i32 m0, s71, 0x2000
	s_nop 0
	global_load_lds_dwordx4 v136, s[10:11]
	s_barrier
	s_waitcnt lgkmcnt(0)
	v_mfma_f32_16x16x32_bf16 v[118:121], v[216:219], v[158:161], 0
	v_mfma_f32_16x16x32_bf16 v[118:121], v[220:223], v[168:171], v[118:121]
	v_mfma_f32_16x16x32_bf16 v[114:117], v[224:227], v[158:161], 0
	v_mfma_f32_16x16x32_bf16 v[114:117], v[228:231], v[168:171], v[114:117]
	v_mfma_f32_16x16x32_bf16 v[102:105], v[216:219], v[172:175], 0
	v_mfma_f32_16x16x32_bf16 v[102:105], v[220:223], v[176:179], v[102:105]
	v_mfma_f32_16x16x32_bf16 v[98:101], v[224:227], v[172:175], 0
	v_mfma_f32_16x16x32_bf16 v[98:101], v[228:231], v[176:179], v[98:101]
	v_mfma_f32_16x16x32_bf16 v[86:89], v[216:219], v[180:183], 0
	v_mfma_f32_16x16x32_bf16 v[86:89], v[220:223], v[204:207], v[86:89]
	v_mfma_f32_16x16x32_bf16 v[82:85], v[224:227], v[180:183], 0
	v_mfma_f32_16x16x32_bf16 v[82:85], v[228:231], v[204:207], v[82:85]
	v_mfma_f32_16x16x32_bf16 v[70:73], v[216:219], v[208:211], 0
	v_mfma_f32_16x16x32_bf16 v[70:73], v[220:223], v[212:215], v[70:73]
	v_mfma_f32_16x16x32_bf16 v[66:69], v[224:227], v[208:211], 0
	v_mfma_f32_16x16x32_bf16 v[66:69], v[228:231], v[212:215], v[66:69]
	s_barrier
	s_mov_b32 m0, s29
	s_add_u32 s78, s4, s6
	s_addc_u32 s79, s5, s7
	ds_read_b128 v[158:161], v166 offset:16384
	ds_read_b128 v[168:171], v166 offset:17408
	ds_read_b128 v[172:175], v166 offset:18432
	ds_read_b128 v[176:179], v166 offset:19456
	ds_read_b128 v[180:183], v166 offset:20480
	ds_read_b128 v[204:207], v166 offset:21504
	ds_read_b128 v[208:211], v166 offset:22528
	ds_read_b128 v[212:215], v166 offset:23552
	global_load_lds_dwordx4 v130, s[4:5]
	s_mov_b32 m0, s30
	s_nop 0
	global_load_lds_dwordx4 v134, s[4:5]
	s_barrier
	s_waitcnt lgkmcnt(0)
	v_mfma_f32_16x16x32_bf16 v[62:65], v[142:145], v[158:161], 0
	v_mfma_f32_16x16x32_bf16 v[62:65], v[146:149], v[168:171], v[62:65]
	v_mfma_f32_16x16x32_bf16 v[58:61], v[150:153], v[158:161], 0
	v_mfma_f32_16x16x32_bf16 v[58:61], v[154:157], v[168:171], v[58:61]
	v_mfma_f32_16x16x32_bf16 v[46:49], v[142:145], v[172:175], 0
	v_mfma_f32_16x16x32_bf16 v[46:49], v[146:149], v[176:179], v[46:49]
	v_mfma_f32_16x16x32_bf16 v[42:45], v[150:153], v[172:175], 0
	v_mfma_f32_16x16x32_bf16 v[42:45], v[154:157], v[176:179], v[42:45]
	v_mfma_f32_16x16x32_bf16 v[30:33], v[142:145], v[180:183], 0
	v_mfma_f32_16x16x32_bf16 v[30:33], v[146:149], v[204:207], v[30:33]
	v_mfma_f32_16x16x32_bf16 v[26:29], v[150:153], v[180:183], 0
	v_mfma_f32_16x16x32_bf16 v[26:29], v[154:157], v[204:207], v[26:29]
	v_mfma_f32_16x16x32_bf16 v[14:17], v[142:145], v[208:211], 0
	v_mfma_f32_16x16x32_bf16 v[14:17], v[146:149], v[212:215], v[14:17]
	v_mfma_f32_16x16x32_bf16 v[10:13], v[150:153], v[208:211], 0
	v_mfma_f32_16x16x32_bf16 v[10:13], v[154:157], v[212:215], v[10:13]
	s_barrier
	s_add_u32 s10, s10, s2
	s_addc_u32 s11, s11, 0
	s_add_i32 s71, s72, s28
	s_add_u32 s80, s10, s6
	s_addc_u32 s81, s11, s7
	s_mov_b32 m0, s71
	s_nop 0
	global_load_lds_dwordx4 v132, s[10:11]
	s_add_i32 m0, s71, 0x2000
	s_nop 0
	global_load_lds_dwordx4 v136, s[10:11]
	s_waitcnt vmcnt(6)
	s_barrier
	v_mfma_f32_16x16x32_bf16 v[54:57], v[216:219], v[158:161], 0
	v_mfma_f32_16x16x32_bf16 v[54:57], v[220:223], v[168:171], v[54:57]
	v_mfma_f32_16x16x32_bf16 v[50:53], v[224:227], v[158:161], 0
	v_mfma_f32_16x16x32_bf16 v[50:53], v[228:231], v[168:171], v[50:53]
	v_mfma_f32_16x16x32_bf16 v[38:41], v[216:219], v[172:175], 0
	v_mfma_f32_16x16x32_bf16 v[38:41], v[220:223], v[176:179], v[38:41]
	v_mfma_f32_16x16x32_bf16 v[34:37], v[224:227], v[172:175], 0
	v_mfma_f32_16x16x32_bf16 v[34:37], v[228:231], v[176:179], v[34:37]
	v_mfma_f32_16x16x32_bf16 v[22:25], v[216:219], v[180:183], 0
	v_mfma_f32_16x16x32_bf16 v[22:25], v[220:223], v[204:207], v[22:25]
	v_mfma_f32_16x16x32_bf16 v[18:21], v[224:227], v[180:183], 0
	v_mfma_f32_16x16x32_bf16 v[18:21], v[228:231], v[204:207], v[18:21]
	v_mfma_f32_16x16x32_bf16 v[6:9], v[216:219], v[208:211], 0
	v_mfma_f32_16x16x32_bf16 v[6:9], v[220:223], v[212:215], v[6:9]
	v_mfma_f32_16x16x32_bf16 v[2:5], v[224:227], v[208:211], 0
	v_mfma_f32_16x16x32_bf16 v[2:5], v[228:231], v[212:215], v[2:5]
	s_barrier
	s_add_i32 s10, 0, 0x18000
	ds_read_b128 v[142:145], v248 offset:32768
	ds_read_b128 v[146:149], v248 offset:33792
	ds_read_b128 v[150:153], v248 offset:34816
	ds_read_b128 v[154:157], v248 offset:35840
	s_add_u32 s4, s4, s2
	s_addc_u32 s5, s5, 0
	s_mov_b32 m0, s31
	ds_read_b128 v[158:161], v166 offset:32768
	ds_read_b128 v[168:171], v166 offset:33792
	ds_read_b128 v[172:175], v166 offset:34816
	ds_read_b128 v[176:179], v166 offset:35840
	ds_read_b128 v[180:183], v166 offset:36864
	ds_read_b128 v[204:207], v166 offset:37888
	ds_read_b128 v[208:211], v166 offset:38912
	ds_read_b128 v[212:215], v166 offset:39936
	global_load_lds_dwordx4 v130, s[4:5]
	s_mov_b32 m0, s34
	s_nop 0
	global_load_lds_dwordx4 v134, s[4:5]
	s_waitcnt lgkmcnt(8)
	s_barrier
	s_waitcnt lgkmcnt(0)
	v_mfma_f32_16x16x32_bf16 v[126:129], v[142:145], v[158:161], v[126:129]
	v_mfma_f32_16x16x32_bf16 v[126:129], v[146:149], v[168:171], v[126:129]
	v_mfma_f32_16x16x32_bf16 v[122:125], v[150:153], v[158:161], v[122:125]
	v_mfma_f32_16x16x32_bf16 v[122:125], v[154:157], v[168:171], v[122:125]
	v_mfma_f32_16x16x32_bf16 v[110:113], v[142:145], v[172:175], v[110:113]
	v_mfma_f32_16x16x32_bf16 v[110:113], v[146:149], v[176:179], v[110:113]
	v_mfma_f32_16x16x32_bf16 v[106:109], v[150:153], v[172:175], v[106:109]
	v_mfma_f32_16x16x32_bf16 v[106:109], v[154:157], v[176:179], v[106:109]
	v_mfma_f32_16x16x32_bf16 v[94:97], v[142:145], v[180:183], v[94:97]
	v_mfma_f32_16x16x32_bf16 v[94:97], v[146:149], v[204:207], v[94:97]
	v_mfma_f32_16x16x32_bf16 v[90:93], v[150:153], v[180:183], v[90:93]
	v_mfma_f32_16x16x32_bf16 v[90:93], v[154:157], v[204:207], v[90:93]
	v_mfma_f32_16x16x32_bf16 v[78:81], v[142:145], v[208:211], v[78:81]
	v_mfma_f32_16x16x32_bf16 v[78:81], v[146:149], v[212:215], v[78:81]
	v_mfma_f32_16x16x32_bf16 v[74:77], v[150:153], v[208:211], v[74:77]
	v_mfma_f32_16x16x32_bf16 v[74:77], v[154:157], v[212:215], v[74:77]
	s_barrier
	s_add_i32 s4, 0, 0x1c000
	s_add_i32 s5, s10, s28
	s_mov_b32 m0, s5
	ds_read_b128 v[216:219], v248 offset:49152
	ds_read_b128 v[220:223], v248 offset:50176
	ds_read_b128 v[224:227], v248 offset:51200
	ds_read_b128 v[228:231], v248 offset:52224
	global_load_lds_dwordx4 v132, s[76:77]
	s_add_i32 m0, s5, 0x2000
	s_nop 0
	global_load_lds_dwordx4 v136, s[76:77]
	s_barrier
	s_waitcnt lgkmcnt(0)
	v_mfma_f32_16x16x32_bf16 v[118:121], v[216:219], v[158:161], v[118:121]
	v_mfma_f32_16x16x32_bf16 v[118:121], v[220:223], v[168:171], v[118:121]
	v_mfma_f32_16x16x32_bf16 v[114:117], v[224:227], v[158:161], v[114:117]
	v_mfma_f32_16x16x32_bf16 v[114:117], v[228:231], v[168:171], v[114:117]
	v_mfma_f32_16x16x32_bf16 v[102:105], v[216:219], v[172:175], v[102:105]
	v_mfma_f32_16x16x32_bf16 v[102:105], v[220:223], v[176:179], v[102:105]
	v_mfma_f32_16x16x32_bf16 v[98:101], v[224:227], v[172:175], v[98:101]
	v_mfma_f32_16x16x32_bf16 v[98:101], v[228:231], v[176:179], v[98:101]
	v_mfma_f32_16x16x32_bf16 v[86:89], v[216:219], v[180:183], v[86:89]
	v_mfma_f32_16x16x32_bf16 v[86:89], v[220:223], v[204:207], v[86:89]
	v_mfma_f32_16x16x32_bf16 v[82:85], v[224:227], v[180:183], v[82:85]
	v_mfma_f32_16x16x32_bf16 v[82:85], v[228:231], v[204:207], v[82:85]
	v_mfma_f32_16x16x32_bf16 v[70:73], v[216:219], v[208:211], v[70:73]
	v_mfma_f32_16x16x32_bf16 v[70:73], v[220:223], v[212:215], v[70:73]
	v_mfma_f32_16x16x32_bf16 v[66:69], v[224:227], v[208:211], v[66:69]
	v_mfma_f32_16x16x32_bf16 v[66:69], v[228:231], v[212:215], v[66:69]
	s_barrier
	s_mov_b32 m0, s41
	ds_read_b128 v[158:161], v166 offset:49152
	ds_read_b128 v[168:171], v166 offset:50176
	ds_read_b128 v[172:175], v166 offset:51200
	ds_read_b128 v[176:179], v166 offset:52224
	ds_read_b128 v[180:183], v166 offset:53248
	ds_read_b128 v[204:207], v166 offset:54272
	ds_read_b128 v[208:211], v166 offset:55296
	ds_read_b128 v[212:215], v166 offset:56320
	global_load_lds_dwordx4 v130, s[78:79]
	s_mov_b32 m0, s42
	s_nop 0
	global_load_lds_dwordx4 v134, s[78:79]
	s_barrier
	s_waitcnt lgkmcnt(0)
	v_mfma_f32_16x16x32_bf16 v[62:65], v[142:145], v[158:161], v[62:65]
	v_mfma_f32_16x16x32_bf16 v[62:65], v[146:149], v[168:171], v[62:65]
	v_mfma_f32_16x16x32_bf16 v[58:61], v[150:153], v[158:161], v[58:61]
	v_mfma_f32_16x16x32_bf16 v[58:61], v[154:157], v[168:171], v[58:61]
	v_mfma_f32_16x16x32_bf16 v[46:49], v[142:145], v[172:175], v[46:49]
	v_mfma_f32_16x16x32_bf16 v[46:49], v[146:149], v[176:179], v[46:49]
	v_mfma_f32_16x16x32_bf16 v[42:45], v[150:153], v[172:175], v[42:45]
	v_mfma_f32_16x16x32_bf16 v[42:45], v[154:157], v[176:179], v[42:45]
	v_mfma_f32_16x16x32_bf16 v[30:33], v[142:145], v[180:183], v[30:33]
	v_mfma_f32_16x16x32_bf16 v[30:33], v[146:149], v[204:207], v[30:33]
	v_mfma_f32_16x16x32_bf16 v[26:29], v[150:153], v[180:183], v[26:29]
	v_mfma_f32_16x16x32_bf16 v[26:29], v[154:157], v[204:207], v[26:29]
	v_mfma_f32_16x16x32_bf16 v[14:17], v[142:145], v[208:211], v[14:17]
	v_mfma_f32_16x16x32_bf16 v[14:17], v[146:149], v[212:215], v[14:17]
	v_mfma_f32_16x16x32_bf16 v[10:13], v[150:153], v[208:211], v[10:13]
	v_mfma_f32_16x16x32_bf16 v[10:13], v[154:157], v[212:215], v[10:13]
	s_barrier
	s_add_i32 s4, s4, s28
	s_mov_b32 m0, s4
	s_nop 0
	global_load_lds_dwordx4 v132, s[80:81]
	s_add_i32 m0, s4, 0x2000
	s_nop 0
	global_load_lds_dwordx4 v136, s[80:81]
	s_add_u32 s0, s0, 0x100
	s_addc_u32 s1, s1, 0
	s_add_u32 s65, s65, 0x100
	s_addc_u32 s66, s66, 0
	s_cmp_ge_u32 s70, s35
	s_mov_b32 s4, s70
	s_waitcnt vmcnt(6)
	s_barrier
	v_mfma_f32_16x16x32_bf16 v[54:57], v[216:219], v[158:161], v[54:57]
	v_mfma_f32_16x16x32_bf16 v[54:57], v[220:223], v[168:171], v[54:57]
	v_mfma_f32_16x16x32_bf16 v[50:53], v[224:227], v[158:161], v[50:53]
	v_mfma_f32_16x16x32_bf16 v[50:53], v[228:231], v[168:171], v[50:53]
	v_mfma_f32_16x16x32_bf16 v[38:41], v[216:219], v[172:175], v[38:41]
	v_mfma_f32_16x16x32_bf16 v[38:41], v[220:223], v[176:179], v[38:41]
	v_mfma_f32_16x16x32_bf16 v[34:37], v[224:227], v[172:175], v[34:37]
	v_mfma_f32_16x16x32_bf16 v[34:37], v[228:231], v[176:179], v[34:37]
	v_mfma_f32_16x16x32_bf16 v[22:25], v[216:219], v[180:183], v[22:25]
	v_mfma_f32_16x16x32_bf16 v[22:25], v[220:223], v[204:207], v[22:25]
	v_mfma_f32_16x16x32_bf16 v[18:21], v[224:227], v[180:183], v[18:21]
	v_mfma_f32_16x16x32_bf16 v[18:21], v[228:231], v[204:207], v[18:21]
	v_mfma_f32_16x16x32_bf16 v[6:9], v[216:219], v[208:211], v[6:9]
	v_mfma_f32_16x16x32_bf16 v[6:9], v[220:223], v[212:215], v[6:9]
	v_mfma_f32_16x16x32_bf16 v[2:5], v[224:227], v[208:211], v[2:5]
	v_mfma_f32_16x16x32_bf16 v[2:5], v[228:231], v[212:215], v[2:5]
	s_barrier
	s_cbranch_scc1 .Lkexit_742
.LBB0_742:
	s_add_i32 s70, s4, 2
	s_add_u32 s10, s0, 0x80
	s_addc_u32 s5, s1, 0
	s_add_i32 s71, 0, 0x10000
	ds_read_b128 v[142:145], v248
	ds_read_b128 v[146:149], v248 offset:1024
	ds_read_b128 v[150:153], v248 offset:2048
	ds_read_b128 v[154:157], v248 offset:3072
	s_cmp_eq_u32 s43, s4
	s_cselect_b32 s4, s22, s10
	s_cselect_b32 s5, s23, s5
	s_cselect_b32 s11, s13, s66
	s_cselect_b32 s10, s12, s65
	s_add_i32 m0, s29, 0xc000
	ds_read_b128 v[158:161], v166
	ds_read_b128 v[168:171], v166 offset:1024
	ds_read_b128 v[172:175], v166 offset:2048
	ds_read_b128 v[176:179], v166 offset:3072
	ds_read_b128 v[180:183], v166 offset:4096
	ds_read_b128 v[204:207], v166 offset:5120
	ds_read_b128 v[208:211], v166 offset:6144
	ds_read_b128 v[212:215], v166 offset:7168
	global_load_lds_dwordx4 v138, s[0:1]
	s_add_i32 m0, s29, 0xe000
	s_nop 0
	global_load_lds_dwordx4 v140, s[0:1]
	s_waitcnt lgkmcnt(8)
	s_barrier
	s_waitcnt lgkmcnt(0)
	v_mfma_f32_16x16x32_bf16 v[126:129], v[142:145], v[158:161], v[126:129]
	v_mfma_f32_16x16x32_bf16 v[126:129], v[146:149], v[168:171], v[126:129]
	v_mfma_f32_16x16x32_bf16 v[122:125], v[150:153], v[158:161], v[122:125]
	v_mfma_f32_16x16x32_bf16 v[122:125], v[154:157], v[168:171], v[122:125]
	v_mfma_f32_16x16x32_bf16 v[110:113], v[142:145], v[172:175], v[110:113]
	v_mfma_f32_16x16x32_bf16 v[110:113], v[146:149], v[176:179], v[110:113]
	v_mfma_f32_16x16x32_bf16 v[106:109], v[150:153], v[172:175], v[106:109]
	v_mfma_f32_16x16x32_bf16 v[106:109], v[154:157], v[176:179], v[106:109]
	v_mfma_f32_16x16x32_bf16 v[94:97], v[142:145], v[180:183], v[94:97]
	v_mfma_f32_16x16x32_bf16 v[94:97], v[146:149], v[204:207], v[94:97]
	v_mfma_f32_16x16x32_bf16 v[90:93], v[150:153], v[180:183], v[90:93]
	v_mfma_f32_16x16x32_bf16 v[90:93], v[154:157], v[204:207], v[90:93]
	v_mfma_f32_16x16x32_bf16 v[78:81], v[142:145], v[208:211], v[78:81]
	v_mfma_f32_16x16x32_bf16 v[78:81], v[146:149], v[212:215], v[78:81]
	v_mfma_f32_16x16x32_bf16 v[74:77], v[150:153], v[208:211], v[74:77]
	v_mfma_f32_16x16x32_bf16 v[74:77], v[154:157], v[212:215], v[74:77]
	s_barrier
	s_add_i32 s72, 0, 0x14000
	s_add_i32 s71, s71, s28
	ds_read_b128 v[216:219], v248 offset:16384
	ds_read_b128 v[220:223], v248 offset:17408
	ds_read_b128 v[224:227], v248 offset:18432
	ds_read_b128 v[228:231], v248 offset:19456
	s_add_u32 s76, s10, s6
	s_addc_u32 s77, s11, s7
	s_mov_b32 m0, s71
	s_nop 0
	global_load_lds_dwordx4 v132, s[10:11]
	s_add_i32 m0, s71, 0x2000
	s_nop 0
	global_load_lds_dwordx4 v136, s[10:11]
	s_barrier
	s_waitcnt lgkmcnt(0)
	v_mfma_f32_16x16x32_bf16 v[118:121], v[216:219], v[158:161], v[118:121]
	v_mfma_f32_16x16x32_bf16 v[118:121], v[220:223], v[168:171], v[118:121]
	v_mfma_f32_16x16x32_bf16 v[114:117], v[224:227], v[158:161], v[114:117]
	v_mfma_f32_16x16x32_bf16 v[114:117], v[228:231], v[168:171], v[114:117]
	v_mfma_f32_16x16x32_bf16 v[102:105], v[216:219], v[172:175], v[102:105]
	v_mfma_f32_16x16x32_bf16 v[102:105], v[220:223], v[176:179], v[102:105]
	v_mfma_f32_16x16x32_bf16 v[98:101], v[224:227], v[172:175], v[98:101]
	v_mfma_f32_16x16x32_bf16 v[98:101], v[228:231], v[176:179], v[98:101]
	v_mfma_f32_16x16x32_bf16 v[86:89], v[216:219], v[180:183], v[86:89]
	v_mfma_f32_16x16x32_bf16 v[86:89], v[220:223], v[204:207], v[86:89]
	v_mfma_f32_16x16x32_bf16 v[82:85], v[224:227], v[180:183], v[82:85]
	v_mfma_f32_16x16x32_bf16 v[82:85], v[228:231], v[204:207], v[82:85]
	v_mfma_f32_16x16x32_bf16 v[70:73], v[216:219], v[208:211], v[70:73]
	v_mfma_f32_16x16x32_bf16 v[70:73], v[220:223], v[212:215], v[70:73]
	v_mfma_f32_16x16x32_bf16 v[66:69], v[224:227], v[208:211], v[66:69]
	v_mfma_f32_16x16x32_bf16 v[66:69], v[228:231], v[212:215], v[66:69]
	s_barrier
	s_mov_b32 m0, s29
	s_add_u32 s78, s4, s6
	s_addc_u32 s79, s5, s7
	ds_read_b128 v[158:161], v166 offset:16384
	ds_read_b128 v[168:171], v166 offset:17408
	ds_read_b128 v[172:175], v166 offset:18432
	ds_read_b128 v[176:179], v166 offset:19456
	ds_read_b128 v[180:183], v166 offset:20480
	ds_read_b128 v[204:207], v166 offset:21504
	ds_read_b128 v[208:211], v166 offset:22528
	ds_read_b128 v[212:215], v166 offset:23552
	global_load_lds_dwordx4 v130, s[4:5]
	s_mov_b32 m0, s30
	s_nop 0
	global_load_lds_dwordx4 v134, s[4:5]
	s_barrier
	s_waitcnt lgkmcnt(0)
	v_mfma_f32_16x16x32_bf16 v[62:65], v[142:145], v[158:161], v[62:65]
	v_mfma_f32_16x16x32_bf16 v[62:65], v[146:149], v[168:171], v[62:65]
	v_mfma_f32_16x16x32_bf16 v[58:61], v[150:153], v[158:161], v[58:61]
	v_mfma_f32_16x16x32_bf16 v[58:61], v[154:157], v[168:171], v[58:61]
	v_mfma_f32_16x16x32_bf16 v[46:49], v[142:145], v[172:175], v[46:49]
	v_mfma_f32_16x16x32_bf16 v[46:49], v[146:149], v[176:179], v[46:49]
	v_mfma_f32_16x16x32_bf16 v[42:45], v[150:153], v[172:175], v[42:45]
	v_mfma_f32_16x16x32_bf16 v[42:45], v[154:157], v[176:179], v[42:45]
	v_mfma_f32_16x16x32_bf16 v[30:33], v[142:145], v[180:183], v[30:33]
	v_mfma_f32_16x16x32_bf16 v[30:33], v[146:149], v[204:207], v[30:33]
	v_mfma_f32_16x16x32_bf16 v[26:29], v[150:153], v[180:183], v[26:29]
	v_mfma_f32_16x16x32_bf16 v[26:29], v[154:157], v[204:207], v[26:29]
	v_mfma_f32_16x16x32_bf16 v[14:17], v[142:145], v[208:211], v[14:17]
	v_mfma_f32_16x16x32_bf16 v[14:17], v[146:149], v[212:215], v[14:17]
	v_mfma_f32_16x16x32_bf16 v[10:13], v[150:153], v[208:211], v[10:13]
	v_mfma_f32_16x16x32_bf16 v[10:13], v[154:157], v[212:215], v[10:13]
	s_barrier
	s_add_u32 s10, s10, s2
	s_addc_u32 s11, s11, 0
	s_add_i32 s71, s72, s28
	s_add_u32 s80, s10, s6
	s_addc_u32 s81, s11, s7
	s_mov_b32 m0, s71
	s_nop 0
	global_load_lds_dwordx4 v132, s[10:11]
	s_add_i32 m0, s71, 0x2000
	s_nop 0
	global_load_lds_dwordx4 v136, s[10:11]
	s_waitcnt vmcnt(6)
	s_barrier
	v_mfma_f32_16x16x32_bf16 v[54:57], v[216:219], v[158:161], v[54:57]
	v_mfma_f32_16x16x32_bf16 v[54:57], v[220:223], v[168:171], v[54:57]
	v_mfma_f32_16x16x32_bf16 v[50:53], v[224:227], v[158:161], v[50:53]
	v_mfma_f32_16x16x32_bf16 v[50:53], v[228:231], v[168:171], v[50:53]
	v_mfma_f32_16x16x32_bf16 v[38:41], v[216:219], v[172:175], v[38:41]
	v_mfma_f32_16x16x32_bf16 v[38:41], v[220:223], v[176:179], v[38:41]
	v_mfma_f32_16x16x32_bf16 v[34:37], v[224:227], v[172:175], v[34:37]
	v_mfma_f32_16x16x32_bf16 v[34:37], v[228:231], v[176:179], v[34:37]
	v_mfma_f32_16x16x32_bf16 v[22:25], v[216:219], v[180:183], v[22:25]
	v_mfma_f32_16x16x32_bf16 v[22:25], v[220:223], v[204:207], v[22:25]
	v_mfma_f32_16x16x32_bf16 v[18:21], v[224:227], v[180:183], v[18:21]
	v_mfma_f32_16x16x32_bf16 v[18:21], v[228:231], v[204:207], v[18:21]
	v_mfma_f32_16x16x32_bf16 v[6:9], v[216:219], v[208:211], v[6:9]
	v_mfma_f32_16x16x32_bf16 v[6:9], v[220:223], v[212:215], v[6:9]
	v_mfma_f32_16x16x32_bf16 v[2:5], v[224:227], v[208:211], v[2:5]
	v_mfma_f32_16x16x32_bf16 v[2:5], v[228:231], v[212:215], v[2:5]
	s_barrier
	s_add_i32 s10, 0, 0x18000
	ds_read_b128 v[142:145], v248 offset:32768
	ds_read_b128 v[146:149], v248 offset:33792
	ds_read_b128 v[150:153], v248 offset:34816
	ds_read_b128 v[154:157], v248 offset:35840
	s_add_u32 s4, s4, s2
	s_addc_u32 s5, s5, 0
	s_mov_b32 m0, s31
	ds_read_b128 v[158:161], v166 offset:32768
	ds_read_b128 v[168:171], v166 offset:33792
	ds_read_b128 v[172:175], v166 offset:34816
	ds_read_b128 v[176:179], v166 offset:35840
	ds_read_b128 v[180:183], v166 offset:36864
	ds_read_b128 v[204:207], v166 offset:37888
	ds_read_b128 v[208:211], v166 offset:38912
	ds_read_b128 v[212:215], v166 offset:39936
	global_load_lds_dwordx4 v130, s[4:5]
	s_mov_b32 m0, s34
	s_nop 0
	global_load_lds_dwordx4 v134, s[4:5]
	s_waitcnt lgkmcnt(8)
	s_barrier
	s_waitcnt lgkmcnt(0)
	v_mfma_f32_16x16x32_bf16 v[126:129], v[142:145], v[158:161], v[126:129]
	v_mfma_f32_16x16x32_bf16 v[126:129], v[146:149], v[168:171], v[126:129]
	v_mfma_f32_16x16x32_bf16 v[122:125], v[150:153], v[158:161], v[122:125]
	v_mfma_f32_16x16x32_bf16 v[122:125], v[154:157], v[168:171], v[122:125]
	v_mfma_f32_16x16x32_bf16 v[110:113], v[142:145], v[172:175], v[110:113]
	v_mfma_f32_16x16x32_bf16 v[110:113], v[146:149], v[176:179], v[110:113]
	v_mfma_f32_16x16x32_bf16 v[106:109], v[150:153], v[172:175], v[106:109]
	v_mfma_f32_16x16x32_bf16 v[106:109], v[154:157], v[176:179], v[106:109]
	v_mfma_f32_16x16x32_bf16 v[94:97], v[142:145], v[180:183], v[94:97]
	v_mfma_f32_16x16x32_bf16 v[94:97], v[146:149], v[204:207], v[94:97]
	v_mfma_f32_16x16x32_bf16 v[90:93], v[150:153], v[180:183], v[90:93]
	v_mfma_f32_16x16x32_bf16 v[90:93], v[154:157], v[204:207], v[90:93]
	v_mfma_f32_16x16x32_bf16 v[78:81], v[142:145], v[208:211], v[78:81]
	v_mfma_f32_16x16x32_bf16 v[78:81], v[146:149], v[212:215], v[78:81]
	v_mfma_f32_16x16x32_bf16 v[74:77], v[150:153], v[208:211], v[74:77]
	v_mfma_f32_16x16x32_bf16 v[74:77], v[154:157], v[212:215], v[74:77]
	s_barrier
	s_add_i32 s4, 0, 0x1c000
	s_add_i32 s5, s10, s28
	s_mov_b32 m0, s5
	ds_read_b128 v[216:219], v248 offset:49152
	ds_read_b128 v[220:223], v248 offset:50176
	ds_read_b128 v[224:227], v248 offset:51200
	ds_read_b128 v[228:231], v248 offset:52224
	global_load_lds_dwordx4 v132, s[76:77]
	s_add_i32 m0, s5, 0x2000
	s_nop 0
	global_load_lds_dwordx4 v136, s[76:77]
	s_barrier
	s_waitcnt lgkmcnt(0)
	v_mfma_f32_16x16x32_bf16 v[118:121], v[216:219], v[158:161], v[118:121]
	v_mfma_f32_16x16x32_bf16 v[118:121], v[220:223], v[168:171], v[118:121]
	v_mfma_f32_16x16x32_bf16 v[114:117], v[224:227], v[158:161], v[114:117]
	v_mfma_f32_16x16x32_bf16 v[114:117], v[228:231], v[168:171], v[114:117]
	v_mfma_f32_16x16x32_bf16 v[102:105], v[216:219], v[172:175], v[102:105]
	v_mfma_f32_16x16x32_bf16 v[102:105], v[220:223], v[176:179], v[102:105]
	v_mfma_f32_16x16x32_bf16 v[98:101], v[224:227], v[172:175], v[98:101]
	v_mfma_f32_16x16x32_bf16 v[98:101], v[228:231], v[176:179], v[98:101]
	v_mfma_f32_16x16x32_bf16 v[86:89], v[216:219], v[180:183], v[86:89]
	v_mfma_f32_16x16x32_bf16 v[86:89], v[220:223], v[204:207], v[86:89]
	v_mfma_f32_16x16x32_bf16 v[82:85], v[224:227], v[180:183], v[82:85]
	v_mfma_f32_16x16x32_bf16 v[82:85], v[228:231], v[204:207], v[82:85]
	v_mfma_f32_16x16x32_bf16 v[70:73], v[216:219], v[208:211], v[70:73]
	v_mfma_f32_16x16x32_bf16 v[70:73], v[220:223], v[212:215], v[70:73]
	v_mfma_f32_16x16x32_bf16 v[66:69], v[224:227], v[208:211], v[66:69]
	v_mfma_f32_16x16x32_bf16 v[66:69], v[228:231], v[212:215], v[66:69]
	s_barrier
	s_mov_b32 m0, s41
	ds_read_b128 v[158:161], v166 offset:49152
	ds_read_b128 v[168:171], v166 offset:50176
	ds_read_b128 v[172:175], v166 offset:51200
	ds_read_b128 v[176:179], v166 offset:52224
	ds_read_b128 v[180:183], v166 offset:53248
	ds_read_b128 v[204:207], v166 offset:54272
	ds_read_b128 v[208:211], v166 offset:55296
	ds_read_b128 v[212:215], v166 offset:56320
	global_load_lds_dwordx4 v130, s[78:79]
	s_mov_b32 m0, s42
	s_nop 0
	global_load_lds_dwordx4 v134, s[78:79]
	s_barrier
	s_waitcnt lgkmcnt(0)
	v_mfma_f32_16x16x32_bf16 v[62:65], v[142:145], v[158:161], v[62:65]
	v_mfma_f32_16x16x32_bf16 v[62:65], v[146:149], v[168:171], v[62:65]
	v_mfma_f32_16x16x32_bf16 v[58:61], v[150:153], v[158:161], v[58:61]
	v_mfma_f32_16x16x32_bf16 v[58:61], v[154:157], v[168:171], v[58:61]
	v_mfma_f32_16x16x32_bf16 v[46:49], v[142:145], v[172:175], v[46:49]
	v_mfma_f32_16x16x32_bf16 v[46:49], v[146:149], v[176:179], v[46:49]
	v_mfma_f32_16x16x32_bf16 v[42:45], v[150:153], v[172:175], v[42:45]
	v_mfma_f32_16x16x32_bf16 v[42:45], v[154:157], v[176:179], v[42:45]
	v_mfma_f32_16x16x32_bf16 v[30:33], v[142:145], v[180:183], v[30:33]
	v_mfma_f32_16x16x32_bf16 v[30:33], v[146:149], v[204:207], v[30:33]
	v_mfma_f32_16x16x32_bf16 v[26:29], v[150:153], v[180:183], v[26:29]
	v_mfma_f32_16x16x32_bf16 v[26:29], v[154:157], v[204:207], v[26:29]
	v_mfma_f32_16x16x32_bf16 v[14:17], v[142:145], v[208:211], v[14:17]
	v_mfma_f32_16x16x32_bf16 v[14:17], v[146:149], v[212:215], v[14:17]
	v_mfma_f32_16x16x32_bf16 v[10:13], v[150:153], v[208:211], v[10:13]
	v_mfma_f32_16x16x32_bf16 v[10:13], v[154:157], v[212:215], v[10:13]
	s_barrier
	s_add_i32 s4, s4, s28
	s_mov_b32 m0, s4
	s_nop 0
	global_load_lds_dwordx4 v132, s[80:81]
	s_add_i32 m0, s4, 0x2000
	s_nop 0
	global_load_lds_dwordx4 v136, s[80:81]
	s_add_u32 s0, s0, 0x100
	s_addc_u32 s1, s1, 0
	s_add_u32 s65, s65, 0x100
	s_addc_u32 s66, s66, 0
	s_cmp_ge_u32 s70, s35
	s_mov_b32 s4, s70
	s_waitcnt vmcnt(6)
	s_barrier
	v_mfma_f32_16x16x32_bf16 v[54:57], v[216:219], v[158:161], v[54:57]
	v_mfma_f32_16x16x32_bf16 v[54:57], v[220:223], v[168:171], v[54:57]
	v_mfma_f32_16x16x32_bf16 v[50:53], v[224:227], v[158:161], v[50:53]
	v_mfma_f32_16x16x32_bf16 v[50:53], v[228:231], v[168:171], v[50:53]
	v_mfma_f32_16x16x32_bf16 v[38:41], v[216:219], v[172:175], v[38:41]
	v_mfma_f32_16x16x32_bf16 v[38:41], v[220:223], v[176:179], v[38:41]
	v_mfma_f32_16x16x32_bf16 v[34:37], v[224:227], v[172:175], v[34:37]
	v_mfma_f32_16x16x32_bf16 v[34:37], v[228:231], v[176:179], v[34:37]
	v_mfma_f32_16x16x32_bf16 v[22:25], v[216:219], v[180:183], v[22:25]
	v_mfma_f32_16x16x32_bf16 v[22:25], v[220:223], v[204:207], v[22:25]
	v_mfma_f32_16x16x32_bf16 v[18:21], v[224:227], v[180:183], v[18:21]
	v_mfma_f32_16x16x32_bf16 v[18:21], v[228:231], v[204:207], v[18:21]
	v_mfma_f32_16x16x32_bf16 v[6:9], v[216:219], v[208:211], v[6:9]
	v_mfma_f32_16x16x32_bf16 v[6:9], v[220:223], v[212:215], v[6:9]
	v_mfma_f32_16x16x32_bf16 v[2:5], v[224:227], v[208:211], v[2:5]
	v_mfma_f32_16x16x32_bf16 v[2:5], v[228:231], v[212:215], v[2:5]
	s_barrier
	s_cbranch_scc0 .LBB0_742

.LBB0_805:
	s_add_u32 s0, s0, 0x80
	s_addc_u32 s1, s1, 0
	s_add_u32 s12, s4, 0x100
	s_addc_u32 s13, s5, 0
	s_mov_b32 s4, 0
	s_waitcnt vmcnt(0)
	s_add_i32 s27, s4, 2
	s_add_u32 s10, s0, 0x80
	s_addc_u32 s5, s1, 0
	s_add_i32 s28, 0, 0x10000
	ds_read_b128 v[142:145], v248
	ds_read_b128 v[146:149], v248 offset:1024
	ds_read_b128 v[150:153], v248 offset:2048
	ds_read_b128 v[154:157], v248 offset:3072
	s_cmp_eq_u32 s48, s4
	s_cselect_b32 s4, s22, s10
	s_cselect_b32 s5, s23, s5
	s_cselect_b32 s11, s25, s13
	s_cselect_b32 s10, s24, s12
	s_add_i32 m0, s35, 0xc000
	ds_read_b128 v[158:161], v172
	ds_read_b128 v[162:165], v172 offset:1024
	ds_read_b128 v[166:169], v172 offset:2048
	ds_read_b128 v[174:177], v172 offset:3072
	ds_read_b128 v[178:181], v172 offset:4096
	ds_read_b128 v[182:185], v172 offset:5120
	ds_read_b128 v[204:207], v172 offset:6144
	ds_read_b128 v[208:211], v172 offset:7168
	global_load_lds_dwordx4 v138, s[0:1]
	s_add_i32 m0, s35, 0xe000
	s_nop 0
	global_load_lds_dwordx4 v140, s[0:1]
	s_waitcnt lgkmcnt(8)
	s_barrier
	s_waitcnt lgkmcnt(0)
	v_mfma_f32_16x16x32_bf16 v[126:129], v[142:145], v[158:161], 0
	v_mfma_f32_16x16x32_bf16 v[126:129], v[146:149], v[162:165], v[126:129]
	v_mfma_f32_16x16x32_bf16 v[122:125], v[150:153], v[158:161], 0
	v_mfma_f32_16x16x32_bf16 v[122:125], v[154:157], v[162:165], v[122:125]
	v_mfma_f32_16x16x32_bf16 v[110:113], v[142:145], v[166:169], 0
	v_mfma_f32_16x16x32_bf16 v[110:113], v[146:149], v[174:177], v[110:113]
	v_mfma_f32_16x16x32_bf16 v[106:109], v[150:153], v[166:169], 0
	v_mfma_f32_16x16x32_bf16 v[106:109], v[154:157], v[174:177], v[106:109]
	v_mfma_f32_16x16x32_bf16 v[94:97], v[142:145], v[178:181], 0
	v_mfma_f32_16x16x32_bf16 v[94:97], v[146:149], v[182:185], v[94:97]
	v_mfma_f32_16x16x32_bf16 v[90:93], v[150:153], v[178:181], 0
	v_mfma_f32_16x16x32_bf16 v[90:93], v[154:157], v[182:185], v[90:93]
	v_mfma_f32_16x16x32_bf16 v[78:81], v[142:145], v[204:207], 0
	v_mfma_f32_16x16x32_bf16 v[78:81], v[146:149], v[208:211], v[78:81]
	v_mfma_f32_16x16x32_bf16 v[74:77], v[150:153], v[204:207], 0
	v_mfma_f32_16x16x32_bf16 v[74:77], v[154:157], v[208:211], v[74:77]
	s_barrier
	s_add_i32 s29, 0, 0x14000
	s_add_i32 s28, s28, s34
	s_add_u32 s78, s10, s6
	s_addc_u32 s79, s11, s7
	s_mov_b32 m0, s28
	ds_read_b128 v[212:215], v248 offset:16384
	ds_read_b128 v[216:219], v248 offset:17408
	ds_read_b128 v[220:223], v248 offset:18432
	ds_read_b128 v[224:227], v248 offset:19456
	global_load_lds_dwordx4 v132, s[10:11]
	s_add_i32 m0, s28, 0x2000
	s_nop 0
	global_load_lds_dwordx4 v136, s[10:11]
	s_barrier
	s_waitcnt lgkmcnt(0)
	v_mfma_f32_16x16x32_bf16 v[118:121], v[212:215], v[158:161], 0
	v_mfma_f32_16x16x32_bf16 v[118:121], v[216:219], v[162:165], v[118:121]
	v_mfma_f32_16x16x32_bf16 v[114:117], v[220:223], v[158:161], 0
	v_mfma_f32_16x16x32_bf16 v[114:117], v[224:227], v[162:165], v[114:117]
	v_mfma_f32_16x16x32_bf16 v[102:105], v[212:215], v[166:169], 0
	v_mfma_f32_16x16x32_bf16 v[102:105], v[216:219], v[174:177], v[102:105]
	v_mfma_f32_16x16x32_bf16 v[98:101], v[220:223], v[166:169], 0
	v_mfma_f32_16x16x32_bf16 v[98:101], v[224:227], v[174:177], v[98:101]
	v_mfma_f32_16x16x32_bf16 v[86:89], v[212:215], v[178:181], 0
	v_mfma_f32_16x16x32_bf16 v[86:89], v[216:219], v[182:185], v[86:89]
	v_mfma_f32_16x16x32_bf16 v[82:85], v[220:223], v[178:181], 0
	v_mfma_f32_16x16x32_bf16 v[82:85], v[224:227], v[182:185], v[82:85]
	v_mfma_f32_16x16x32_bf16 v[70:73], v[212:215], v[204:207], 0
	v_mfma_f32_16x16x32_bf16 v[70:73], v[216:219], v[208:211], v[70:73]
	v_mfma_f32_16x16x32_bf16 v[66:69], v[220:223], v[204:207], 0
	v_mfma_f32_16x16x32_bf16 v[66:69], v[224:227], v[208:211], v[66:69]
	s_barrier
	s_mov_b32 m0, s35
	s_add_u32 s80, s4, s6
	s_addc_u32 s81, s5, s7
	ds_read_b128 v[158:161], v172 offset:16384
	ds_read_b128 v[162:165], v172 offset:17408
	ds_read_b128 v[166:169], v172 offset:18432
	ds_read_b128 v[174:177], v172 offset:19456
	ds_read_b128 v[178:181], v172 offset:20480
	ds_read_b128 v[182:185], v172 offset:21504
	ds_read_b128 v[204:207], v172 offset:22528
	ds_read_b128 v[208:211], v172 offset:23552
	global_load_lds_dwordx4 v130, s[4:5]
	s_mov_b32 m0, s40
	s_nop 0
	global_load_lds_dwordx4 v134, s[4:5]
	s_barrier
	s_waitcnt lgkmcnt(0)
	v_mfma_f32_16x16x32_bf16 v[62:65], v[142:145], v[158:161], 0
	v_mfma_f32_16x16x32_bf16 v[62:65], v[146:149], v[162:165], v[62:65]
	v_mfma_f32_16x16x32_bf16 v[58:61], v[150:153], v[158:161], 0
	v_mfma_f32_16x16x32_bf16 v[58:61], v[154:157], v[162:165], v[58:61]
	v_mfma_f32_16x16x32_bf16 v[46:49], v[142:145], v[166:169], 0
	v_mfma_f32_16x16x32_bf16 v[46:49], v[146:149], v[174:177], v[46:49]
	v_mfma_f32_16x16x32_bf16 v[42:45], v[150:153], v[166:169], 0
	v_mfma_f32_16x16x32_bf16 v[42:45], v[154:157], v[174:177], v[42:45]
	v_mfma_f32_16x16x32_bf16 v[30:33], v[142:145], v[178:181], 0
	v_mfma_f32_16x16x32_bf16 v[30:33], v[146:149], v[182:185], v[30:33]
	v_mfma_f32_16x16x32_bf16 v[26:29], v[150:153], v[178:181], 0
	v_mfma_f32_16x16x32_bf16 v[26:29], v[154:157], v[182:185], v[26:29]
	v_mfma_f32_16x16x32_bf16 v[14:17], v[142:145], v[204:207], 0
	v_mfma_f32_16x16x32_bf16 v[14:17], v[146:149], v[208:211], v[14:17]
	v_mfma_f32_16x16x32_bf16 v[10:13], v[150:153], v[204:207], 0
	v_mfma_f32_16x16x32_bf16 v[10:13], v[154:157], v[208:211], v[10:13]
	s_barrier
	s_add_u32 s10, s10, s92
	s_addc_u32 s11, s11, 0
	s_add_i32 s28, s29, s34
	s_add_u32 s58, s10, s6
	s_addc_u32 s59, s11, s7
	s_mov_b32 m0, s28
	s_nop 0
	global_load_lds_dwordx4 v132, s[10:11]
	s_add_i32 m0, s28, 0x2000
	s_nop 0
	global_load_lds_dwordx4 v136, s[10:11]
	s_waitcnt vmcnt(6)
	s_barrier
	v_mfma_f32_16x16x32_bf16 v[54:57], v[212:215], v[158:161], 0
	v_mfma_f32_16x16x32_bf16 v[54:57], v[216:219], v[162:165], v[54:57]
	v_mfma_f32_16x16x32_bf16 v[50:53], v[220:223], v[158:161], 0
	v_mfma_f32_16x16x32_bf16 v[50:53], v[224:227], v[162:165], v[50:53]
	v_mfma_f32_16x16x32_bf16 v[38:41], v[212:215], v[166:169], 0
	v_mfma_f32_16x16x32_bf16 v[38:41], v[216:219], v[174:177], v[38:41]
	v_mfma_f32_16x16x32_bf16 v[34:37], v[220:223], v[166:169], 0
	v_mfma_f32_16x16x32_bf16 v[34:37], v[224:227], v[174:177], v[34:37]
	v_mfma_f32_16x16x32_bf16 v[22:25], v[212:215], v[178:181], 0
	v_mfma_f32_16x16x32_bf16 v[22:25], v[216:219], v[182:185], v[22:25]
	v_mfma_f32_16x16x32_bf16 v[18:21], v[220:223], v[178:181], 0
	v_mfma_f32_16x16x32_bf16 v[18:21], v[224:227], v[182:185], v[18:21]
	v_mfma_f32_16x16x32_bf16 v[6:9], v[212:215], v[204:207], 0
	v_mfma_f32_16x16x32_bf16 v[6:9], v[216:219], v[208:211], v[6:9]
	v_mfma_f32_16x16x32_bf16 v[2:5], v[220:223], v[204:207], 0
	v_mfma_f32_16x16x32_bf16 v[2:5], v[224:227], v[208:211], v[2:5]
	s_barrier
	s_add_i32 s10, 0, 0x18000
	ds_read_b128 v[142:145], v248 offset:32768
	ds_read_b128 v[146:149], v248 offset:33792
	ds_read_b128 v[150:153], v248 offset:34816
	ds_read_b128 v[154:157], v248 offset:35840
	s_add_u32 s4, s4, s92
	s_addc_u32 s5, s5, 0
	s_mov_b32 m0, s41
	ds_read_b128 v[158:161], v172 offset:32768
	ds_read_b128 v[162:165], v172 offset:33792
	ds_read_b128 v[166:169], v172 offset:34816
	ds_read_b128 v[174:177], v172 offset:35840
	ds_read_b128 v[178:181], v172 offset:36864
	ds_read_b128 v[182:185], v172 offset:37888
	ds_read_b128 v[204:207], v172 offset:38912
	ds_read_b128 v[208:211], v172 offset:39936
	global_load_lds_dwordx4 v130, s[4:5]
	s_mov_b32 m0, s42
	s_nop 0
	global_load_lds_dwordx4 v134, s[4:5]
	s_waitcnt lgkmcnt(8)
	s_barrier
	s_waitcnt lgkmcnt(0)
	v_mfma_f32_16x16x32_bf16 v[126:129], v[142:145], v[158:161], v[126:129]
	v_mfma_f32_16x16x32_bf16 v[126:129], v[146:149], v[162:165], v[126:129]
	v_mfma_f32_16x16x32_bf16 v[122:125], v[150:153], v[158:161], v[122:125]
	v_mfma_f32_16x16x32_bf16 v[122:125], v[154:157], v[162:165], v[122:125]
	v_mfma_f32_16x16x32_bf16 v[110:113], v[142:145], v[166:169], v[110:113]
	v_mfma_f32_16x16x32_bf16 v[110:113], v[146:149], v[174:177], v[110:113]
	v_mfma_f32_16x16x32_bf16 v[106:109], v[150:153], v[166:169], v[106:109]
	v_mfma_f32_16x16x32_bf16 v[106:109], v[154:157], v[174:177], v[106:109]
	v_mfma_f32_16x16x32_bf16 v[94:97], v[142:145], v[178:181], v[94:97]
	v_mfma_f32_16x16x32_bf16 v[94:97], v[146:149], v[182:185], v[94:97]
	v_mfma_f32_16x16x32_bf16 v[90:93], v[150:153], v[178:181], v[90:93]
	v_mfma_f32_16x16x32_bf16 v[90:93], v[154:157], v[182:185], v[90:93]
	v_mfma_f32_16x16x32_bf16 v[78:81], v[142:145], v[204:207], v[78:81]
	v_mfma_f32_16x16x32_bf16 v[78:81], v[146:149], v[208:211], v[78:81]
	v_mfma_f32_16x16x32_bf16 v[74:77], v[150:153], v[204:207], v[74:77]
	v_mfma_f32_16x16x32_bf16 v[74:77], v[154:157], v[208:211], v[74:77]
	s_barrier
	s_add_i32 s4, 0, 0x1c000
	s_add_i32 s5, s10, s34
	s_mov_b32 m0, s5
	ds_read_b128 v[212:215], v248 offset:49152
	ds_read_b128 v[216:219], v248 offset:50176
	ds_read_b128 v[220:223], v248 offset:51200
	ds_read_b128 v[224:227], v248 offset:52224
	global_load_lds_dwordx4 v132, s[78:79]
	s_add_i32 m0, s5, 0x2000
	s_nop 0
	global_load_lds_dwordx4 v136, s[78:79]
	s_barrier
	s_waitcnt lgkmcnt(0)
	v_mfma_f32_16x16x32_bf16 v[118:121], v[212:215], v[158:161], v[118:121]
	v_mfma_f32_16x16x32_bf16 v[118:121], v[216:219], v[162:165], v[118:121]
	v_mfma_f32_16x16x32_bf16 v[114:117], v[220:223], v[158:161], v[114:117]
	v_mfma_f32_16x16x32_bf16 v[114:117], v[224:227], v[162:165], v[114:117]
	v_mfma_f32_16x16x32_bf16 v[102:105], v[212:215], v[166:169], v[102:105]
	v_mfma_f32_16x16x32_bf16 v[102:105], v[216:219], v[174:177], v[102:105]
	v_mfma_f32_16x16x32_bf16 v[98:101], v[220:223], v[166:169], v[98:101]
	v_mfma_f32_16x16x32_bf16 v[98:101], v[224:227], v[174:177], v[98:101]
	v_mfma_f32_16x16x32_bf16 v[86:89], v[212:215], v[178:181], v[86:89]
	v_mfma_f32_16x16x32_bf16 v[86:89], v[216:219], v[182:185], v[86:89]
	v_mfma_f32_16x16x32_bf16 v[82:85], v[220:223], v[178:181], v[82:85]
	v_mfma_f32_16x16x32_bf16 v[82:85], v[224:227], v[182:185], v[82:85]
	v_mfma_f32_16x16x32_bf16 v[70:73], v[212:215], v[204:207], v[70:73]
	v_mfma_f32_16x16x32_bf16 v[70:73], v[216:219], v[208:211], v[70:73]
	v_mfma_f32_16x16x32_bf16 v[66:69], v[220:223], v[204:207], v[66:69]
	v_mfma_f32_16x16x32_bf16 v[66:69], v[224:227], v[208:211], v[66:69]
	s_barrier
	s_mov_b32 m0, s46
	ds_read_b128 v[158:161], v172 offset:49152
	ds_read_b128 v[162:165], v172 offset:50176
	ds_read_b128 v[166:169], v172 offset:51200
	ds_read_b128 v[174:177], v172 offset:52224
	ds_read_b128 v[178:181], v172 offset:53248
	ds_read_b128 v[182:185], v172 offset:54272
	ds_read_b128 v[204:207], v172 offset:55296
	ds_read_b128 v[208:211], v172 offset:56320
	global_load_lds_dwordx4 v130, s[80:81]
	s_mov_b32 m0, s47
	s_nop 0
	global_load_lds_dwordx4 v134, s[80:81]
	s_barrier
	s_waitcnt lgkmcnt(0)
	v_mfma_f32_16x16x32_bf16 v[62:65], v[142:145], v[158:161], v[62:65]
	v_mfma_f32_16x16x32_bf16 v[62:65], v[146:149], v[162:165], v[62:65]
	v_mfma_f32_16x16x32_bf16 v[58:61], v[150:153], v[158:161], v[58:61]
	v_mfma_f32_16x16x32_bf16 v[58:61], v[154:157], v[162:165], v[58:61]
	v_mfma_f32_16x16x32_bf16 v[46:49], v[142:145], v[166:169], v[46:49]
	v_mfma_f32_16x16x32_bf16 v[46:49], v[146:149], v[174:177], v[46:49]
	v_mfma_f32_16x16x32_bf16 v[42:45], v[150:153], v[166:169], v[42:45]
	v_mfma_f32_16x16x32_bf16 v[42:45], v[154:157], v[174:177], v[42:45]
	v_mfma_f32_16x16x32_bf16 v[30:33], v[142:145], v[178:181], v[30:33]
	v_mfma_f32_16x16x32_bf16 v[30:33], v[146:149], v[182:185], v[30:33]
	v_mfma_f32_16x16x32_bf16 v[26:29], v[150:153], v[178:181], v[26:29]
	v_mfma_f32_16x16x32_bf16 v[26:29], v[154:157], v[182:185], v[26:29]
	v_mfma_f32_16x16x32_bf16 v[14:17], v[142:145], v[204:207], v[14:17]
	v_mfma_f32_16x16x32_bf16 v[14:17], v[146:149], v[208:211], v[14:17]
	v_mfma_f32_16x16x32_bf16 v[10:13], v[150:153], v[204:207], v[10:13]
	v_mfma_f32_16x16x32_bf16 v[10:13], v[154:157], v[208:211], v[10:13]
	s_barrier
	s_add_i32 s4, s4, s34
	s_mov_b32 m0, s4
	s_nop 0
	global_load_lds_dwordx4 v132, s[58:59]
	s_add_i32 m0, s4, 0x2000
	s_nop 0
	global_load_lds_dwordx4 v136, s[58:59]
	s_add_u32 s0, s0, 0x100
	s_addc_u32 s1, s1, 0
	s_add_u32 s12, s12, 0x100
	s_addc_u32 s13, s13, 0
	s_cmp_ge_u32 s27, s43
	s_mov_b32 s4, s27
	s_waitcnt vmcnt(6)
	s_barrier
	v_mfma_f32_16x16x32_bf16 v[54:57], v[212:215], v[158:161], v[54:57]
	v_mfma_f32_16x16x32_bf16 v[54:57], v[216:219], v[162:165], v[54:57]
	v_mfma_f32_16x16x32_bf16 v[50:53], v[220:223], v[158:161], v[50:53]
	v_mfma_f32_16x16x32_bf16 v[50:53], v[224:227], v[162:165], v[50:53]
	v_mfma_f32_16x16x32_bf16 v[38:41], v[212:215], v[166:169], v[38:41]
	v_mfma_f32_16x16x32_bf16 v[38:41], v[216:219], v[174:177], v[38:41]
	v_mfma_f32_16x16x32_bf16 v[34:37], v[220:223], v[166:169], v[34:37]
	v_mfma_f32_16x16x32_bf16 v[34:37], v[224:227], v[174:177], v[34:37]
	v_mfma_f32_16x16x32_bf16 v[22:25], v[212:215], v[178:181], v[22:25]
	v_mfma_f32_16x16x32_bf16 v[22:25], v[216:219], v[182:185], v[22:25]
	v_mfma_f32_16x16x32_bf16 v[18:21], v[220:223], v[178:181], v[18:21]
	v_mfma_f32_16x16x32_bf16 v[18:21], v[224:227], v[182:185], v[18:21]
	v_mfma_f32_16x16x32_bf16 v[6:9], v[212:215], v[204:207], v[6:9]
	v_mfma_f32_16x16x32_bf16 v[6:9], v[216:219], v[208:211], v[6:9]
	v_mfma_f32_16x16x32_bf16 v[2:5], v[220:223], v[204:207], v[2:5]
	v_mfma_f32_16x16x32_bf16 v[2:5], v[224:227], v[208:211], v[2:5]
	s_barrier
	s_cbranch_scc1 .Lkexit_806
.LBB0_806:
	s_add_i32 s27, s4, 2
	s_add_u32 s10, s0, 0x80
	s_addc_u32 s5, s1, 0
	s_add_i32 s28, 0, 0x10000
	ds_read_b128 v[142:145], v248
	ds_read_b128 v[146:149], v248 offset:1024
	ds_read_b128 v[150:153], v248 offset:2048
	ds_read_b128 v[154:157], v248 offset:3072
	s_cmp_eq_u32 s48, s4
	s_cselect_b32 s4, s22, s10
	s_cselect_b32 s5, s23, s5
	s_cselect_b32 s11, s25, s13
	s_cselect_b32 s10, s24, s12
	s_add_i32 m0, s35, 0xc000
	ds_read_b128 v[158:161], v172
	ds_read_b128 v[162:165], v172 offset:1024
	ds_read_b128 v[166:169], v172 offset:2048
	ds_read_b128 v[174:177], v172 offset:3072
	ds_read_b128 v[178:181], v172 offset:4096
	ds_read_b128 v[182:185], v172 offset:5120
	ds_read_b128 v[204:207], v172 offset:6144
	ds_read_b128 v[208:211], v172 offset:7168
	global_load_lds_dwordx4 v138, s[0:1]
	s_add_i32 m0, s35, 0xe000
	s_nop 0
	global_load_lds_dwordx4 v140, s[0:1]
	s_waitcnt lgkmcnt(8)
	s_barrier
	s_waitcnt lgkmcnt(0)
	v_mfma_f32_16x16x32_bf16 v[126:129], v[142:145], v[158:161], v[126:129]
	v_mfma_f32_16x16x32_bf16 v[126:129], v[146:149], v[162:165], v[126:129]
	v_mfma_f32_16x16x32_bf16 v[122:125], v[150:153], v[158:161], v[122:125]
	v_mfma_f32_16x16x32_bf16 v[122:125], v[154:157], v[162:165], v[122:125]
	v_mfma_f32_16x16x32_bf16 v[110:113], v[142:145], v[166:169], v[110:113]
	v_mfma_f32_16x16x32_bf16 v[110:113], v[146:149], v[174:177], v[110:113]
	v_mfma_f32_16x16x32_bf16 v[106:109], v[150:153], v[166:169], v[106:109]
	v_mfma_f32_16x16x32_bf16 v[106:109], v[154:157], v[174:177], v[106:109]
	v_mfma_f32_16x16x32_bf16 v[94:97], v[142:145], v[178:181], v[94:97]
	v_mfma_f32_16x16x32_bf16 v[94:97], v[146:149], v[182:185], v[94:97]
	v_mfma_f32_16x16x32_bf16 v[90:93], v[150:153], v[178:181], v[90:93]
	v_mfma_f32_16x16x32_bf16 v[90:93], v[154:157], v[182:185], v[90:93]
	v_mfma_f32_16x16x32_bf16 v[78:81], v[142:145], v[204:207], v[78:81]
	v_mfma_f32_16x16x32_bf16 v[78:81], v[146:149], v[208:211], v[78:81]
	v_mfma_f32_16x16x32_bf16 v[74:77], v[150:153], v[204:207], v[74:77]
	v_mfma_f32_16x16x32_bf16 v[74:77], v[154:157], v[208:211], v[74:77]
	s_barrier
	s_add_i32 s29, 0, 0x14000
	s_add_i32 s28, s28, s34
	s_add_u32 s78, s10, s6
	s_addc_u32 s79, s11, s7
	s_mov_b32 m0, s28
	ds_read_b128 v[212:215], v248 offset:16384
	ds_read_b128 v[216:219], v248 offset:17408
	ds_read_b128 v[220:223], v248 offset:18432
	ds_read_b128 v[224:227], v248 offset:19456
	global_load_lds_dwordx4 v132, s[10:11]
	s_add_i32 m0, s28, 0x2000
	s_nop 0
	global_load_lds_dwordx4 v136, s[10:11]
	s_barrier
	s_waitcnt lgkmcnt(0)
	v_mfma_f32_16x16x32_bf16 v[118:121], v[212:215], v[158:161], v[118:121]
	v_mfma_f32_16x16x32_bf16 v[118:121], v[216:219], v[162:165], v[118:121]
	v_mfma_f32_16x16x32_bf16 v[114:117], v[220:223], v[158:161], v[114:117]
	v_mfma_f32_16x16x32_bf16 v[114:117], v[224:227], v[162:165], v[114:117]
	v_mfma_f32_16x16x32_bf16 v[102:105], v[212:215], v[166:169], v[102:105]
	v_mfma_f32_16x16x32_bf16 v[102:105], v[216:219], v[174:177], v[102:105]
	v_mfma_f32_16x16x32_bf16 v[98:101], v[220:223], v[166:169], v[98:101]
	v_mfma_f32_16x16x32_bf16 v[98:101], v[224:227], v[174:177], v[98:101]
	v_mfma_f32_16x16x32_bf16 v[86:89], v[212:215], v[178:181], v[86:89]
	v_mfma_f32_16x16x32_bf16 v[86:89], v[216:219], v[182:185], v[86:89]
	v_mfma_f32_16x16x32_bf16 v[82:85], v[220:223], v[178:181], v[82:85]
	v_mfma_f32_16x16x32_bf16 v[82:85], v[224:227], v[182:185], v[82:85]
	v_mfma_f32_16x16x32_bf16 v[70:73], v[212:215], v[204:207], v[70:73]
	v_mfma_f32_16x16x32_bf16 v[70:73], v[216:219], v[208:211], v[70:73]
	v_mfma_f32_16x16x32_bf16 v[66:69], v[220:223], v[204:207], v[66:69]
	v_mfma_f32_16x16x32_bf16 v[66:69], v[224:227], v[208:211], v[66:69]
	s_barrier
	s_mov_b32 m0, s35
	s_add_u32 s80, s4, s6
	s_addc_u32 s81, s5, s7
	ds_read_b128 v[158:161], v172 offset:16384
	ds_read_b128 v[162:165], v172 offset:17408
	ds_read_b128 v[166:169], v172 offset:18432
	ds_read_b128 v[174:177], v172 offset:19456
	ds_read_b128 v[178:181], v172 offset:20480
	ds_read_b128 v[182:185], v172 offset:21504
	ds_read_b128 v[204:207], v172 offset:22528
	ds_read_b128 v[208:211], v172 offset:23552
	global_load_lds_dwordx4 v130, s[4:5]
	s_mov_b32 m0, s40
	s_nop 0
	global_load_lds_dwordx4 v134, s[4:5]
	s_barrier
	s_waitcnt lgkmcnt(0)
	v_mfma_f32_16x16x32_bf16 v[62:65], v[142:145], v[158:161], v[62:65]
	v_mfma_f32_16x16x32_bf16 v[62:65], v[146:149], v[162:165], v[62:65]
	v_mfma_f32_16x16x32_bf16 v[58:61], v[150:153], v[158:161], v[58:61]
	v_mfma_f32_16x16x32_bf16 v[58:61], v[154:157], v[162:165], v[58:61]
	v_mfma_f32_16x16x32_bf16 v[46:49], v[142:145], v[166:169], v[46:49]
	v_mfma_f32_16x16x32_bf16 v[46:49], v[146:149], v[174:177], v[46:49]
	v_mfma_f32_16x16x32_bf16 v[42:45], v[150:153], v[166:169], v[42:45]
	v_mfma_f32_16x16x32_bf16 v[42:45], v[154:157], v[174:177], v[42:45]
	v_mfma_f32_16x16x32_bf16 v[30:33], v[142:145], v[178:181], v[30:33]
	v_mfma_f32_16x16x32_bf16 v[30:33], v[146:149], v[182:185], v[30:33]
	v_mfma_f32_16x16x32_bf16 v[26:29], v[150:153], v[178:181], v[26:29]
	v_mfma_f32_16x16x32_bf16 v[26:29], v[154:157], v[182:185], v[26:29]
	v_mfma_f32_16x16x32_bf16 v[14:17], v[142:145], v[204:207], v[14:17]
	v_mfma_f32_16x16x32_bf16 v[14:17], v[146:149], v[208:211], v[14:17]
	v_mfma_f32_16x16x32_bf16 v[10:13], v[150:153], v[204:207], v[10:13]
	v_mfma_f32_16x16x32_bf16 v[10:13], v[154:157], v[208:211], v[10:13]
	s_barrier
	s_add_u32 s10, s10, s92
	s_addc_u32 s11, s11, 0
	s_add_i32 s28, s29, s34
	s_add_u32 s58, s10, s6
	s_addc_u32 s59, s11, s7
	s_mov_b32 m0, s28
	s_nop 0
	global_load_lds_dwordx4 v132, s[10:11]
	s_add_i32 m0, s28, 0x2000
	s_nop 0
	global_load_lds_dwordx4 v136, s[10:11]
	s_waitcnt vmcnt(6)
	s_barrier
	v_mfma_f32_16x16x32_bf16 v[54:57], v[212:215], v[158:161], v[54:57]
	v_mfma_f32_16x16x32_bf16 v[54:57], v[216:219], v[162:165], v[54:57]
	v_mfma_f32_16x16x32_bf16 v[50:53], v[220:223], v[158:161], v[50:53]
	v_mfma_f32_16x16x32_bf16 v[50:53], v[224:227], v[162:165], v[50:53]
	v_mfma_f32_16x16x32_bf16 v[38:41], v[212:215], v[166:169], v[38:41]
	v_mfma_f32_16x16x32_bf16 v[38:41], v[216:219], v[174:177], v[38:41]
	v_mfma_f32_16x16x32_bf16 v[34:37], v[220:223], v[166:169], v[34:37]
	v_mfma_f32_16x16x32_bf16 v[34:37], v[224:227], v[174:177], v[34:37]
	v_mfma_f32_16x16x32_bf16 v[22:25], v[212:215], v[178:181], v[22:25]
	v_mfma_f32_16x16x32_bf16 v[22:25], v[216:219], v[182:185], v[22:25]
	v_mfma_f32_16x16x32_bf16 v[18:21], v[220:223], v[178:181], v[18:21]
	v_mfma_f32_16x16x32_bf16 v[18:21], v[224:227], v[182:185], v[18:21]
	v_mfma_f32_16x16x32_bf16 v[6:9], v[212:215], v[204:207], v[6:9]
	v_mfma_f32_16x16x32_bf16 v[6:9], v[216:219], v[208:211], v[6:9]
	v_mfma_f32_16x16x32_bf16 v[2:5], v[220:223], v[204:207], v[2:5]
	v_mfma_f32_16x16x32_bf16 v[2:5], v[224:227], v[208:211], v[2:5]
	s_barrier
	s_add_i32 s10, 0, 0x18000
	ds_read_b128 v[142:145], v248 offset:32768
	ds_read_b128 v[146:149], v248 offset:33792
	ds_read_b128 v[150:153], v248 offset:34816
	ds_read_b128 v[154:157], v248 offset:35840
	s_add_u32 s4, s4, s92
	s_addc_u32 s5, s5, 0
	s_mov_b32 m0, s41
	ds_read_b128 v[158:161], v172 offset:32768
	ds_read_b128 v[162:165], v172 offset:33792
	ds_read_b128 v[166:169], v172 offset:34816
	ds_read_b128 v[174:177], v172 offset:35840
	ds_read_b128 v[178:181], v172 offset:36864
	ds_read_b128 v[182:185], v172 offset:37888
	ds_read_b128 v[204:207], v172 offset:38912
	ds_read_b128 v[208:211], v172 offset:39936
	global_load_lds_dwordx4 v130, s[4:5]
	s_mov_b32 m0, s42
	s_nop 0
	global_load_lds_dwordx4 v134, s[4:5]
	s_waitcnt lgkmcnt(8)
	s_barrier
	s_waitcnt lgkmcnt(0)
	v_mfma_f32_16x16x32_bf16 v[126:129], v[142:145], v[158:161], v[126:129]
	v_mfma_f32_16x16x32_bf16 v[126:129], v[146:149], v[162:165], v[126:129]
	v_mfma_f32_16x16x32_bf16 v[122:125], v[150:153], v[158:161], v[122:125]
	v_mfma_f32_16x16x32_bf16 v[122:125], v[154:157], v[162:165], v[122:125]
	v_mfma_f32_16x16x32_bf16 v[110:113], v[142:145], v[166:169], v[110:113]
	v_mfma_f32_16x16x32_bf16 v[110:113], v[146:149], v[174:177], v[110:113]
	v_mfma_f32_16x16x32_bf16 v[106:109], v[150:153], v[166:169], v[106:109]
	v_mfma_f32_16x16x32_bf16 v[106:109], v[154:157], v[174:177], v[106:109]
	v_mfma_f32_16x16x32_bf16 v[94:97], v[142:145], v[178:181], v[94:97]
	v_mfma_f32_16x16x32_bf16 v[94:97], v[146:149], v[182:185], v[94:97]
	v_mfma_f32_16x16x32_bf16 v[90:93], v[150:153], v[178:181], v[90:93]
	v_mfma_f32_16x16x32_bf16 v[90:93], v[154:157], v[182:185], v[90:93]
	v_mfma_f32_16x16x32_bf16 v[78:81], v[142:145], v[204:207], v[78:81]
	v_mfma_f32_16x16x32_bf16 v[78:81], v[146:149], v[208:211], v[78:81]
	v_mfma_f32_16x16x32_bf16 v[74:77], v[150:153], v[204:207], v[74:77]
	v_mfma_f32_16x16x32_bf16 v[74:77], v[154:157], v[208:211], v[74:77]
	s_barrier
	s_add_i32 s4, 0, 0x1c000
	s_add_i32 s5, s10, s34
	s_mov_b32 m0, s5
	ds_read_b128 v[212:215], v248 offset:49152
	ds_read_b128 v[216:219], v248 offset:50176
	ds_read_b128 v[220:223], v248 offset:51200
	ds_read_b128 v[224:227], v248 offset:52224
	global_load_lds_dwordx4 v132, s[78:79]
	s_add_i32 m0, s5, 0x2000
	s_nop 0
	global_load_lds_dwordx4 v136, s[78:79]
	s_barrier
	s_waitcnt lgkmcnt(0)
	v_mfma_f32_16x16x32_bf16 v[118:121], v[212:215], v[158:161], v[118:121]
	v_mfma_f32_16x16x32_bf16 v[118:121], v[216:219], v[162:165], v[118:121]
	v_mfma_f32_16x16x32_bf16 v[114:117], v[220:223], v[158:161], v[114:117]
	v_mfma_f32_16x16x32_bf16 v[114:117], v[224:227], v[162:165], v[114:117]
	v_mfma_f32_16x16x32_bf16 v[102:105], v[212:215], v[166:169], v[102:105]
	v_mfma_f32_16x16x32_bf16 v[102:105], v[216:219], v[174:177], v[102:105]
	v_mfma_f32_16x16x32_bf16 v[98:101], v[220:223], v[166:169], v[98:101]
	v_mfma_f32_16x16x32_bf16 v[98:101], v[224:227], v[174:177], v[98:101]
	v_mfma_f32_16x16x32_bf16 v[86:89], v[212:215], v[178:181], v[86:89]
	v_mfma_f32_16x16x32_bf16 v[86:89], v[216:219], v[182:185], v[86:89]
	v_mfma_f32_16x16x32_bf16 v[82:85], v[220:223], v[178:181], v[82:85]
	v_mfma_f32_16x16x32_bf16 v[82:85], v[224:227], v[182:185], v[82:85]
	v_mfma_f32_16x16x32_bf16 v[70:73], v[212:215], v[204:207], v[70:73]
	v_mfma_f32_16x16x32_bf16 v[70:73], v[216:219], v[208:211], v[70:73]
	v_mfma_f32_16x16x32_bf16 v[66:69], v[220:223], v[204:207], v[66:69]
	v_mfma_f32_16x16x32_bf16 v[66:69], v[224:227], v[208:211], v[66:69]
	s_barrier
	s_mov_b32 m0, s46
	ds_read_b128 v[158:161], v172 offset:49152
	ds_read_b128 v[162:165], v172 offset:50176
	ds_read_b128 v[166:169], v172 offset:51200
	ds_read_b128 v[174:177], v172 offset:52224
	ds_read_b128 v[178:181], v172 offset:53248
	ds_read_b128 v[182:185], v172 offset:54272
	ds_read_b128 v[204:207], v172 offset:55296
	ds_read_b128 v[208:211], v172 offset:56320
	global_load_lds_dwordx4 v130, s[80:81]
	s_mov_b32 m0, s47
	s_nop 0
	global_load_lds_dwordx4 v134, s[80:81]
	s_barrier
	s_waitcnt lgkmcnt(0)
	v_mfma_f32_16x16x32_bf16 v[62:65], v[142:145], v[158:161], v[62:65]
	v_mfma_f32_16x16x32_bf16 v[62:65], v[146:149], v[162:165], v[62:65]
	v_mfma_f32_16x16x32_bf16 v[58:61], v[150:153], v[158:161], v[58:61]
	v_mfma_f32_16x16x32_bf16 v[58:61], v[154:157], v[162:165], v[58:61]
	v_mfma_f32_16x16x32_bf16 v[46:49], v[142:145], v[166:169], v[46:49]
	v_mfma_f32_16x16x32_bf16 v[46:49], v[146:149], v[174:177], v[46:49]
	v_mfma_f32_16x16x32_bf16 v[42:45], v[150:153], v[166:169], v[42:45]
	v_mfma_f32_16x16x32_bf16 v[42:45], v[154:157], v[174:177], v[42:45]
	v_mfma_f32_16x16x32_bf16 v[30:33], v[142:145], v[178:181], v[30:33]
	v_mfma_f32_16x16x32_bf16 v[30:33], v[146:149], v[182:185], v[30:33]
	v_mfma_f32_16x16x32_bf16 v[26:29], v[150:153], v[178:181], v[26:29]
	v_mfma_f32_16x16x32_bf16 v[26:29], v[154:157], v[182:185], v[26:29]
	v_mfma_f32_16x16x32_bf16 v[14:17], v[142:145], v[204:207], v[14:17]
	v_mfma_f32_16x16x32_bf16 v[14:17], v[146:149], v[208:211], v[14:17]
	v_mfma_f32_16x16x32_bf16 v[10:13], v[150:153], v[204:207], v[10:13]
	v_mfma_f32_16x16x32_bf16 v[10:13], v[154:157], v[208:211], v[10:13]
	s_barrier
	s_add_i32 s4, s4, s34
	s_mov_b32 m0, s4
	s_nop 0
	global_load_lds_dwordx4 v132, s[58:59]
	s_add_i32 m0, s4, 0x2000
	s_nop 0
	global_load_lds_dwordx4 v136, s[58:59]
	s_add_u32 s0, s0, 0x100
	s_addc_u32 s1, s1, 0
	s_add_u32 s12, s12, 0x100
	s_addc_u32 s13, s13, 0
	s_cmp_ge_u32 s27, s43
	s_mov_b32 s4, s27
	s_waitcnt vmcnt(6)
	s_barrier
	v_mfma_f32_16x16x32_bf16 v[54:57], v[212:215], v[158:161], v[54:57]
	v_mfma_f32_16x16x32_bf16 v[54:57], v[216:219], v[162:165], v[54:57]
	v_mfma_f32_16x16x32_bf16 v[50:53], v[220:223], v[158:161], v[50:53]
	v_mfma_f32_16x16x32_bf16 v[50:53], v[224:227], v[162:165], v[50:53]
	v_mfma_f32_16x16x32_bf16 v[38:41], v[212:215], v[166:169], v[38:41]
	v_mfma_f32_16x16x32_bf16 v[38:41], v[216:219], v[174:177], v[38:41]
	v_mfma_f32_16x16x32_bf16 v[34:37], v[220:223], v[166:169], v[34:37]
	v_mfma_f32_16x16x32_bf16 v[34:37], v[224:227], v[174:177], v[34:37]
	v_mfma_f32_16x16x32_bf16 v[22:25], v[212:215], v[178:181], v[22:25]
	v_mfma_f32_16x16x32_bf16 v[22:25], v[216:219], v[182:185], v[22:25]
	v_mfma_f32_16x16x32_bf16 v[18:21], v[220:223], v[178:181], v[18:21]
	v_mfma_f32_16x16x32_bf16 v[18:21], v[224:227], v[182:185], v[18:21]
	v_mfma_f32_16x16x32_bf16 v[6:9], v[212:215], v[204:207], v[6:9]
	v_mfma_f32_16x16x32_bf16 v[6:9], v[216:219], v[208:211], v[6:9]
	v_mfma_f32_16x16x32_bf16 v[2:5], v[220:223], v[204:207], v[2:5]
	v_mfma_f32_16x16x32_bf16 v[2:5], v[224:227], v[208:211], v[2:5]
	s_barrier
	s_cbranch_scc0 .LBB0_806
